# v83 with the two deferred DMA pairs issued from inside the wave's own MFMA blocks 2 and 4 (after the 24th MFMA); loop-top guard and last-iteration copy removed
# baseline (speedup 1.0000x reference)
.LBB0_163:
	s_add_u32 s26, s24, 0xfffc0080
	s_addc_u32 s27, s25, -1
	s_cmp_eq_u32 s55, 12
	s_cselect_b32 s29, s19, s27
	s_cselect_b32 s28, s51, s26
	s_cselect_b32 s27, s17, s54
	s_cselect_b32 s26, s52, s53
	s_add_i32 m0, s38, 0xc000
	s_nop 0
	global_load_lds_dwordx4 v138, s[24:25]
	s_add_i32 m0, s38, 0xe000
	s_nop 0
	global_load_lds_dwordx4 v136, s[24:25]
	ds_read_b128 v[144:147], v151
	ds_read_b128 v[156:159], v151 offset:1024
	ds_read_b128 v[160:163], v151 offset:2048
	ds_read_b128 v[164:167], v151 offset:3072
	ds_read_b128 v[168:171], v152
	ds_read_b128 v[172:175], v152 offset:1024
	ds_read_b128 v[176:179], v152 offset:2048
	ds_read_b128 v[180:183], v152 offset:3072
	ds_read_b128 v[184:187], v153
	ds_read_b128 v[188:191], v153 offset:1024
	ds_read_b128 v[192:195], v153 offset:2048
	ds_read_b128 v[196:199], v153 offset:3072
	ds_read_b128 v[200:203], v153 offset:4096
	ds_read_b128 v[208:211], v153 offset:5120
	ds_read_b128 v[212:215], v153 offset:6144
	ds_read_b128 v[216:219], v153 offset:7168
	s_waitcnt vmcnt(8)
	s_waitcnt lgkmcnt(0)
	s_barrier
	s_waitcnt lgkmcnt(0)
	v_mfma_f32_16x16x32_bf16 v[124:127], v[144:147], v[184:187], v[124:127]
	v_mfma_f32_16x16x32_bf16 v[120:123], v[160:163], v[184:187], v[120:123]
	v_mfma_f32_16x16x32_bf16 v[108:111], v[144:147], v[192:195], v[108:111]
	v_mfma_f32_16x16x32_bf16 v[104:107], v[160:163], v[192:195], v[104:107]
	v_mfma_f32_16x16x32_bf16 v[92:95], v[144:147], v[200:203], v[92:95]
	v_mfma_f32_16x16x32_bf16 v[88:91], v[160:163], v[200:203], v[88:91]
	v_mfma_f32_16x16x32_bf16 v[76:79], v[144:147], v[212:215], v[76:79]
	v_mfma_f32_16x16x32_bf16 v[72:75], v[160:163], v[212:215], v[72:75]
	v_mfma_f32_16x16x32_bf16 v[124:127], v[156:159], v[188:191], v[124:127]
	v_mfma_f32_16x16x32_bf16 v[120:123], v[164:167], v[188:191], v[120:123]
	v_mfma_f32_16x16x32_bf16 v[108:111], v[156:159], v[196:199], v[108:111]
	v_mfma_f32_16x16x32_bf16 v[104:107], v[164:167], v[196:199], v[104:107]
	v_mfma_f32_16x16x32_bf16 v[92:95], v[156:159], v[208:211], v[92:95]
	v_mfma_f32_16x16x32_bf16 v[88:91], v[164:167], v[208:211], v[88:91]
	v_mfma_f32_16x16x32_bf16 v[76:79], v[156:159], v[216:219], v[76:79]
	v_mfma_f32_16x16x32_bf16 v[72:75], v[164:167], v[216:219], v[72:75]
	v_mfma_f32_16x16x32_bf16 v[116:119], v[168:171], v[184:187], v[116:119]
	v_mfma_f32_16x16x32_bf16 v[112:115], v[176:179], v[184:187], v[112:115]
	v_mfma_f32_16x16x32_bf16 v[100:103], v[168:171], v[192:195], v[100:103]
	v_mfma_f32_16x16x32_bf16 v[96:99], v[176:179], v[192:195], v[96:99]
	v_mfma_f32_16x16x32_bf16 v[84:87], v[168:171], v[200:203], v[84:87]
	v_mfma_f32_16x16x32_bf16 v[80:83], v[176:179], v[200:203], v[80:83]
	v_mfma_f32_16x16x32_bf16 v[68:71], v[168:171], v[212:215], v[68:71]
	v_mfma_f32_16x16x32_bf16 v[64:67], v[176:179], v[212:215], v[64:67]
	v_mfma_f32_16x16x32_bf16 v[116:119], v[172:175], v[188:191], v[116:119]
	v_mfma_f32_16x16x32_bf16 v[112:115], v[180:183], v[188:191], v[112:115]
	v_mfma_f32_16x16x32_bf16 v[100:103], v[172:175], v[196:199], v[100:103]
	v_mfma_f32_16x16x32_bf16 v[96:99], v[180:183], v[196:199], v[96:99]
	v_mfma_f32_16x16x32_bf16 v[84:87], v[172:175], v[208:211], v[84:87]
	v_mfma_f32_16x16x32_bf16 v[80:83], v[180:183], v[208:211], v[80:83]
	v_mfma_f32_16x16x32_bf16 v[68:71], v[172:175], v[216:219], v[68:71]
	v_mfma_f32_16x16x32_bf16 v[64:67], v[180:183], v[216:219], v[64:67]
	s_barrier
	s_add_i32 s56, s48, s35
	s_mov_b32 m0, s56
	s_nop 0
	global_load_lds_dwordx4 v132, s[26:27]
	s_add_i32 m0, s56, 0x2000
	s_add_u32 s56, s26, 0x40000
	s_mov_b64 s[98:99], s[26:27]
	s_addc_u32 s57, s27, 0
	s_add_i32 s58, s49, s35
	global_load_lds_dwordx4 v128, s[26:27]
	s_mov_b32 m0, s58
	s_mov_b64 s[100:101], s[28:29]
	global_load_lds_dwordx4 v132, s[56:57]
	s_add_i32 m0, s58, 0x2000
	s_nop 0
	global_load_lds_dwordx4 v128, s[56:57]
	ds_read_b128 v[184:187], v153 offset:16384
	ds_read_b128 v[188:191], v153 offset:17408
	ds_read_b128 v[192:195], v153 offset:18432
	ds_read_b128 v[196:199], v153 offset:19456
	ds_read_b128 v[200:203], v153 offset:20480
	ds_read_b128 v[208:211], v153 offset:21504
	ds_read_b128 v[212:215], v153 offset:22528
	ds_read_b128 v[216:219], v153 offset:23552
	s_waitcnt vmcnt(6)
	s_waitcnt lgkmcnt(0)
	s_barrier
	s_waitcnt lgkmcnt(0)
	v_mfma_f32_16x16x32_bf16 v[60:63], v[144:147], v[184:187], v[60:63]
	v_mfma_f32_16x16x32_bf16 v[56:59], v[160:163], v[184:187], v[56:59]
	v_mfma_f32_16x16x32_bf16 v[44:47], v[144:147], v[192:195], v[44:47]
	v_mfma_f32_16x16x32_bf16 v[40:43], v[160:163], v[192:195], v[40:43]
	v_mfma_f32_16x16x32_bf16 v[28:31], v[144:147], v[200:203], v[28:31]
	v_mfma_f32_16x16x32_bf16 v[24:27], v[160:163], v[200:203], v[24:27]
	v_mfma_f32_16x16x32_bf16 v[12:15], v[144:147], v[212:215], v[12:15]
	v_mfma_f32_16x16x32_bf16 v[8:11], v[160:163], v[212:215], v[8:11]
	v_mfma_f32_16x16x32_bf16 v[60:63], v[156:159], v[188:191], v[60:63]
	v_mfma_f32_16x16x32_bf16 v[56:59], v[164:167], v[188:191], v[56:59]
	v_mfma_f32_16x16x32_bf16 v[44:47], v[156:159], v[196:199], v[44:47]
	v_mfma_f32_16x16x32_bf16 v[40:43], v[164:167], v[196:199], v[40:43]
	v_mfma_f32_16x16x32_bf16 v[28:31], v[156:159], v[208:211], v[28:31]
	v_mfma_f32_16x16x32_bf16 v[24:27], v[164:167], v[208:211], v[24:27]
	v_mfma_f32_16x16x32_bf16 v[12:15], v[156:159], v[216:219], v[12:15]
	v_mfma_f32_16x16x32_bf16 v[8:11], v[164:167], v[216:219], v[8:11]
	v_mfma_f32_16x16x32_bf16 v[52:55], v[168:171], v[184:187], v[52:55]
	v_mfma_f32_16x16x32_bf16 v[48:51], v[176:179], v[184:187], v[48:51]
	v_mfma_f32_16x16x32_bf16 v[36:39], v[168:171], v[192:195], v[36:39]
	v_mfma_f32_16x16x32_bf16 v[32:35], v[176:179], v[192:195], v[32:35]
	v_mfma_f32_16x16x32_bf16 v[20:23], v[168:171], v[200:203], v[20:23]
	v_mfma_f32_16x16x32_bf16 v[16:19], v[176:179], v[200:203], v[16:19]
	v_mfma_f32_16x16x32_bf16 v[4:7], v[168:171], v[212:215], v[4:7]
	v_mfma_f32_16x16x32_bf16 v[0:3], v[176:179], v[212:215], v[0:3]
	s_mov_b32 m0, s38
	s_nop 0
	global_load_lds_dwordx4 v134, s[28:29]
	s_mov_b32 m0, s39
	s_nop 0
	global_load_lds_dwordx4 v130, s[28:29]
	v_mfma_f32_16x16x32_bf16 v[52:55], v[172:175], v[188:191], v[52:55]
	v_mfma_f32_16x16x32_bf16 v[48:51], v[180:183], v[188:191], v[48:51]
	v_mfma_f32_16x16x32_bf16 v[36:39], v[172:175], v[196:199], v[36:39]
	v_mfma_f32_16x16x32_bf16 v[32:35], v[180:183], v[196:199], v[32:35]
	v_mfma_f32_16x16x32_bf16 v[20:23], v[172:175], v[208:211], v[20:23]
	v_mfma_f32_16x16x32_bf16 v[16:19], v[180:183], v[208:211], v[16:19]
	v_mfma_f32_16x16x32_bf16 v[4:7], v[172:175], v[216:219], v[4:7]
	v_mfma_f32_16x16x32_bf16 v[0:3], v[180:183], v[216:219], v[0:3]
	s_barrier
	s_add_i32 s56, 0, 0x18000
	s_add_i32 s57, 0, 0x1c000
	s_add_u32 s28, s28, 0x40000
	s_addc_u32 s29, s29, 0
	s_mov_b32 m0, s40
	s_nop 0
	global_load_lds_dwordx4 v134, s[28:29]
	s_mov_b32 m0, s41
	s_nop 0
	global_load_lds_dwordx4 v130, s[28:29]
	v_add_u32_e32 v164, s56, v149
	v_add_u32_e32 v180, s57, v149
	ds_read_b128 v[144:147], v164
	ds_read_b128 v[156:159], v164 offset:1024
	ds_read_b128 v[160:163], v164 offset:2048
	ds_read_b128 v[164:167], v164 offset:3072
	ds_read_b128 v[168:171], v180
	ds_read_b128 v[172:175], v180 offset:1024
	ds_read_b128 v[176:179], v180 offset:2048
	ds_read_b128 v[180:183], v180 offset:3072
	ds_read_b128 v[184:187], v153 offset:32768
	ds_read_b128 v[188:191], v153 offset:33792
	ds_read_b128 v[192:195], v153 offset:34816
	ds_read_b128 v[196:199], v153 offset:35840
	ds_read_b128 v[200:203], v153 offset:36864
	ds_read_b128 v[208:211], v153 offset:37888
	ds_read_b128 v[212:215], v153 offset:38912
	ds_read_b128 v[216:219], v153 offset:39936
	s_waitcnt vmcnt(8)
	s_waitcnt lgkmcnt(0)
	s_barrier
	s_waitcnt lgkmcnt(0)
	v_mfma_f32_16x16x32_bf16 v[124:127], v[144:147], v[184:187], v[124:127]
	v_mfma_f32_16x16x32_bf16 v[120:123], v[160:163], v[184:187], v[120:123]
	v_mfma_f32_16x16x32_bf16 v[108:111], v[144:147], v[192:195], v[108:111]
	v_mfma_f32_16x16x32_bf16 v[104:107], v[160:163], v[192:195], v[104:107]
	v_mfma_f32_16x16x32_bf16 v[92:95], v[144:147], v[200:203], v[92:95]
	v_mfma_f32_16x16x32_bf16 v[88:91], v[160:163], v[200:203], v[88:91]
	v_mfma_f32_16x16x32_bf16 v[76:79], v[144:147], v[212:215], v[76:79]
	v_mfma_f32_16x16x32_bf16 v[72:75], v[160:163], v[212:215], v[72:75]
	v_mfma_f32_16x16x32_bf16 v[124:127], v[156:159], v[188:191], v[124:127]
	v_mfma_f32_16x16x32_bf16 v[120:123], v[164:167], v[188:191], v[120:123]
	v_mfma_f32_16x16x32_bf16 v[108:111], v[156:159], v[196:199], v[108:111]
	v_mfma_f32_16x16x32_bf16 v[104:107], v[164:167], v[196:199], v[104:107]
	v_mfma_f32_16x16x32_bf16 v[92:95], v[156:159], v[208:211], v[92:95]
	v_mfma_f32_16x16x32_bf16 v[88:91], v[164:167], v[208:211], v[88:91]
	v_mfma_f32_16x16x32_bf16 v[76:79], v[156:159], v[216:219], v[76:79]
	v_mfma_f32_16x16x32_bf16 v[72:75], v[164:167], v[216:219], v[72:75]
	v_mfma_f32_16x16x32_bf16 v[116:119], v[168:171], v[184:187], v[116:119]
	v_mfma_f32_16x16x32_bf16 v[112:115], v[176:179], v[184:187], v[112:115]
	v_mfma_f32_16x16x32_bf16 v[100:103], v[168:171], v[192:195], v[100:103]
	v_mfma_f32_16x16x32_bf16 v[96:99], v[176:179], v[192:195], v[96:99]
	v_mfma_f32_16x16x32_bf16 v[84:87], v[168:171], v[200:203], v[84:87]
	v_mfma_f32_16x16x32_bf16 v[80:83], v[176:179], v[200:203], v[80:83]
	v_mfma_f32_16x16x32_bf16 v[68:71], v[168:171], v[212:215], v[68:71]
	v_mfma_f32_16x16x32_bf16 v[64:67], v[176:179], v[212:215], v[64:67]
	v_mfma_f32_16x16x32_bf16 v[116:119], v[172:175], v[188:191], v[116:119]
	v_mfma_f32_16x16x32_bf16 v[112:115], v[180:183], v[188:191], v[112:115]
	v_mfma_f32_16x16x32_bf16 v[100:103], v[172:175], v[196:199], v[100:103]
	v_mfma_f32_16x16x32_bf16 v[96:99], v[180:183], v[196:199], v[96:99]
	v_mfma_f32_16x16x32_bf16 v[84:87], v[172:175], v[208:211], v[84:87]
	v_mfma_f32_16x16x32_bf16 v[80:83], v[180:183], v[208:211], v[80:83]
	v_mfma_f32_16x16x32_bf16 v[68:71], v[172:175], v[216:219], v[68:71]
	v_mfma_f32_16x16x32_bf16 v[64:67], v[180:183], v[216:219], v[64:67]
	s_barrier
	s_add_i32 s28, s56, s35
	s_mov_b32 m0, s28
	s_nop 0
	global_load_lds_dwordx4 v220, s[26:27]
	s_add_i32 m0, s28, 0x2000
	s_add_u32 s26, s26, 0x40080
	s_addc_u32 s27, s27, 0
	s_add_i32 s28, s57, s35
	global_load_lds_dwordx4 v204, s[98:99]
	s_mov_b32 m0, s28
	s_nop 0
	global_load_lds_dwordx4 v132, s[26:27]
	s_add_i32 m0, s28, 0x2000
	s_nop 0
	global_load_lds_dwordx4 v128, s[26:27]
	ds_read_b128 v[184:187], v153 offset:49152
	ds_read_b128 v[188:191], v153 offset:50176
	ds_read_b128 v[192:195], v153 offset:51200
	ds_read_b128 v[196:199], v153 offset:52224
	ds_read_b128 v[200:203], v153 offset:53248
	ds_read_b128 v[208:211], v153 offset:54272
	ds_read_b128 v[212:215], v153 offset:55296
	ds_read_b128 v[216:219], v153 offset:56320
	s_waitcnt vmcnt(6)
	s_waitcnt lgkmcnt(0)
	s_barrier
	s_waitcnt lgkmcnt(0)
	v_mfma_f32_16x16x32_bf16 v[60:63], v[144:147], v[184:187], v[60:63]
	v_mfma_f32_16x16x32_bf16 v[56:59], v[160:163], v[184:187], v[56:59]
	v_mfma_f32_16x16x32_bf16 v[44:47], v[144:147], v[192:195], v[44:47]
	v_mfma_f32_16x16x32_bf16 v[40:43], v[160:163], v[192:195], v[40:43]
	v_mfma_f32_16x16x32_bf16 v[28:31], v[144:147], v[200:203], v[28:31]
	v_mfma_f32_16x16x32_bf16 v[24:27], v[160:163], v[200:203], v[24:27]
	v_mfma_f32_16x16x32_bf16 v[12:15], v[144:147], v[212:215], v[12:15]
	v_mfma_f32_16x16x32_bf16 v[8:11], v[160:163], v[212:215], v[8:11]
	v_mfma_f32_16x16x32_bf16 v[60:63], v[156:159], v[188:191], v[60:63]
	v_mfma_f32_16x16x32_bf16 v[56:59], v[164:167], v[188:191], v[56:59]
	v_mfma_f32_16x16x32_bf16 v[44:47], v[156:159], v[196:199], v[44:47]
	v_mfma_f32_16x16x32_bf16 v[40:43], v[164:167], v[196:199], v[40:43]
	v_mfma_f32_16x16x32_bf16 v[28:31], v[156:159], v[208:211], v[28:31]
	v_mfma_f32_16x16x32_bf16 v[24:27], v[164:167], v[208:211], v[24:27]
	v_mfma_f32_16x16x32_bf16 v[12:15], v[156:159], v[216:219], v[12:15]
	v_mfma_f32_16x16x32_bf16 v[8:11], v[164:167], v[216:219], v[8:11]
	v_mfma_f32_16x16x32_bf16 v[52:55], v[168:171], v[184:187], v[52:55]
	v_mfma_f32_16x16x32_bf16 v[48:51], v[176:179], v[184:187], v[48:51]
	v_mfma_f32_16x16x32_bf16 v[36:39], v[168:171], v[192:195], v[36:39]
	v_mfma_f32_16x16x32_bf16 v[32:35], v[176:179], v[192:195], v[32:35]
	v_mfma_f32_16x16x32_bf16 v[20:23], v[168:171], v[200:203], v[20:23]
	v_mfma_f32_16x16x32_bf16 v[16:19], v[176:179], v[200:203], v[16:19]
	v_mfma_f32_16x16x32_bf16 v[4:7], v[168:171], v[212:215], v[4:7]
	v_mfma_f32_16x16x32_bf16 v[0:3], v[176:179], v[212:215], v[0:3]
	s_mov_b32 m0, s45
	s_nop 0
	global_load_lds_dwordx4 v221, s[100:101]
	s_mov_b32 m0, s46
	s_nop 0
	global_load_lds_dwordx4 v205, s[100:101]
	v_mfma_f32_16x16x32_bf16 v[52:55], v[172:175], v[188:191], v[52:55]
	v_mfma_f32_16x16x32_bf16 v[48:51], v[180:183], v[188:191], v[48:51]
	v_mfma_f32_16x16x32_bf16 v[36:39], v[172:175], v[196:199], v[36:39]
	v_mfma_f32_16x16x32_bf16 v[32:35], v[180:183], v[196:199], v[32:35]
	v_mfma_f32_16x16x32_bf16 v[20:23], v[172:175], v[208:211], v[20:23]
	v_mfma_f32_16x16x32_bf16 v[16:19], v[180:183], v[208:211], v[16:19]
	v_mfma_f32_16x16x32_bf16 v[4:7], v[172:175], v[216:219], v[4:7]
	v_mfma_f32_16x16x32_bf16 v[0:3], v[180:183], v[216:219], v[0:3]
	s_barrier
	s_add_i32 s55, s55, 2
	s_add_u32 s53, s53, 0x100
	s_addc_u32 s54, s54, 0
	s_add_u32 s24, s24, 0x100
	s_addc_u32 s25, s25, 0
	s_cmp_gt_u32 s55, 13
	s_cbranch_scc0 .LBB0_163
	s_setprio 0
	s_and_b64 vcc, exec, s[14:15]
	s_cbranch_vccz .LBB0_166
	s_barrier

.LBB0_606:
	s_add_u32 s30, s28, 0x100
	s_addc_u32 s31, s29, 0
	s_cmp_eq_u32 s58, 12
	s_cselect_b32 s37, s21, s31
	s_cselect_b32 s36, s27, s30
	s_cselect_b32 s35, s19, s57
	s_cselect_b32 s34, s55, s56
	s_add_i32 m0, s44, 0xc000
	s_nop 0
	global_load_lds_dwordx4 v134, s[28:29]
	s_add_i32 m0, s44, 0xe000
	s_nop 0
	global_load_lds_dwordx4 v132, s[28:29]
	ds_read_b128 v[140:143], v147
	ds_read_b128 v[150:153], v147 offset:1024
	ds_read_b128 v[154:157], v147 offset:2048
	ds_read_b128 v[158:161], v147 offset:3072
	ds_read_b128 v[162:165], v148
	ds_read_b128 v[166:169], v148 offset:1024
	ds_read_b128 v[170:173], v148 offset:2048
	ds_read_b128 v[174:177], v148 offset:3072
	ds_read_b128 v[178:181], v149
	ds_read_b128 v[182:185], v149 offset:1024
	ds_read_b128 v[186:189], v149 offset:2048
	ds_read_b128 v[190:193], v149 offset:3072
	ds_read_b128 v[194:197], v149 offset:4096
	ds_read_b128 v[198:201], v149 offset:5120
	ds_read_b128 v[202:205], v149 offset:6144
	ds_read_b128 v[208:211], v149 offset:7168
	s_waitcnt vmcnt(8)
	s_waitcnt lgkmcnt(0)
	s_barrier
	s_waitcnt lgkmcnt(0)
	v_mfma_f32_16x16x32_bf16 v[124:127], v[140:143], v[178:181], v[124:127]
	v_mfma_f32_16x16x32_bf16 v[120:123], v[154:157], v[178:181], v[120:123]
	v_mfma_f32_16x16x32_bf16 v[108:111], v[140:143], v[186:189], v[108:111]
	v_mfma_f32_16x16x32_bf16 v[104:107], v[154:157], v[186:189], v[104:107]
	v_mfma_f32_16x16x32_bf16 v[92:95], v[140:143], v[194:197], v[92:95]
	v_mfma_f32_16x16x32_bf16 v[88:91], v[154:157], v[194:197], v[88:91]
	v_mfma_f32_16x16x32_bf16 v[76:79], v[140:143], v[202:205], v[76:79]
	v_mfma_f32_16x16x32_bf16 v[72:75], v[154:157], v[202:205], v[72:75]
	v_mfma_f32_16x16x32_bf16 v[124:127], v[150:153], v[182:185], v[124:127]
	v_mfma_f32_16x16x32_bf16 v[120:123], v[158:161], v[182:185], v[120:123]
	v_mfma_f32_16x16x32_bf16 v[108:111], v[150:153], v[190:193], v[108:111]
	v_mfma_f32_16x16x32_bf16 v[104:107], v[158:161], v[190:193], v[104:107]
	v_mfma_f32_16x16x32_bf16 v[92:95], v[150:153], v[198:201], v[92:95]
	v_mfma_f32_16x16x32_bf16 v[88:91], v[158:161], v[198:201], v[88:91]
	v_mfma_f32_16x16x32_bf16 v[76:79], v[150:153], v[208:211], v[76:79]
	v_mfma_f32_16x16x32_bf16 v[72:75], v[158:161], v[208:211], v[72:75]
	v_mfma_f32_16x16x32_bf16 v[116:119], v[162:165], v[178:181], v[116:119]
	v_mfma_f32_16x16x32_bf16 v[112:115], v[170:173], v[178:181], v[112:115]
	v_mfma_f32_16x16x32_bf16 v[100:103], v[162:165], v[186:189], v[100:103]
	v_mfma_f32_16x16x32_bf16 v[96:99], v[170:173], v[186:189], v[96:99]
	v_mfma_f32_16x16x32_bf16 v[84:87], v[162:165], v[194:197], v[84:87]
	v_mfma_f32_16x16x32_bf16 v[80:83], v[170:173], v[194:197], v[80:83]
	v_mfma_f32_16x16x32_bf16 v[68:71], v[162:165], v[202:205], v[68:71]
	v_mfma_f32_16x16x32_bf16 v[64:67], v[170:173], v[202:205], v[64:67]
	v_mfma_f32_16x16x32_bf16 v[116:119], v[166:169], v[182:185], v[116:119]
	v_mfma_f32_16x16x32_bf16 v[112:115], v[174:177], v[182:185], v[112:115]
	v_mfma_f32_16x16x32_bf16 v[100:103], v[166:169], v[190:193], v[100:103]
	v_mfma_f32_16x16x32_bf16 v[96:99], v[174:177], v[190:193], v[96:99]
	v_mfma_f32_16x16x32_bf16 v[84:87], v[166:169], v[198:201], v[84:87]
	v_mfma_f32_16x16x32_bf16 v[80:83], v[174:177], v[198:201], v[80:83]
	v_mfma_f32_16x16x32_bf16 v[68:71], v[166:169], v[208:211], v[68:71]
	v_mfma_f32_16x16x32_bf16 v[64:67], v[174:177], v[208:211], v[64:67]
	s_barrier
	s_add_i32 s28, s52, s43
	s_mov_b32 m0, s28
	s_nop 0
	global_load_lds_dwordx4 v128, s[34:35]
	s_add_i32 m0, s28, 0x2000
	s_add_u32 s28, s34, 0x40000
	s_mov_b64 s[98:99], s[34:35]
	s_addc_u32 s29, s35, 0
	s_add_i32 s59, s53, s43
	global_load_lds_dwordx4 v130, s[34:35]
	s_mov_b32 m0, s59
	s_nop 0
	global_load_lds_dwordx4 v128, s[28:29]
	s_add_i32 m0, s59, 0x2000
	s_nop 0
	global_load_lds_dwordx4 v130, s[28:29]
	ds_read_b128 v[178:181], v149 offset:16384
	ds_read_b128 v[182:185], v149 offset:17408
	ds_read_b128 v[186:189], v149 offset:18432
	ds_read_b128 v[190:193], v149 offset:19456
	ds_read_b128 v[194:197], v149 offset:20480
	ds_read_b128 v[198:201], v149 offset:21504
	ds_read_b128 v[202:205], v149 offset:22528
	ds_read_b128 v[208:211], v149 offset:23552
	s_waitcnt vmcnt(6)
	s_waitcnt lgkmcnt(0)
	s_barrier
	s_waitcnt lgkmcnt(0)
	v_mfma_f32_16x16x32_bf16 v[60:63], v[140:143], v[178:181], v[60:63]
	v_mfma_f32_16x16x32_bf16 v[56:59], v[154:157], v[178:181], v[56:59]
	v_mfma_f32_16x16x32_bf16 v[44:47], v[140:143], v[186:189], v[44:47]
	v_mfma_f32_16x16x32_bf16 v[40:43], v[154:157], v[186:189], v[40:43]
	v_mfma_f32_16x16x32_bf16 v[28:31], v[140:143], v[194:197], v[28:31]
	v_mfma_f32_16x16x32_bf16 v[24:27], v[154:157], v[194:197], v[24:27]
	v_mfma_f32_16x16x32_bf16 v[12:15], v[140:143], v[202:205], v[12:15]
	v_mfma_f32_16x16x32_bf16 v[8:11], v[154:157], v[202:205], v[8:11]
	v_mfma_f32_16x16x32_bf16 v[60:63], v[150:153], v[182:185], v[60:63]
	v_mfma_f32_16x16x32_bf16 v[56:59], v[158:161], v[182:185], v[56:59]
	v_mfma_f32_16x16x32_bf16 v[44:47], v[150:153], v[190:193], v[44:47]
	v_mfma_f32_16x16x32_bf16 v[40:43], v[158:161], v[190:193], v[40:43]
	v_mfma_f32_16x16x32_bf16 v[28:31], v[150:153], v[198:201], v[28:31]
	v_mfma_f32_16x16x32_bf16 v[24:27], v[158:161], v[198:201], v[24:27]
	v_mfma_f32_16x16x32_bf16 v[12:15], v[150:153], v[208:211], v[12:15]
	v_mfma_f32_16x16x32_bf16 v[8:11], v[158:161], v[208:211], v[8:11]
	v_mfma_f32_16x16x32_bf16 v[52:55], v[162:165], v[178:181], v[52:55]
	v_mfma_f32_16x16x32_bf16 v[48:51], v[170:173], v[178:181], v[48:51]
	v_mfma_f32_16x16x32_bf16 v[36:39], v[162:165], v[186:189], v[36:39]
	v_mfma_f32_16x16x32_bf16 v[32:35], v[170:173], v[186:189], v[32:35]
	v_mfma_f32_16x16x32_bf16 v[20:23], v[162:165], v[194:197], v[20:23]
	v_mfma_f32_16x16x32_bf16 v[16:19], v[170:173], v[194:197], v[16:19]
	v_mfma_f32_16x16x32_bf16 v[4:7], v[162:165], v[202:205], v[4:7]
	v_mfma_f32_16x16x32_bf16 v[0:3], v[170:173], v[202:205], v[0:3]
	s_mov_b32 m0, s44
	s_nop 0
	global_load_lds_dwordx4 v128, s[36:37]
	s_mov_b32 m0, s45
	s_nop 0
	global_load_lds_dwordx4 v130, s[36:37]
	v_mfma_f32_16x16x32_bf16 v[52:55], v[166:169], v[182:185], v[52:55]
	v_mfma_f32_16x16x32_bf16 v[48:51], v[174:177], v[182:185], v[48:51]
	v_mfma_f32_16x16x32_bf16 v[36:39], v[166:169], v[190:193], v[36:39]
	v_mfma_f32_16x16x32_bf16 v[32:35], v[174:177], v[190:193], v[32:35]
	v_mfma_f32_16x16x32_bf16 v[20:23], v[166:169], v[198:201], v[20:23]
	v_mfma_f32_16x16x32_bf16 v[16:19], v[174:177], v[198:201], v[16:19]
	v_mfma_f32_16x16x32_bf16 v[4:7], v[166:169], v[208:211], v[4:7]
	v_mfma_f32_16x16x32_bf16 v[0:3], v[174:177], v[208:211], v[0:3]
	s_barrier
	s_add_i32 s59, 0, 0x18000
	s_add_i32 s60, 0, 0x1c000
	s_add_u32 s28, s36, 0x40000
	s_addc_u32 s29, s37, 0
	s_mov_b32 m0, s46
	s_nop 0
	global_load_lds_dwordx4 v128, s[28:29]
	s_mov_b32 m0, s47
	s_nop 0
	global_load_lds_dwordx4 v130, s[28:29]
	v_add_u32_e32 v158, s59, v145
	v_add_u32_e32 v174, s60, v145
	ds_read_b128 v[140:143], v158
	ds_read_b128 v[150:153], v158 offset:1024
	ds_read_b128 v[154:157], v158 offset:2048
	ds_read_b128 v[158:161], v158 offset:3072
	ds_read_b128 v[162:165], v174
	ds_read_b128 v[166:169], v174 offset:1024
	ds_read_b128 v[170:173], v174 offset:2048
	ds_read_b128 v[174:177], v174 offset:3072
	ds_read_b128 v[178:181], v149 offset:32768
	ds_read_b128 v[182:185], v149 offset:33792
	ds_read_b128 v[186:189], v149 offset:34816
	ds_read_b128 v[190:193], v149 offset:35840
	ds_read_b128 v[194:197], v149 offset:36864
	ds_read_b128 v[198:201], v149 offset:37888
	ds_read_b128 v[202:205], v149 offset:38912
	ds_read_b128 v[208:211], v149 offset:39936
	s_waitcnt vmcnt(8)
	s_waitcnt lgkmcnt(0)
	s_barrier
	s_waitcnt lgkmcnt(0)
	v_mfma_f32_16x16x32_bf16 v[124:127], v[140:143], v[178:181], v[124:127]
	v_mfma_f32_16x16x32_bf16 v[120:123], v[154:157], v[178:181], v[120:123]
	v_mfma_f32_16x16x32_bf16 v[108:111], v[140:143], v[186:189], v[108:111]
	v_mfma_f32_16x16x32_bf16 v[104:107], v[154:157], v[186:189], v[104:107]
	v_mfma_f32_16x16x32_bf16 v[92:95], v[140:143], v[194:197], v[92:95]
	v_mfma_f32_16x16x32_bf16 v[88:91], v[154:157], v[194:197], v[88:91]
	v_mfma_f32_16x16x32_bf16 v[76:79], v[140:143], v[202:205], v[76:79]
	v_mfma_f32_16x16x32_bf16 v[72:75], v[154:157], v[202:205], v[72:75]
	v_mfma_f32_16x16x32_bf16 v[124:127], v[150:153], v[182:185], v[124:127]
	v_mfma_f32_16x16x32_bf16 v[120:123], v[158:161], v[182:185], v[120:123]
	v_mfma_f32_16x16x32_bf16 v[108:111], v[150:153], v[190:193], v[108:111]
	v_mfma_f32_16x16x32_bf16 v[104:107], v[158:161], v[190:193], v[104:107]
	v_mfma_f32_16x16x32_bf16 v[92:95], v[150:153], v[198:201], v[92:95]
	v_mfma_f32_16x16x32_bf16 v[88:91], v[158:161], v[198:201], v[88:91]
	v_mfma_f32_16x16x32_bf16 v[76:79], v[150:153], v[208:211], v[76:79]
	v_mfma_f32_16x16x32_bf16 v[72:75], v[158:161], v[208:211], v[72:75]
	v_mfma_f32_16x16x32_bf16 v[116:119], v[162:165], v[178:181], v[116:119]
	v_mfma_f32_16x16x32_bf16 v[112:115], v[170:173], v[178:181], v[112:115]
	v_mfma_f32_16x16x32_bf16 v[100:103], v[162:165], v[186:189], v[100:103]
	v_mfma_f32_16x16x32_bf16 v[96:99], v[170:173], v[186:189], v[96:99]
	v_mfma_f32_16x16x32_bf16 v[84:87], v[162:165], v[194:197], v[84:87]
	v_mfma_f32_16x16x32_bf16 v[80:83], v[170:173], v[194:197], v[80:83]
	v_mfma_f32_16x16x32_bf16 v[68:71], v[162:165], v[202:205], v[68:71]
	v_mfma_f32_16x16x32_bf16 v[64:67], v[170:173], v[202:205], v[64:67]
	v_mfma_f32_16x16x32_bf16 v[116:119], v[166:169], v[182:185], v[116:119]
	v_mfma_f32_16x16x32_bf16 v[112:115], v[174:177], v[182:185], v[112:115]
	v_mfma_f32_16x16x32_bf16 v[100:103], v[166:169], v[190:193], v[100:103]
	v_mfma_f32_16x16x32_bf16 v[96:99], v[174:177], v[190:193], v[96:99]
	v_mfma_f32_16x16x32_bf16 v[84:87], v[166:169], v[198:201], v[84:87]
	v_mfma_f32_16x16x32_bf16 v[80:83], v[174:177], v[198:201], v[80:83]
	v_mfma_f32_16x16x32_bf16 v[68:71], v[166:169], v[208:211], v[68:71]
	v_mfma_f32_16x16x32_bf16 v[64:67], v[174:177], v[208:211], v[64:67]
	s_barrier
	s_add_i32 s28, s59, s43
	s_mov_b32 m0, s28
	s_nop 0
	global_load_lds_dwordx4 v212, s[34:35]
	s_add_i32 m0, s28, 0x2000
	s_add_u32 s28, s34, 0x40080
	s_addc_u32 s29, s35, 0
	s_add_i32 s34, s60, s43
	global_load_lds_dwordx4 v213, s[98:99]
	s_mov_b32 m0, s34
	s_nop 0
	global_load_lds_dwordx4 v128, s[28:29]
	s_add_i32 m0, s34, 0x2000
	s_nop 0
	global_load_lds_dwordx4 v130, s[28:29]
	ds_read_b128 v[178:181], v149 offset:49152
	ds_read_b128 v[182:185], v149 offset:50176
	ds_read_b128 v[186:189], v149 offset:51200
	ds_read_b128 v[190:193], v149 offset:52224
	ds_read_b128 v[194:197], v149 offset:53248
	ds_read_b128 v[198:201], v149 offset:54272
	ds_read_b128 v[202:205], v149 offset:55296
	ds_read_b128 v[208:211], v149 offset:56320
	s_waitcnt vmcnt(6)
	s_waitcnt lgkmcnt(0)
	s_barrier
	s_waitcnt lgkmcnt(0)
	v_mfma_f32_16x16x32_bf16 v[60:63], v[140:143], v[178:181], v[60:63]
	v_mfma_f32_16x16x32_bf16 v[56:59], v[154:157], v[178:181], v[56:59]
	v_mfma_f32_16x16x32_bf16 v[44:47], v[140:143], v[186:189], v[44:47]
	v_mfma_f32_16x16x32_bf16 v[40:43], v[154:157], v[186:189], v[40:43]
	v_mfma_f32_16x16x32_bf16 v[28:31], v[140:143], v[194:197], v[28:31]
	v_mfma_f32_16x16x32_bf16 v[24:27], v[154:157], v[194:197], v[24:27]
	v_mfma_f32_16x16x32_bf16 v[12:15], v[140:143], v[202:205], v[12:15]
	v_mfma_f32_16x16x32_bf16 v[8:11], v[154:157], v[202:205], v[8:11]
	v_mfma_f32_16x16x32_bf16 v[60:63], v[150:153], v[182:185], v[60:63]
	v_mfma_f32_16x16x32_bf16 v[56:59], v[158:161], v[182:185], v[56:59]
	v_mfma_f32_16x16x32_bf16 v[44:47], v[150:153], v[190:193], v[44:47]
	v_mfma_f32_16x16x32_bf16 v[40:43], v[158:161], v[190:193], v[40:43]
	v_mfma_f32_16x16x32_bf16 v[28:31], v[150:153], v[198:201], v[28:31]
	v_mfma_f32_16x16x32_bf16 v[24:27], v[158:161], v[198:201], v[24:27]
	v_mfma_f32_16x16x32_bf16 v[12:15], v[150:153], v[208:211], v[12:15]
	v_mfma_f32_16x16x32_bf16 v[8:11], v[158:161], v[208:211], v[8:11]
	v_mfma_f32_16x16x32_bf16 v[52:55], v[162:165], v[178:181], v[52:55]
	v_mfma_f32_16x16x32_bf16 v[48:51], v[170:173], v[178:181], v[48:51]
	v_mfma_f32_16x16x32_bf16 v[36:39], v[162:165], v[186:189], v[36:39]
	v_mfma_f32_16x16x32_bf16 v[32:35], v[170:173], v[186:189], v[32:35]
	v_mfma_f32_16x16x32_bf16 v[20:23], v[162:165], v[194:197], v[20:23]
	v_mfma_f32_16x16x32_bf16 v[16:19], v[170:173], v[194:197], v[16:19]
	v_mfma_f32_16x16x32_bf16 v[4:7], v[162:165], v[202:205], v[4:7]
	v_mfma_f32_16x16x32_bf16 v[0:3], v[170:173], v[202:205], v[0:3]
	s_mov_b32 m0, s49
	s_nop 0
	global_load_lds_dwordx4 v212, s[36:37]
	s_mov_b32 m0, s50
	s_nop 0
	global_load_lds_dwordx4 v213, s[36:37]
	v_mfma_f32_16x16x32_bf16 v[52:55], v[166:169], v[182:185], v[52:55]
	v_mfma_f32_16x16x32_bf16 v[48:51], v[174:177], v[182:185], v[48:51]
	v_mfma_f32_16x16x32_bf16 v[36:39], v[166:169], v[190:193], v[36:39]
	v_mfma_f32_16x16x32_bf16 v[32:35], v[174:177], v[190:193], v[32:35]
	v_mfma_f32_16x16x32_bf16 v[20:23], v[166:169], v[198:201], v[20:23]
	v_mfma_f32_16x16x32_bf16 v[16:19], v[174:177], v[198:201], v[16:19]
	v_mfma_f32_16x16x32_bf16 v[4:7], v[166:169], v[208:211], v[4:7]
	v_mfma_f32_16x16x32_bf16 v[0:3], v[174:177], v[208:211], v[0:3]
	s_barrier
	s_add_i32 s58, s58, 2
	s_add_u32 s56, s56, 0x100
	s_addc_u32 s57, s57, 0
	s_cmp_gt_u32 s58, 13
	s_mov_b64 s[28:29], s[30:31]
	s_cbranch_scc0 .LBB0_606
	s_setprio 0
	s_and_b64 vcc, exec, s[16:17]
	s_cbranch_vccz .LBB0_609
	s_barrier

.LBB0_699:
	s_add_u32 s28, s26, 0xfffc0080
	s_addc_u32 s29, s27, -1
	s_cmp_eq_u32 s53, 12
	s_cselect_b32 s31, s21, s29
	s_cselect_b32 s30, s49, s28
	s_cselect_b32 s29, s19, s52
	s_cselect_b32 s28, s50, s51
	s_add_i32 m0, s39, 0xc000
	s_nop 0
	global_load_lds_dwordx4 v138, s[26:27]
	s_add_i32 m0, s39, 0xe000
	s_nop 0
	global_load_lds_dwordx4 v136, s[26:27]
	ds_read_b128 v[144:147], v151
	ds_read_b128 v[156:159], v151 offset:1024
	ds_read_b128 v[160:163], v151 offset:2048
	ds_read_b128 v[164:167], v151 offset:3072
	ds_read_b128 v[168:171], v152
	ds_read_b128 v[172:175], v152 offset:1024
	ds_read_b128 v[176:179], v152 offset:2048
	ds_read_b128 v[180:183], v152 offset:3072
	ds_read_b128 v[184:187], v153
	ds_read_b128 v[188:191], v153 offset:1024
	ds_read_b128 v[192:195], v153 offset:2048
	ds_read_b128 v[196:199], v153 offset:3072
	ds_read_b128 v[200:203], v153 offset:4096
	ds_read_b128 v[208:211], v153 offset:5120
	ds_read_b128 v[212:215], v153 offset:6144
	ds_read_b128 v[216:219], v153 offset:7168
	s_waitcnt vmcnt(8)
	s_waitcnt lgkmcnt(0)
	s_barrier
	s_waitcnt lgkmcnt(0)
	v_mfma_f32_16x16x32_bf16 v[124:127], v[144:147], v[184:187], v[124:127]
	v_mfma_f32_16x16x32_bf16 v[120:123], v[160:163], v[184:187], v[120:123]
	v_mfma_f32_16x16x32_bf16 v[108:111], v[144:147], v[192:195], v[108:111]
	v_mfma_f32_16x16x32_bf16 v[104:107], v[160:163], v[192:195], v[104:107]
	v_mfma_f32_16x16x32_bf16 v[92:95], v[144:147], v[200:203], v[92:95]
	v_mfma_f32_16x16x32_bf16 v[88:91], v[160:163], v[200:203], v[88:91]
	v_mfma_f32_16x16x32_bf16 v[76:79], v[144:147], v[212:215], v[76:79]
	v_mfma_f32_16x16x32_bf16 v[72:75], v[160:163], v[212:215], v[72:75]
	v_mfma_f32_16x16x32_bf16 v[124:127], v[156:159], v[188:191], v[124:127]
	v_mfma_f32_16x16x32_bf16 v[120:123], v[164:167], v[188:191], v[120:123]
	v_mfma_f32_16x16x32_bf16 v[108:111], v[156:159], v[196:199], v[108:111]
	v_mfma_f32_16x16x32_bf16 v[104:107], v[164:167], v[196:199], v[104:107]
	v_mfma_f32_16x16x32_bf16 v[92:95], v[156:159], v[208:211], v[92:95]
	v_mfma_f32_16x16x32_bf16 v[88:91], v[164:167], v[208:211], v[88:91]
	v_mfma_f32_16x16x32_bf16 v[76:79], v[156:159], v[216:219], v[76:79]
	v_mfma_f32_16x16x32_bf16 v[72:75], v[164:167], v[216:219], v[72:75]
	v_mfma_f32_16x16x32_bf16 v[116:119], v[168:171], v[184:187], v[116:119]
	v_mfma_f32_16x16x32_bf16 v[112:115], v[176:179], v[184:187], v[112:115]
	v_mfma_f32_16x16x32_bf16 v[100:103], v[168:171], v[192:195], v[100:103]
	v_mfma_f32_16x16x32_bf16 v[96:99], v[176:179], v[192:195], v[96:99]
	v_mfma_f32_16x16x32_bf16 v[84:87], v[168:171], v[200:203], v[84:87]
	v_mfma_f32_16x16x32_bf16 v[80:83], v[176:179], v[200:203], v[80:83]
	v_mfma_f32_16x16x32_bf16 v[68:71], v[168:171], v[212:215], v[68:71]
	v_mfma_f32_16x16x32_bf16 v[64:67], v[176:179], v[212:215], v[64:67]
	v_mfma_f32_16x16x32_bf16 v[116:119], v[172:175], v[188:191], v[116:119]
	v_mfma_f32_16x16x32_bf16 v[112:115], v[180:183], v[188:191], v[112:115]
	v_mfma_f32_16x16x32_bf16 v[100:103], v[172:175], v[196:199], v[100:103]
	v_mfma_f32_16x16x32_bf16 v[96:99], v[180:183], v[196:199], v[96:99]
	v_mfma_f32_16x16x32_bf16 v[84:87], v[172:175], v[208:211], v[84:87]
	v_mfma_f32_16x16x32_bf16 v[80:83], v[180:183], v[208:211], v[80:83]
	v_mfma_f32_16x16x32_bf16 v[68:71], v[172:175], v[216:219], v[68:71]
	v_mfma_f32_16x16x32_bf16 v[64:67], v[180:183], v[216:219], v[64:67]
	s_barrier
	s_add_i32 s54, s46, s38
	s_mov_b32 m0, s54
	s_nop 0
	global_load_lds_dwordx4 v130, s[28:29]
	s_add_i32 m0, s54, 0x2000
	s_add_u32 s54, s28, 0x40000
	s_mov_b64 s[98:99], s[28:29]
	s_addc_u32 s55, s29, 0
	s_add_i32 s56, s47, s38
	global_load_lds_dwordx4 v134, s[28:29]
	s_mov_b32 m0, s56
	s_mov_b64 s[100:101], s[30:31]
	global_load_lds_dwordx4 v130, s[54:55]
	s_add_i32 m0, s56, 0x2000
	s_nop 0
	global_load_lds_dwordx4 v134, s[54:55]
	ds_read_b128 v[184:187], v153 offset:16384
	ds_read_b128 v[188:191], v153 offset:17408
	ds_read_b128 v[192:195], v153 offset:18432
	ds_read_b128 v[196:199], v153 offset:19456
	ds_read_b128 v[200:203], v153 offset:20480
	ds_read_b128 v[208:211], v153 offset:21504
	ds_read_b128 v[212:215], v153 offset:22528
	ds_read_b128 v[216:219], v153 offset:23552
	s_waitcnt vmcnt(6)
	s_waitcnt lgkmcnt(0)
	s_barrier
	s_waitcnt lgkmcnt(0)
	v_mfma_f32_16x16x32_bf16 v[60:63], v[144:147], v[184:187], v[60:63]
	v_mfma_f32_16x16x32_bf16 v[56:59], v[160:163], v[184:187], v[56:59]
	v_mfma_f32_16x16x32_bf16 v[44:47], v[144:147], v[192:195], v[44:47]
	v_mfma_f32_16x16x32_bf16 v[40:43], v[160:163], v[192:195], v[40:43]
	v_mfma_f32_16x16x32_bf16 v[28:31], v[144:147], v[200:203], v[28:31]
	v_mfma_f32_16x16x32_bf16 v[24:27], v[160:163], v[200:203], v[24:27]
	v_mfma_f32_16x16x32_bf16 v[12:15], v[144:147], v[212:215], v[12:15]
	v_mfma_f32_16x16x32_bf16 v[8:11], v[160:163], v[212:215], v[8:11]
	v_mfma_f32_16x16x32_bf16 v[60:63], v[156:159], v[188:191], v[60:63]
	v_mfma_f32_16x16x32_bf16 v[56:59], v[164:167], v[188:191], v[56:59]
	v_mfma_f32_16x16x32_bf16 v[44:47], v[156:159], v[196:199], v[44:47]
	v_mfma_f32_16x16x32_bf16 v[40:43], v[164:167], v[196:199], v[40:43]
	v_mfma_f32_16x16x32_bf16 v[28:31], v[156:159], v[208:211], v[28:31]
	v_mfma_f32_16x16x32_bf16 v[24:27], v[164:167], v[208:211], v[24:27]
	v_mfma_f32_16x16x32_bf16 v[12:15], v[156:159], v[216:219], v[12:15]
	v_mfma_f32_16x16x32_bf16 v[8:11], v[164:167], v[216:219], v[8:11]
	v_mfma_f32_16x16x32_bf16 v[52:55], v[168:171], v[184:187], v[52:55]
	v_mfma_f32_16x16x32_bf16 v[48:51], v[176:179], v[184:187], v[48:51]
	v_mfma_f32_16x16x32_bf16 v[36:39], v[168:171], v[192:195], v[36:39]
	v_mfma_f32_16x16x32_bf16 v[32:35], v[176:179], v[192:195], v[32:35]
	v_mfma_f32_16x16x32_bf16 v[20:23], v[168:171], v[200:203], v[20:23]
	v_mfma_f32_16x16x32_bf16 v[16:19], v[176:179], v[200:203], v[16:19]
	v_mfma_f32_16x16x32_bf16 v[4:7], v[168:171], v[212:215], v[4:7]
	v_mfma_f32_16x16x32_bf16 v[0:3], v[176:179], v[212:215], v[0:3]
	s_mov_b32 m0, s39
	s_nop 0
	global_load_lds_dwordx4 v128, s[30:31]
	s_mov_b32 m0, s40
	s_nop 0
	global_load_lds_dwordx4 v132, s[30:31]
	v_mfma_f32_16x16x32_bf16 v[52:55], v[172:175], v[188:191], v[52:55]
	v_mfma_f32_16x16x32_bf16 v[48:51], v[180:183], v[188:191], v[48:51]
	v_mfma_f32_16x16x32_bf16 v[36:39], v[172:175], v[196:199], v[36:39]
	v_mfma_f32_16x16x32_bf16 v[32:35], v[180:183], v[196:199], v[32:35]
	v_mfma_f32_16x16x32_bf16 v[20:23], v[172:175], v[208:211], v[20:23]
	v_mfma_f32_16x16x32_bf16 v[16:19], v[180:183], v[208:211], v[16:19]
	v_mfma_f32_16x16x32_bf16 v[4:7], v[172:175], v[216:219], v[4:7]
	v_mfma_f32_16x16x32_bf16 v[0:3], v[180:183], v[216:219], v[0:3]
	s_barrier
	s_add_i32 s54, 0, 0x18000
	s_add_i32 s55, 0, 0x1c000
	s_add_u32 s30, s30, 0x40000
	s_addc_u32 s31, s31, 0
	s_mov_b32 m0, s41
	s_nop 0
	global_load_lds_dwordx4 v128, s[30:31]
	s_mov_b32 m0, s42
	s_nop 0
	global_load_lds_dwordx4 v132, s[30:31]
	v_add_u32_e32 v155, s54, v149
	ds_read_b128 v[144:147], v155
	ds_read_b128 v[156:159], v155 offset:1024
	ds_read_b128 v[160:163], v155 offset:2048
	ds_read_b128 v[164:167], v155 offset:3072
	v_add_u32_e32 v155, s55, v149
	ds_read_b128 v[168:171], v155
	ds_read_b128 v[172:175], v155 offset:1024
	ds_read_b128 v[176:179], v155 offset:2048
	ds_read_b128 v[180:183], v155 offset:3072
	ds_read_b128 v[184:187], v153 offset:32768
	ds_read_b128 v[188:191], v153 offset:33792
	ds_read_b128 v[192:195], v153 offset:34816
	ds_read_b128 v[196:199], v153 offset:35840
	ds_read_b128 v[200:203], v153 offset:36864
	ds_read_b128 v[208:211], v153 offset:37888
	ds_read_b128 v[212:215], v153 offset:38912
	ds_read_b128 v[216:219], v153 offset:39936
	s_waitcnt vmcnt(8)
	s_waitcnt lgkmcnt(0)
	s_barrier
	s_waitcnt lgkmcnt(0)
	v_mfma_f32_16x16x32_bf16 v[124:127], v[144:147], v[184:187], v[124:127]
	v_mfma_f32_16x16x32_bf16 v[120:123], v[160:163], v[184:187], v[120:123]
	v_mfma_f32_16x16x32_bf16 v[108:111], v[144:147], v[192:195], v[108:111]
	v_mfma_f32_16x16x32_bf16 v[104:107], v[160:163], v[192:195], v[104:107]
	v_mfma_f32_16x16x32_bf16 v[92:95], v[144:147], v[200:203], v[92:95]
	v_mfma_f32_16x16x32_bf16 v[88:91], v[160:163], v[200:203], v[88:91]
	v_mfma_f32_16x16x32_bf16 v[76:79], v[144:147], v[212:215], v[76:79]
	v_mfma_f32_16x16x32_bf16 v[72:75], v[160:163], v[212:215], v[72:75]
	v_mfma_f32_16x16x32_bf16 v[124:127], v[156:159], v[188:191], v[124:127]
	v_mfma_f32_16x16x32_bf16 v[120:123], v[164:167], v[188:191], v[120:123]
	v_mfma_f32_16x16x32_bf16 v[108:111], v[156:159], v[196:199], v[108:111]
	v_mfma_f32_16x16x32_bf16 v[104:107], v[164:167], v[196:199], v[104:107]
	v_mfma_f32_16x16x32_bf16 v[92:95], v[156:159], v[208:211], v[92:95]
	v_mfma_f32_16x16x32_bf16 v[88:91], v[164:167], v[208:211], v[88:91]
	v_mfma_f32_16x16x32_bf16 v[76:79], v[156:159], v[216:219], v[76:79]
	v_mfma_f32_16x16x32_bf16 v[72:75], v[164:167], v[216:219], v[72:75]
	v_mfma_f32_16x16x32_bf16 v[116:119], v[168:171], v[184:187], v[116:119]
	v_mfma_f32_16x16x32_bf16 v[112:115], v[176:179], v[184:187], v[112:115]
	v_mfma_f32_16x16x32_bf16 v[100:103], v[168:171], v[192:195], v[100:103]
	v_mfma_f32_16x16x32_bf16 v[96:99], v[176:179], v[192:195], v[96:99]
	v_mfma_f32_16x16x32_bf16 v[84:87], v[168:171], v[200:203], v[84:87]
	v_mfma_f32_16x16x32_bf16 v[80:83], v[176:179], v[200:203], v[80:83]
	v_mfma_f32_16x16x32_bf16 v[68:71], v[168:171], v[212:215], v[68:71]
	v_mfma_f32_16x16x32_bf16 v[64:67], v[176:179], v[212:215], v[64:67]
	v_mfma_f32_16x16x32_bf16 v[116:119], v[172:175], v[188:191], v[116:119]
	v_mfma_f32_16x16x32_bf16 v[112:115], v[180:183], v[188:191], v[112:115]
	v_mfma_f32_16x16x32_bf16 v[100:103], v[172:175], v[196:199], v[100:103]
	v_mfma_f32_16x16x32_bf16 v[96:99], v[180:183], v[196:199], v[96:99]
	v_mfma_f32_16x16x32_bf16 v[84:87], v[172:175], v[208:211], v[84:87]
	v_mfma_f32_16x16x32_bf16 v[80:83], v[180:183], v[208:211], v[80:83]
	v_mfma_f32_16x16x32_bf16 v[68:71], v[172:175], v[216:219], v[68:71]
	v_mfma_f32_16x16x32_bf16 v[64:67], v[180:183], v[216:219], v[64:67]
	s_barrier
	s_add_i32 s30, s54, s38
	s_mov_b32 m0, s30
	s_nop 0
	global_load_lds_dwordx4 v205, s[28:29]
	s_add_i32 m0, s30, 0x2000
	s_add_u32 s28, s28, 0x40080
	s_addc_u32 s29, s29, 0
	s_add_i32 s30, s55, s38
	global_load_lds_dwordx4 v221, s[98:99]
	s_mov_b32 m0, s30
	s_nop 0
	global_load_lds_dwordx4 v130, s[28:29]
	s_add_i32 m0, s30, 0x2000
	s_nop 0
	global_load_lds_dwordx4 v134, s[28:29]
	ds_read_b128 v[184:187], v153 offset:49152
	ds_read_b128 v[188:191], v153 offset:50176
	ds_read_b128 v[192:195], v153 offset:51200
	ds_read_b128 v[196:199], v153 offset:52224
	ds_read_b128 v[200:203], v153 offset:53248
	ds_read_b128 v[208:211], v153 offset:54272
	ds_read_b128 v[212:215], v153 offset:55296
	ds_read_b128 v[216:219], v153 offset:56320
	s_waitcnt vmcnt(6)
	s_waitcnt lgkmcnt(0)
	s_barrier
	s_waitcnt lgkmcnt(0)
	v_mfma_f32_16x16x32_bf16 v[60:63], v[144:147], v[184:187], v[60:63]
	v_mfma_f32_16x16x32_bf16 v[56:59], v[160:163], v[184:187], v[56:59]
	v_mfma_f32_16x16x32_bf16 v[44:47], v[144:147], v[192:195], v[44:47]
	v_mfma_f32_16x16x32_bf16 v[40:43], v[160:163], v[192:195], v[40:43]
	v_mfma_f32_16x16x32_bf16 v[28:31], v[144:147], v[200:203], v[28:31]
	v_mfma_f32_16x16x32_bf16 v[24:27], v[160:163], v[200:203], v[24:27]
	v_mfma_f32_16x16x32_bf16 v[12:15], v[144:147], v[212:215], v[12:15]
	v_mfma_f32_16x16x32_bf16 v[8:11], v[160:163], v[212:215], v[8:11]
	v_mfma_f32_16x16x32_bf16 v[60:63], v[156:159], v[188:191], v[60:63]
	v_mfma_f32_16x16x32_bf16 v[56:59], v[164:167], v[188:191], v[56:59]
	v_mfma_f32_16x16x32_bf16 v[44:47], v[156:159], v[196:199], v[44:47]
	v_mfma_f32_16x16x32_bf16 v[40:43], v[164:167], v[196:199], v[40:43]
	v_mfma_f32_16x16x32_bf16 v[28:31], v[156:159], v[208:211], v[28:31]
	v_mfma_f32_16x16x32_bf16 v[24:27], v[164:167], v[208:211], v[24:27]
	v_mfma_f32_16x16x32_bf16 v[12:15], v[156:159], v[216:219], v[12:15]
	v_mfma_f32_16x16x32_bf16 v[8:11], v[164:167], v[216:219], v[8:11]
	v_mfma_f32_16x16x32_bf16 v[52:55], v[168:171], v[184:187], v[52:55]
	v_mfma_f32_16x16x32_bf16 v[48:51], v[176:179], v[184:187], v[48:51]
	v_mfma_f32_16x16x32_bf16 v[36:39], v[168:171], v[192:195], v[36:39]
	v_mfma_f32_16x16x32_bf16 v[32:35], v[176:179], v[192:195], v[32:35]
	v_mfma_f32_16x16x32_bf16 v[20:23], v[168:171], v[200:203], v[20:23]
	v_mfma_f32_16x16x32_bf16 v[16:19], v[176:179], v[200:203], v[16:19]
	v_mfma_f32_16x16x32_bf16 v[4:7], v[168:171], v[212:215], v[4:7]
	v_mfma_f32_16x16x32_bf16 v[0:3], v[176:179], v[212:215], v[0:3]
	s_mov_b32 m0, s44
	s_nop 0
	global_load_lds_dwordx4 v204, s[100:101]
	s_mov_b32 m0, s45
	s_nop 0
	global_load_lds_dwordx4 v220, s[100:101]
	v_mfma_f32_16x16x32_bf16 v[52:55], v[172:175], v[188:191], v[52:55]
	v_mfma_f32_16x16x32_bf16 v[48:51], v[180:183], v[188:191], v[48:51]
	v_mfma_f32_16x16x32_bf16 v[36:39], v[172:175], v[196:199], v[36:39]
	v_mfma_f32_16x16x32_bf16 v[32:35], v[180:183], v[196:199], v[32:35]
	v_mfma_f32_16x16x32_bf16 v[20:23], v[172:175], v[208:211], v[20:23]
	v_mfma_f32_16x16x32_bf16 v[16:19], v[180:183], v[208:211], v[16:19]
	v_mfma_f32_16x16x32_bf16 v[4:7], v[172:175], v[216:219], v[4:7]
	v_mfma_f32_16x16x32_bf16 v[0:3], v[180:183], v[216:219], v[0:3]
	s_barrier
	s_add_i32 s53, s53, 2
	s_add_u32 s51, s51, 0x100
	s_addc_u32 s52, s52, 0
	s_add_u32 s26, s26, 0x100
	s_addc_u32 s27, s27, 0
	s_cmp_gt_u32 s53, 13
	s_cbranch_scc0 .LBB0_699
	s_setprio 0
	s_and_b64 vcc, exec, s[16:17]
	s_cbranch_vccz .LBB0_702
	s_barrier

.LBB0_778:
	s_add_u32 s30, s28, 0x100
	s_addc_u32 s31, s29, 0
	s_cmp_eq_u32 s58, 60
	s_cselect_b32 s37, s21, s31
	s_cselect_b32 s36, s27, s30
	s_cselect_b32 s35, s19, s57
	s_cselect_b32 s34, s55, s56
	s_add_i32 m0, s44, 0xc000
	s_nop 0
	global_load_lds_dwordx4 v134, s[28:29]
	s_add_i32 m0, s44, 0xe000
	s_nop 0
	global_load_lds_dwordx4 v132, s[28:29]
	ds_read_b128 v[140:143], v147
	ds_read_b128 v[150:153], v147 offset:1024
	ds_read_b128 v[154:157], v147 offset:2048
	ds_read_b128 v[158:161], v147 offset:3072
	ds_read_b128 v[162:165], v148
	ds_read_b128 v[166:169], v148 offset:1024
	ds_read_b128 v[170:173], v148 offset:2048
	ds_read_b128 v[174:177], v148 offset:3072
	ds_read_b128 v[178:181], v149
	ds_read_b128 v[182:185], v149 offset:1024
	ds_read_b128 v[186:189], v149 offset:2048
	ds_read_b128 v[190:193], v149 offset:3072
	ds_read_b128 v[194:197], v149 offset:4096
	ds_read_b128 v[198:201], v149 offset:5120
	ds_read_b128 v[202:205], v149 offset:6144
	ds_read_b128 v[208:211], v149 offset:7168
	s_waitcnt vmcnt(8)
	s_waitcnt lgkmcnt(0)
	s_barrier
	s_waitcnt lgkmcnt(0)
	v_mfma_f32_16x16x32_bf16 v[124:127], v[140:143], v[178:181], v[124:127]
	v_mfma_f32_16x16x32_bf16 v[120:123], v[154:157], v[178:181], v[120:123]
	v_mfma_f32_16x16x32_bf16 v[108:111], v[140:143], v[186:189], v[108:111]
	v_mfma_f32_16x16x32_bf16 v[104:107], v[154:157], v[186:189], v[104:107]
	v_mfma_f32_16x16x32_bf16 v[92:95], v[140:143], v[194:197], v[92:95]
	v_mfma_f32_16x16x32_bf16 v[88:91], v[154:157], v[194:197], v[88:91]
	v_mfma_f32_16x16x32_bf16 v[76:79], v[140:143], v[202:205], v[76:79]
	v_mfma_f32_16x16x32_bf16 v[72:75], v[154:157], v[202:205], v[72:75]
	v_mfma_f32_16x16x32_bf16 v[124:127], v[150:153], v[182:185], v[124:127]
	v_mfma_f32_16x16x32_bf16 v[120:123], v[158:161], v[182:185], v[120:123]
	v_mfma_f32_16x16x32_bf16 v[108:111], v[150:153], v[190:193], v[108:111]
	v_mfma_f32_16x16x32_bf16 v[104:107], v[158:161], v[190:193], v[104:107]
	v_mfma_f32_16x16x32_bf16 v[92:95], v[150:153], v[198:201], v[92:95]
	v_mfma_f32_16x16x32_bf16 v[88:91], v[158:161], v[198:201], v[88:91]
	v_mfma_f32_16x16x32_bf16 v[76:79], v[150:153], v[208:211], v[76:79]
	v_mfma_f32_16x16x32_bf16 v[72:75], v[158:161], v[208:211], v[72:75]
	v_mfma_f32_16x16x32_bf16 v[116:119], v[162:165], v[178:181], v[116:119]
	v_mfma_f32_16x16x32_bf16 v[112:115], v[170:173], v[178:181], v[112:115]
	v_mfma_f32_16x16x32_bf16 v[100:103], v[162:165], v[186:189], v[100:103]
	v_mfma_f32_16x16x32_bf16 v[96:99], v[170:173], v[186:189], v[96:99]
	v_mfma_f32_16x16x32_bf16 v[84:87], v[162:165], v[194:197], v[84:87]
	v_mfma_f32_16x16x32_bf16 v[80:83], v[170:173], v[194:197], v[80:83]
	v_mfma_f32_16x16x32_bf16 v[68:71], v[162:165], v[202:205], v[68:71]
	v_mfma_f32_16x16x32_bf16 v[64:67], v[170:173], v[202:205], v[64:67]
	v_mfma_f32_16x16x32_bf16 v[116:119], v[166:169], v[182:185], v[116:119]
	v_mfma_f32_16x16x32_bf16 v[112:115], v[174:177], v[182:185], v[112:115]
	v_mfma_f32_16x16x32_bf16 v[100:103], v[166:169], v[190:193], v[100:103]
	v_mfma_f32_16x16x32_bf16 v[96:99], v[174:177], v[190:193], v[96:99]
	v_mfma_f32_16x16x32_bf16 v[84:87], v[166:169], v[198:201], v[84:87]
	v_mfma_f32_16x16x32_bf16 v[80:83], v[174:177], v[198:201], v[80:83]
	v_mfma_f32_16x16x32_bf16 v[68:71], v[166:169], v[208:211], v[68:71]
	v_mfma_f32_16x16x32_bf16 v[64:67], v[174:177], v[208:211], v[64:67]
	s_barrier
	s_add_i32 s28, s52, s43
	s_mov_b32 m0, s28
	s_nop 0
	global_load_lds_dwordx4 v128, s[34:35]
	s_add_i32 m0, s28, 0x2000
	s_add_u32 s28, s34, 0x100000
	s_mov_b64 s[98:99], s[34:35]
	s_addc_u32 s29, s35, 0
	s_add_i32 s59, s53, s43
	global_load_lds_dwordx4 v130, s[34:35]
	s_mov_b32 m0, s59
	s_nop 0
	global_load_lds_dwordx4 v128, s[28:29]
	s_add_i32 m0, s59, 0x2000
	s_nop 0
	global_load_lds_dwordx4 v130, s[28:29]
	ds_read_b128 v[178:181], v149 offset:16384
	ds_read_b128 v[182:185], v149 offset:17408
	ds_read_b128 v[186:189], v149 offset:18432
	ds_read_b128 v[190:193], v149 offset:19456
	ds_read_b128 v[194:197], v149 offset:20480
	ds_read_b128 v[198:201], v149 offset:21504
	ds_read_b128 v[202:205], v149 offset:22528
	ds_read_b128 v[208:211], v149 offset:23552
	s_waitcnt vmcnt(6)
	s_waitcnt lgkmcnt(0)
	s_barrier
	s_waitcnt lgkmcnt(0)
	v_mfma_f32_16x16x32_bf16 v[60:63], v[140:143], v[178:181], v[60:63]
	v_mfma_f32_16x16x32_bf16 v[56:59], v[154:157], v[178:181], v[56:59]
	v_mfma_f32_16x16x32_bf16 v[44:47], v[140:143], v[186:189], v[44:47]
	v_mfma_f32_16x16x32_bf16 v[40:43], v[154:157], v[186:189], v[40:43]
	v_mfma_f32_16x16x32_bf16 v[28:31], v[140:143], v[194:197], v[28:31]
	v_mfma_f32_16x16x32_bf16 v[24:27], v[154:157], v[194:197], v[24:27]
	v_mfma_f32_16x16x32_bf16 v[12:15], v[140:143], v[202:205], v[12:15]
	v_mfma_f32_16x16x32_bf16 v[8:11], v[154:157], v[202:205], v[8:11]
	v_mfma_f32_16x16x32_bf16 v[60:63], v[150:153], v[182:185], v[60:63]
	v_mfma_f32_16x16x32_bf16 v[56:59], v[158:161], v[182:185], v[56:59]
	v_mfma_f32_16x16x32_bf16 v[44:47], v[150:153], v[190:193], v[44:47]
	v_mfma_f32_16x16x32_bf16 v[40:43], v[158:161], v[190:193], v[40:43]
	v_mfma_f32_16x16x32_bf16 v[28:31], v[150:153], v[198:201], v[28:31]
	v_mfma_f32_16x16x32_bf16 v[24:27], v[158:161], v[198:201], v[24:27]
	v_mfma_f32_16x16x32_bf16 v[12:15], v[150:153], v[208:211], v[12:15]
	v_mfma_f32_16x16x32_bf16 v[8:11], v[158:161], v[208:211], v[8:11]
	v_mfma_f32_16x16x32_bf16 v[52:55], v[162:165], v[178:181], v[52:55]
	v_mfma_f32_16x16x32_bf16 v[48:51], v[170:173], v[178:181], v[48:51]
	v_mfma_f32_16x16x32_bf16 v[36:39], v[162:165], v[186:189], v[36:39]
	v_mfma_f32_16x16x32_bf16 v[32:35], v[170:173], v[186:189], v[32:35]
	v_mfma_f32_16x16x32_bf16 v[20:23], v[162:165], v[194:197], v[20:23]
	v_mfma_f32_16x16x32_bf16 v[16:19], v[170:173], v[194:197], v[16:19]
	v_mfma_f32_16x16x32_bf16 v[4:7], v[162:165], v[202:205], v[4:7]
	v_mfma_f32_16x16x32_bf16 v[0:3], v[170:173], v[202:205], v[0:3]
	s_mov_b32 m0, s44
	s_nop 0
	global_load_lds_dwordx4 v128, s[36:37]
	s_mov_b32 m0, s45
	s_nop 0
	global_load_lds_dwordx4 v130, s[36:37]
	v_mfma_f32_16x16x32_bf16 v[52:55], v[166:169], v[182:185], v[52:55]
	v_mfma_f32_16x16x32_bf16 v[48:51], v[174:177], v[182:185], v[48:51]
	v_mfma_f32_16x16x32_bf16 v[36:39], v[166:169], v[190:193], v[36:39]
	v_mfma_f32_16x16x32_bf16 v[32:35], v[174:177], v[190:193], v[32:35]
	v_mfma_f32_16x16x32_bf16 v[20:23], v[166:169], v[198:201], v[20:23]
	v_mfma_f32_16x16x32_bf16 v[16:19], v[174:177], v[198:201], v[16:19]
	v_mfma_f32_16x16x32_bf16 v[4:7], v[166:169], v[208:211], v[4:7]
	v_mfma_f32_16x16x32_bf16 v[0:3], v[174:177], v[208:211], v[0:3]
	s_barrier
	s_add_i32 s59, 0, 0x18000
	s_add_i32 s60, 0, 0x1c000
	s_add_u32 s28, s36, 0x100000
	s_addc_u32 s29, s37, 0
	s_mov_b32 m0, s46
	s_nop 0
	global_load_lds_dwordx4 v128, s[28:29]
	s_mov_b32 m0, s47
	s_nop 0
	global_load_lds_dwordx4 v130, s[28:29]
	v_add_u32_e32 v158, s59, v145
	v_add_u32_e32 v174, s60, v145
	ds_read_b128 v[140:143], v158
	ds_read_b128 v[150:153], v158 offset:1024
	ds_read_b128 v[154:157], v158 offset:2048
	ds_read_b128 v[158:161], v158 offset:3072
	ds_read_b128 v[162:165], v174
	ds_read_b128 v[166:169], v174 offset:1024
	ds_read_b128 v[170:173], v174 offset:2048
	ds_read_b128 v[174:177], v174 offset:3072
	ds_read_b128 v[178:181], v149 offset:32768
	ds_read_b128 v[182:185], v149 offset:33792
	ds_read_b128 v[186:189], v149 offset:34816
	ds_read_b128 v[190:193], v149 offset:35840
	ds_read_b128 v[194:197], v149 offset:36864
	ds_read_b128 v[198:201], v149 offset:37888
	ds_read_b128 v[202:205], v149 offset:38912
	ds_read_b128 v[208:211], v149 offset:39936
	s_waitcnt vmcnt(8)
	s_waitcnt lgkmcnt(0)
	s_barrier
	s_waitcnt lgkmcnt(0)
	v_mfma_f32_16x16x32_bf16 v[124:127], v[140:143], v[178:181], v[124:127]
	v_mfma_f32_16x16x32_bf16 v[120:123], v[154:157], v[178:181], v[120:123]
	v_mfma_f32_16x16x32_bf16 v[108:111], v[140:143], v[186:189], v[108:111]
	v_mfma_f32_16x16x32_bf16 v[104:107], v[154:157], v[186:189], v[104:107]
	v_mfma_f32_16x16x32_bf16 v[92:95], v[140:143], v[194:197], v[92:95]
	v_mfma_f32_16x16x32_bf16 v[88:91], v[154:157], v[194:197], v[88:91]
	v_mfma_f32_16x16x32_bf16 v[76:79], v[140:143], v[202:205], v[76:79]
	v_mfma_f32_16x16x32_bf16 v[72:75], v[154:157], v[202:205], v[72:75]
	v_mfma_f32_16x16x32_bf16 v[124:127], v[150:153], v[182:185], v[124:127]
	v_mfma_f32_16x16x32_bf16 v[120:123], v[158:161], v[182:185], v[120:123]
	v_mfma_f32_16x16x32_bf16 v[108:111], v[150:153], v[190:193], v[108:111]
	v_mfma_f32_16x16x32_bf16 v[104:107], v[158:161], v[190:193], v[104:107]
	v_mfma_f32_16x16x32_bf16 v[92:95], v[150:153], v[198:201], v[92:95]
	v_mfma_f32_16x16x32_bf16 v[88:91], v[158:161], v[198:201], v[88:91]
	v_mfma_f32_16x16x32_bf16 v[76:79], v[150:153], v[208:211], v[76:79]
	v_mfma_f32_16x16x32_bf16 v[72:75], v[158:161], v[208:211], v[72:75]
	v_mfma_f32_16x16x32_bf16 v[116:119], v[162:165], v[178:181], v[116:119]
	v_mfma_f32_16x16x32_bf16 v[112:115], v[170:173], v[178:181], v[112:115]
	v_mfma_f32_16x16x32_bf16 v[100:103], v[162:165], v[186:189], v[100:103]
	v_mfma_f32_16x16x32_bf16 v[96:99], v[170:173], v[186:189], v[96:99]
	v_mfma_f32_16x16x32_bf16 v[84:87], v[162:165], v[194:197], v[84:87]
	v_mfma_f32_16x16x32_bf16 v[80:83], v[170:173], v[194:197], v[80:83]
	v_mfma_f32_16x16x32_bf16 v[68:71], v[162:165], v[202:205], v[68:71]
	v_mfma_f32_16x16x32_bf16 v[64:67], v[170:173], v[202:205], v[64:67]
	v_mfma_f32_16x16x32_bf16 v[116:119], v[166:169], v[182:185], v[116:119]
	v_mfma_f32_16x16x32_bf16 v[112:115], v[174:177], v[182:185], v[112:115]
	v_mfma_f32_16x16x32_bf16 v[100:103], v[166:169], v[190:193], v[100:103]
	v_mfma_f32_16x16x32_bf16 v[96:99], v[174:177], v[190:193], v[96:99]
	v_mfma_f32_16x16x32_bf16 v[84:87], v[166:169], v[198:201], v[84:87]
	v_mfma_f32_16x16x32_bf16 v[80:83], v[174:177], v[198:201], v[80:83]
	v_mfma_f32_16x16x32_bf16 v[68:71], v[166:169], v[208:211], v[68:71]
	v_mfma_f32_16x16x32_bf16 v[64:67], v[174:177], v[208:211], v[64:67]
	s_barrier
	s_add_i32 s28, s59, s43
	s_mov_b32 m0, s28
	s_nop 0
	global_load_lds_dwordx4 v212, s[34:35]
	s_add_i32 m0, s28, 0x2000
	s_add_u32 s28, s34, 0x100080
	s_addc_u32 s29, s35, 0
	s_add_i32 s34, s60, s43
	global_load_lds_dwordx4 v213, s[98:99]
	s_mov_b32 m0, s34
	s_nop 0
	global_load_lds_dwordx4 v128, s[28:29]
	s_add_i32 m0, s34, 0x2000
	s_nop 0
	global_load_lds_dwordx4 v130, s[28:29]
	ds_read_b128 v[178:181], v149 offset:49152
	ds_read_b128 v[182:185], v149 offset:50176
	ds_read_b128 v[186:189], v149 offset:51200
	ds_read_b128 v[190:193], v149 offset:52224
	ds_read_b128 v[194:197], v149 offset:53248
	ds_read_b128 v[198:201], v149 offset:54272
	ds_read_b128 v[202:205], v149 offset:55296
	ds_read_b128 v[208:211], v149 offset:56320
	s_waitcnt vmcnt(6)
	s_waitcnt lgkmcnt(0)
	s_barrier
	s_waitcnt lgkmcnt(0)
	v_mfma_f32_16x16x32_bf16 v[60:63], v[140:143], v[178:181], v[60:63]
	v_mfma_f32_16x16x32_bf16 v[56:59], v[154:157], v[178:181], v[56:59]
	v_mfma_f32_16x16x32_bf16 v[44:47], v[140:143], v[186:189], v[44:47]
	v_mfma_f32_16x16x32_bf16 v[40:43], v[154:157], v[186:189], v[40:43]
	v_mfma_f32_16x16x32_bf16 v[28:31], v[140:143], v[194:197], v[28:31]
	v_mfma_f32_16x16x32_bf16 v[24:27], v[154:157], v[194:197], v[24:27]
	v_mfma_f32_16x16x32_bf16 v[12:15], v[140:143], v[202:205], v[12:15]
	v_mfma_f32_16x16x32_bf16 v[8:11], v[154:157], v[202:205], v[8:11]
	v_mfma_f32_16x16x32_bf16 v[60:63], v[150:153], v[182:185], v[60:63]
	v_mfma_f32_16x16x32_bf16 v[56:59], v[158:161], v[182:185], v[56:59]
	v_mfma_f32_16x16x32_bf16 v[44:47], v[150:153], v[190:193], v[44:47]
	v_mfma_f32_16x16x32_bf16 v[40:43], v[158:161], v[190:193], v[40:43]
	v_mfma_f32_16x16x32_bf16 v[28:31], v[150:153], v[198:201], v[28:31]
	v_mfma_f32_16x16x32_bf16 v[24:27], v[158:161], v[198:201], v[24:27]
	v_mfma_f32_16x16x32_bf16 v[12:15], v[150:153], v[208:211], v[12:15]
	v_mfma_f32_16x16x32_bf16 v[8:11], v[158:161], v[208:211], v[8:11]
	v_mfma_f32_16x16x32_bf16 v[52:55], v[162:165], v[178:181], v[52:55]
	v_mfma_f32_16x16x32_bf16 v[48:51], v[170:173], v[178:181], v[48:51]
	v_mfma_f32_16x16x32_bf16 v[36:39], v[162:165], v[186:189], v[36:39]
	v_mfma_f32_16x16x32_bf16 v[32:35], v[170:173], v[186:189], v[32:35]
	v_mfma_f32_16x16x32_bf16 v[20:23], v[162:165], v[194:197], v[20:23]
	v_mfma_f32_16x16x32_bf16 v[16:19], v[170:173], v[194:197], v[16:19]
	v_mfma_f32_16x16x32_bf16 v[4:7], v[162:165], v[202:205], v[4:7]
	v_mfma_f32_16x16x32_bf16 v[0:3], v[170:173], v[202:205], v[0:3]
	s_mov_b32 m0, s49
	s_nop 0
	global_load_lds_dwordx4 v212, s[36:37]
	s_mov_b32 m0, s50
	s_nop 0
	global_load_lds_dwordx4 v213, s[36:37]
	v_mfma_f32_16x16x32_bf16 v[52:55], v[166:169], v[182:185], v[52:55]
	v_mfma_f32_16x16x32_bf16 v[48:51], v[174:177], v[182:185], v[48:51]
	v_mfma_f32_16x16x32_bf16 v[36:39], v[166:169], v[190:193], v[36:39]
	v_mfma_f32_16x16x32_bf16 v[32:35], v[174:177], v[190:193], v[32:35]
	v_mfma_f32_16x16x32_bf16 v[20:23], v[166:169], v[198:201], v[20:23]
	v_mfma_f32_16x16x32_bf16 v[16:19], v[174:177], v[198:201], v[16:19]
	v_mfma_f32_16x16x32_bf16 v[4:7], v[166:169], v[208:211], v[4:7]
	v_mfma_f32_16x16x32_bf16 v[0:3], v[174:177], v[208:211], v[0:3]
	s_barrier
	s_add_i32 s58, s58, 2
	s_add_u32 s56, s56, 0x100
	s_addc_u32 s57, s57, 0
	s_cmp_gt_u32 s58, 61
	s_mov_b64 s[28:29], s[30:31]
	s_cbranch_scc0 .LBB0_778
	s_setprio 0
	s_and_b64 vcc, exec, s[16:17]
	s_cbranch_vccz .LBB0_781
	s_barrier

.LBB0_895:
	s_add_u32 s38, s36, 0xfffc0080
	s_addc_u32 s39, s37, -1
	s_cmp_eq_u32 s61, 12
	s_cselect_b32 s41, s3, s39
	s_cselect_b32 s40, s29, s38
	s_cselect_b32 s39, s27, s60
	s_cselect_b32 s38, s58, s59
	s_add_i32 m0, s46, 0xc000
	s_nop 0
	global_load_lds_dwordx4 v134, s[36:37]
	s_add_i32 m0, s46, 0xe000
	s_nop 0
	global_load_lds_dwordx4 v132, s[36:37]
	ds_read_b128 v[140:143], v153
	ds_read_b128 v[144:147], v153 offset:1024
	ds_read_b128 v[158:161], v153 offset:2048
	ds_read_b128 v[162:165], v153 offset:3072
	ds_read_b128 v[166:169], v154
	ds_read_b128 v[170:173], v154 offset:1024
	ds_read_b128 v[174:177], v154 offset:2048
	ds_read_b128 v[178:181], v154 offset:3072
	ds_read_b128 v[182:185], v155
	ds_read_b128 v[186:189], v155 offset:1024
	ds_read_b128 v[190:193], v155 offset:2048
	ds_read_b128 v[194:197], v155 offset:3072
	ds_read_b128 v[198:201], v155 offset:4096
	ds_read_b128 v[202:205], v155 offset:5120
	ds_read_b128 v[208:211], v155 offset:6144
	ds_read_b128 v[212:215], v155 offset:7168
	s_waitcnt vmcnt(8)
	s_waitcnt lgkmcnt(0)
	s_barrier
	s_waitcnt lgkmcnt(0)
	v_mfma_f32_16x16x32_bf16 v[124:127], v[140:143], v[182:185], v[124:127]
	v_mfma_f32_16x16x32_bf16 v[120:123], v[158:161], v[182:185], v[120:123]
	v_mfma_f32_16x16x32_bf16 v[108:111], v[140:143], v[190:193], v[108:111]
	v_mfma_f32_16x16x32_bf16 v[104:107], v[158:161], v[190:193], v[104:107]
	v_mfma_f32_16x16x32_bf16 v[92:95], v[140:143], v[198:201], v[92:95]
	v_mfma_f32_16x16x32_bf16 v[88:91], v[158:161], v[198:201], v[88:91]
	v_mfma_f32_16x16x32_bf16 v[76:79], v[140:143], v[208:211], v[76:79]
	v_mfma_f32_16x16x32_bf16 v[72:75], v[158:161], v[208:211], v[72:75]
	v_mfma_f32_16x16x32_bf16 v[124:127], v[144:147], v[186:189], v[124:127]
	v_mfma_f32_16x16x32_bf16 v[120:123], v[162:165], v[186:189], v[120:123]
	v_mfma_f32_16x16x32_bf16 v[108:111], v[144:147], v[194:197], v[108:111]
	v_mfma_f32_16x16x32_bf16 v[104:107], v[162:165], v[194:197], v[104:107]
	v_mfma_f32_16x16x32_bf16 v[92:95], v[144:147], v[202:205], v[92:95]
	v_mfma_f32_16x16x32_bf16 v[88:91], v[162:165], v[202:205], v[88:91]
	v_mfma_f32_16x16x32_bf16 v[76:79], v[144:147], v[212:215], v[76:79]
	v_mfma_f32_16x16x32_bf16 v[72:75], v[162:165], v[212:215], v[72:75]
	v_mfma_f32_16x16x32_bf16 v[116:119], v[166:169], v[182:185], v[116:119]
	v_mfma_f32_16x16x32_bf16 v[112:115], v[174:177], v[182:185], v[112:115]
	v_mfma_f32_16x16x32_bf16 v[100:103], v[166:169], v[190:193], v[100:103]
	v_mfma_f32_16x16x32_bf16 v[96:99], v[174:177], v[190:193], v[96:99]
	v_mfma_f32_16x16x32_bf16 v[84:87], v[166:169], v[198:201], v[84:87]
	v_mfma_f32_16x16x32_bf16 v[80:83], v[174:177], v[198:201], v[80:83]
	v_mfma_f32_16x16x32_bf16 v[68:71], v[166:169], v[208:211], v[68:71]
	v_mfma_f32_16x16x32_bf16 v[64:67], v[174:177], v[208:211], v[64:67]
	v_mfma_f32_16x16x32_bf16 v[116:119], v[170:173], v[186:189], v[116:119]
	v_mfma_f32_16x16x32_bf16 v[112:115], v[178:181], v[186:189], v[112:115]
	v_mfma_f32_16x16x32_bf16 v[100:103], v[170:173], v[194:197], v[100:103]
	v_mfma_f32_16x16x32_bf16 v[96:99], v[178:181], v[194:197], v[96:99]
	v_mfma_f32_16x16x32_bf16 v[84:87], v[170:173], v[202:205], v[84:87]
	v_mfma_f32_16x16x32_bf16 v[80:83], v[178:181], v[202:205], v[80:83]
	v_mfma_f32_16x16x32_bf16 v[68:71], v[170:173], v[212:215], v[68:71]
	v_mfma_f32_16x16x32_bf16 v[64:67], v[178:181], v[212:215], v[64:67]
	s_barrier
	s_add_i32 s62, s54, s45
	s_mov_b32 m0, s62
	s_nop 0
	global_load_lds_dwordx4 v128, s[38:39]
	s_add_i32 m0, s62, 0x2000
	s_add_u32 s62, s38, 0x40000
	s_mov_b64 s[98:99], s[38:39]
	s_addc_u32 s63, s39, 0
	s_add_i32 s64, s55, s45
	global_load_lds_dwordx4 v130, s[38:39]
	s_mov_b32 m0, s64
	s_mov_b64 s[100:101], s[40:41]
	global_load_lds_dwordx4 v128, s[62:63]
	s_add_i32 m0, s64, 0x2000
	s_nop 0
	global_load_lds_dwordx4 v130, s[62:63]
	ds_read_b128 v[182:185], v155 offset:16384
	ds_read_b128 v[186:189], v155 offset:17408
	ds_read_b128 v[190:193], v155 offset:18432
	ds_read_b128 v[194:197], v155 offset:19456
	ds_read_b128 v[198:201], v155 offset:20480
	ds_read_b128 v[202:205], v155 offset:21504
	ds_read_b128 v[208:211], v155 offset:22528
	ds_read_b128 v[212:215], v155 offset:23552
	s_waitcnt vmcnt(6)
	s_waitcnt lgkmcnt(0)
	s_barrier
	s_waitcnt lgkmcnt(0)
	v_mfma_f32_16x16x32_bf16 v[60:63], v[140:143], v[182:185], v[60:63]
	v_mfma_f32_16x16x32_bf16 v[56:59], v[158:161], v[182:185], v[56:59]
	v_mfma_f32_16x16x32_bf16 v[44:47], v[140:143], v[190:193], v[44:47]
	v_mfma_f32_16x16x32_bf16 v[40:43], v[158:161], v[190:193], v[40:43]
	v_mfma_f32_16x16x32_bf16 v[28:31], v[140:143], v[198:201], v[28:31]
	v_mfma_f32_16x16x32_bf16 v[24:27], v[158:161], v[198:201], v[24:27]
	v_mfma_f32_16x16x32_bf16 v[12:15], v[140:143], v[208:211], v[12:15]
	v_mfma_f32_16x16x32_bf16 v[8:11], v[158:161], v[208:211], v[8:11]
	v_mfma_f32_16x16x32_bf16 v[60:63], v[144:147], v[186:189], v[60:63]
	v_mfma_f32_16x16x32_bf16 v[56:59], v[162:165], v[186:189], v[56:59]
	v_mfma_f32_16x16x32_bf16 v[44:47], v[144:147], v[194:197], v[44:47]
	v_mfma_f32_16x16x32_bf16 v[40:43], v[162:165], v[194:197], v[40:43]
	v_mfma_f32_16x16x32_bf16 v[28:31], v[144:147], v[202:205], v[28:31]
	v_mfma_f32_16x16x32_bf16 v[24:27], v[162:165], v[202:205], v[24:27]
	v_mfma_f32_16x16x32_bf16 v[12:15], v[144:147], v[212:215], v[12:15]
	v_mfma_f32_16x16x32_bf16 v[8:11], v[162:165], v[212:215], v[8:11]
	v_mfma_f32_16x16x32_bf16 v[52:55], v[166:169], v[182:185], v[52:55]
	v_mfma_f32_16x16x32_bf16 v[48:51], v[174:177], v[182:185], v[48:51]
	v_mfma_f32_16x16x32_bf16 v[36:39], v[166:169], v[190:193], v[36:39]
	v_mfma_f32_16x16x32_bf16 v[32:35], v[174:177], v[190:193], v[32:35]
	v_mfma_f32_16x16x32_bf16 v[20:23], v[166:169], v[198:201], v[20:23]
	v_mfma_f32_16x16x32_bf16 v[16:19], v[174:177], v[198:201], v[16:19]
	v_mfma_f32_16x16x32_bf16 v[4:7], v[166:169], v[208:211], v[4:7]
	v_mfma_f32_16x16x32_bf16 v[0:3], v[174:177], v[208:211], v[0:3]
	s_mov_b32 m0, s46
	s_nop 0
	global_load_lds_dwordx4 v128, s[40:41]
	s_mov_b32 m0, s47
	s_nop 0
	global_load_lds_dwordx4 v130, s[40:41]
	v_mfma_f32_16x16x32_bf16 v[52:55], v[170:173], v[186:189], v[52:55]
	v_mfma_f32_16x16x32_bf16 v[48:51], v[178:181], v[186:189], v[48:51]
	v_mfma_f32_16x16x32_bf16 v[36:39], v[170:173], v[194:197], v[36:39]
	v_mfma_f32_16x16x32_bf16 v[32:35], v[178:181], v[194:197], v[32:35]
	v_mfma_f32_16x16x32_bf16 v[20:23], v[170:173], v[202:205], v[20:23]
	v_mfma_f32_16x16x32_bf16 v[16:19], v[178:181], v[202:205], v[16:19]
	v_mfma_f32_16x16x32_bf16 v[4:7], v[170:173], v[212:215], v[4:7]
	v_mfma_f32_16x16x32_bf16 v[0:3], v[178:181], v[212:215], v[0:3]
	s_barrier
	s_add_i32 s62, 0, 0x18000
	s_add_i32 s63, 0, 0x1c000
	s_add_u32 s40, s40, 0x40000
	s_addc_u32 s41, s41, 0
	s_mov_b32 m0, s48
	s_nop 0
	global_load_lds_dwordx4 v128, s[40:41]
	s_mov_b32 m0, s49
	s_nop 0
	global_load_lds_dwordx4 v130, s[40:41]
	v_add_u32_e32 v157, s62, v151
	ds_read_b128 v[140:143], v157
	ds_read_b128 v[144:147], v157 offset:1024
	ds_read_b128 v[158:161], v157 offset:2048
	ds_read_b128 v[162:165], v157 offset:3072
	v_add_u32_e32 v157, s63, v151
	ds_read_b128 v[166:169], v157
	ds_read_b128 v[170:173], v157 offset:1024
	ds_read_b128 v[174:177], v157 offset:2048
	ds_read_b128 v[178:181], v157 offset:3072
	ds_read_b128 v[182:185], v155 offset:32768
	ds_read_b128 v[186:189], v155 offset:33792
	ds_read_b128 v[190:193], v155 offset:34816
	ds_read_b128 v[194:197], v155 offset:35840
	ds_read_b128 v[198:201], v155 offset:36864
	ds_read_b128 v[202:205], v155 offset:37888
	ds_read_b128 v[208:211], v155 offset:38912
	ds_read_b128 v[212:215], v155 offset:39936
	s_waitcnt vmcnt(8)
	s_waitcnt lgkmcnt(0)
	s_barrier
	s_waitcnt lgkmcnt(0)
	v_mfma_f32_16x16x32_bf16 v[124:127], v[140:143], v[182:185], v[124:127]
	v_mfma_f32_16x16x32_bf16 v[120:123], v[158:161], v[182:185], v[120:123]
	v_mfma_f32_16x16x32_bf16 v[108:111], v[140:143], v[190:193], v[108:111]
	v_mfma_f32_16x16x32_bf16 v[104:107], v[158:161], v[190:193], v[104:107]
	v_mfma_f32_16x16x32_bf16 v[92:95], v[140:143], v[198:201], v[92:95]
	v_mfma_f32_16x16x32_bf16 v[88:91], v[158:161], v[198:201], v[88:91]
	v_mfma_f32_16x16x32_bf16 v[76:79], v[140:143], v[208:211], v[76:79]
	v_mfma_f32_16x16x32_bf16 v[72:75], v[158:161], v[208:211], v[72:75]
	v_mfma_f32_16x16x32_bf16 v[124:127], v[144:147], v[186:189], v[124:127]
	v_mfma_f32_16x16x32_bf16 v[120:123], v[162:165], v[186:189], v[120:123]
	v_mfma_f32_16x16x32_bf16 v[108:111], v[144:147], v[194:197], v[108:111]
	v_mfma_f32_16x16x32_bf16 v[104:107], v[162:165], v[194:197], v[104:107]
	v_mfma_f32_16x16x32_bf16 v[92:95], v[144:147], v[202:205], v[92:95]
	v_mfma_f32_16x16x32_bf16 v[88:91], v[162:165], v[202:205], v[88:91]
	v_mfma_f32_16x16x32_bf16 v[76:79], v[144:147], v[212:215], v[76:79]
	v_mfma_f32_16x16x32_bf16 v[72:75], v[162:165], v[212:215], v[72:75]
	v_mfma_f32_16x16x32_bf16 v[116:119], v[166:169], v[182:185], v[116:119]
	v_mfma_f32_16x16x32_bf16 v[112:115], v[174:177], v[182:185], v[112:115]
	v_mfma_f32_16x16x32_bf16 v[100:103], v[166:169], v[190:193], v[100:103]
	v_mfma_f32_16x16x32_bf16 v[96:99], v[174:177], v[190:193], v[96:99]
	v_mfma_f32_16x16x32_bf16 v[84:87], v[166:169], v[198:201], v[84:87]
	v_mfma_f32_16x16x32_bf16 v[80:83], v[174:177], v[198:201], v[80:83]
	v_mfma_f32_16x16x32_bf16 v[68:71], v[166:169], v[208:211], v[68:71]
	v_mfma_f32_16x16x32_bf16 v[64:67], v[174:177], v[208:211], v[64:67]
	v_mfma_f32_16x16x32_bf16 v[116:119], v[170:173], v[186:189], v[116:119]
	v_mfma_f32_16x16x32_bf16 v[112:115], v[178:181], v[186:189], v[112:115]
	v_mfma_f32_16x16x32_bf16 v[100:103], v[170:173], v[194:197], v[100:103]
	v_mfma_f32_16x16x32_bf16 v[96:99], v[178:181], v[194:197], v[96:99]
	v_mfma_f32_16x16x32_bf16 v[84:87], v[170:173], v[202:205], v[84:87]
	v_mfma_f32_16x16x32_bf16 v[80:83], v[178:181], v[202:205], v[80:83]
	v_mfma_f32_16x16x32_bf16 v[68:71], v[170:173], v[212:215], v[68:71]
	v_mfma_f32_16x16x32_bf16 v[64:67], v[178:181], v[212:215], v[64:67]
	s_barrier
	s_add_i32 s40, s62, s45
	s_mov_b32 m0, s40
	s_nop 0
	global_load_lds_dwordx4 v148, s[38:39]
	s_add_i32 m0, s40, 0x2000
	s_add_u32 s38, s38, 0x40080
	s_addc_u32 s39, s39, 0
	s_add_i32 s40, s63, s45
	global_load_lds_dwordx4 v149, s[98:99]
	s_mov_b32 m0, s40
	s_nop 0
	global_load_lds_dwordx4 v128, s[38:39]
	s_add_i32 m0, s40, 0x2000
	s_nop 0
	global_load_lds_dwordx4 v130, s[38:39]
	ds_read_b128 v[182:185], v155 offset:49152
	ds_read_b128 v[186:189], v155 offset:50176
	ds_read_b128 v[190:193], v155 offset:51200
	ds_read_b128 v[194:197], v155 offset:52224
	ds_read_b128 v[198:201], v155 offset:53248
	ds_read_b128 v[202:205], v155 offset:54272
	ds_read_b128 v[208:211], v155 offset:55296
	ds_read_b128 v[212:215], v155 offset:56320
	s_waitcnt vmcnt(6)
	s_waitcnt lgkmcnt(0)
	s_barrier
	s_waitcnt lgkmcnt(0)
	v_mfma_f32_16x16x32_bf16 v[60:63], v[140:143], v[182:185], v[60:63]
	v_mfma_f32_16x16x32_bf16 v[56:59], v[158:161], v[182:185], v[56:59]
	v_mfma_f32_16x16x32_bf16 v[44:47], v[140:143], v[190:193], v[44:47]
	v_mfma_f32_16x16x32_bf16 v[40:43], v[158:161], v[190:193], v[40:43]
	v_mfma_f32_16x16x32_bf16 v[28:31], v[140:143], v[198:201], v[28:31]
	v_mfma_f32_16x16x32_bf16 v[24:27], v[158:161], v[198:201], v[24:27]
	v_mfma_f32_16x16x32_bf16 v[12:15], v[140:143], v[208:211], v[12:15]
	v_mfma_f32_16x16x32_bf16 v[8:11], v[158:161], v[208:211], v[8:11]
	v_mfma_f32_16x16x32_bf16 v[60:63], v[144:147], v[186:189], v[60:63]
	v_mfma_f32_16x16x32_bf16 v[56:59], v[162:165], v[186:189], v[56:59]
	v_mfma_f32_16x16x32_bf16 v[44:47], v[144:147], v[194:197], v[44:47]
	v_mfma_f32_16x16x32_bf16 v[40:43], v[162:165], v[194:197], v[40:43]
	v_mfma_f32_16x16x32_bf16 v[28:31], v[144:147], v[202:205], v[28:31]
	v_mfma_f32_16x16x32_bf16 v[24:27], v[162:165], v[202:205], v[24:27]
	v_mfma_f32_16x16x32_bf16 v[12:15], v[144:147], v[212:215], v[12:15]
	v_mfma_f32_16x16x32_bf16 v[8:11], v[162:165], v[212:215], v[8:11]
	v_mfma_f32_16x16x32_bf16 v[52:55], v[166:169], v[182:185], v[52:55]
	v_mfma_f32_16x16x32_bf16 v[48:51], v[174:177], v[182:185], v[48:51]
	v_mfma_f32_16x16x32_bf16 v[36:39], v[166:169], v[190:193], v[36:39]
	v_mfma_f32_16x16x32_bf16 v[32:35], v[174:177], v[190:193], v[32:35]
	v_mfma_f32_16x16x32_bf16 v[20:23], v[166:169], v[198:201], v[20:23]
	v_mfma_f32_16x16x32_bf16 v[16:19], v[174:177], v[198:201], v[16:19]
	v_mfma_f32_16x16x32_bf16 v[4:7], v[166:169], v[208:211], v[4:7]
	v_mfma_f32_16x16x32_bf16 v[0:3], v[174:177], v[208:211], v[0:3]
	s_mov_b32 m0, s51
	s_nop 0
	global_load_lds_dwordx4 v148, s[100:101]
	s_mov_b32 m0, s52
	s_nop 0
	global_load_lds_dwordx4 v149, s[100:101]
	v_mfma_f32_16x16x32_bf16 v[52:55], v[170:173], v[186:189], v[52:55]
	v_mfma_f32_16x16x32_bf16 v[48:51], v[178:181], v[186:189], v[48:51]
	v_mfma_f32_16x16x32_bf16 v[36:39], v[170:173], v[194:197], v[36:39]
	v_mfma_f32_16x16x32_bf16 v[32:35], v[178:181], v[194:197], v[32:35]
	v_mfma_f32_16x16x32_bf16 v[20:23], v[170:173], v[202:205], v[20:23]
	v_mfma_f32_16x16x32_bf16 v[16:19], v[178:181], v[202:205], v[16:19]
	v_mfma_f32_16x16x32_bf16 v[4:7], v[170:173], v[212:215], v[4:7]
	v_mfma_f32_16x16x32_bf16 v[0:3], v[178:181], v[212:215], v[0:3]
	s_barrier
	s_add_i32 s61, s61, 2
	s_add_u32 s59, s59, 0x100
	s_addc_u32 s60, s60, 0
	s_add_u32 s36, s36, 0x100
	s_addc_u32 s37, s37, 0
	s_cmp_gt_u32 s61, 13
	s_cbranch_scc0 .LBB0_895
	s_setprio 0
	s_and_b64 vcc, exec, s[24:25]
	s_cbranch_vccz .LBB0_898
	s_barrier

.LBB0_988:
	s_add_u32 s26, s6, 0xfffc0080
	s_addc_u32 s27, s7, -1
	s_cmp_eq_u32 s53, 12
	s_cselect_b32 s29, s19, s27
	s_cselect_b32 s28, s49, s26
	s_cselect_b32 s27, s17, s52
	s_cselect_b32 s26, s50, s51
	s_add_i32 m0, s25, 0xc000
	s_nop 0
	global_load_lds_dwordx4 v138, s[6:7]
	s_add_i32 m0, s25, 0xe000
	s_nop 0
	global_load_lds_dwordx4 v136, s[6:7]
	ds_read_b128 v[144:147], v151
	ds_read_b128 v[156:159], v151 offset:1024
	ds_read_b128 v[160:163], v151 offset:2048
	ds_read_b128 v[164:167], v151 offset:3072
	ds_read_b128 v[168:171], v152
	ds_read_b128 v[172:175], v152 offset:1024
	ds_read_b128 v[176:179], v152 offset:2048
	ds_read_b128 v[180:183], v152 offset:3072
	ds_read_b128 v[184:187], v153
	ds_read_b128 v[188:191], v153 offset:1024
	ds_read_b128 v[192:195], v153 offset:2048
	ds_read_b128 v[196:199], v153 offset:3072
	ds_read_b128 v[200:203], v153 offset:4096
	ds_read_b128 v[208:211], v153 offset:5120
	ds_read_b128 v[212:215], v153 offset:6144
	ds_read_b128 v[216:219], v153 offset:7168
	s_waitcnt vmcnt(8)
	s_waitcnt lgkmcnt(0)
	s_barrier
	s_waitcnt lgkmcnt(0)
	v_mfma_f32_16x16x32_bf16 v[124:127], v[144:147], v[184:187], v[124:127]
	v_mfma_f32_16x16x32_bf16 v[120:123], v[160:163], v[184:187], v[120:123]
	v_mfma_f32_16x16x32_bf16 v[108:111], v[144:147], v[192:195], v[108:111]
	v_mfma_f32_16x16x32_bf16 v[104:107], v[160:163], v[192:195], v[104:107]
	v_mfma_f32_16x16x32_bf16 v[92:95], v[144:147], v[200:203], v[92:95]
	v_mfma_f32_16x16x32_bf16 v[88:91], v[160:163], v[200:203], v[88:91]
	v_mfma_f32_16x16x32_bf16 v[76:79], v[144:147], v[212:215], v[76:79]
	v_mfma_f32_16x16x32_bf16 v[72:75], v[160:163], v[212:215], v[72:75]
	v_mfma_f32_16x16x32_bf16 v[124:127], v[156:159], v[188:191], v[124:127]
	v_mfma_f32_16x16x32_bf16 v[120:123], v[164:167], v[188:191], v[120:123]
	v_mfma_f32_16x16x32_bf16 v[108:111], v[156:159], v[196:199], v[108:111]
	v_mfma_f32_16x16x32_bf16 v[104:107], v[164:167], v[196:199], v[104:107]
	v_mfma_f32_16x16x32_bf16 v[92:95], v[156:159], v[208:211], v[92:95]
	v_mfma_f32_16x16x32_bf16 v[88:91], v[164:167], v[208:211], v[88:91]
	v_mfma_f32_16x16x32_bf16 v[76:79], v[156:159], v[216:219], v[76:79]
	v_mfma_f32_16x16x32_bf16 v[72:75], v[164:167], v[216:219], v[72:75]
	v_mfma_f32_16x16x32_bf16 v[116:119], v[168:171], v[184:187], v[116:119]
	v_mfma_f32_16x16x32_bf16 v[112:115], v[176:179], v[184:187], v[112:115]
	v_mfma_f32_16x16x32_bf16 v[100:103], v[168:171], v[192:195], v[100:103]
	v_mfma_f32_16x16x32_bf16 v[96:99], v[176:179], v[192:195], v[96:99]
	v_mfma_f32_16x16x32_bf16 v[84:87], v[168:171], v[200:203], v[84:87]
	v_mfma_f32_16x16x32_bf16 v[80:83], v[176:179], v[200:203], v[80:83]
	v_mfma_f32_16x16x32_bf16 v[68:71], v[168:171], v[212:215], v[68:71]
	v_mfma_f32_16x16x32_bf16 v[64:67], v[176:179], v[212:215], v[64:67]
	v_mfma_f32_16x16x32_bf16 v[116:119], v[172:175], v[188:191], v[116:119]
	v_mfma_f32_16x16x32_bf16 v[112:115], v[180:183], v[188:191], v[112:115]
	v_mfma_f32_16x16x32_bf16 v[100:103], v[172:175], v[196:199], v[100:103]
	v_mfma_f32_16x16x32_bf16 v[96:99], v[180:183], v[196:199], v[96:99]
	v_mfma_f32_16x16x32_bf16 v[84:87], v[172:175], v[208:211], v[84:87]
	v_mfma_f32_16x16x32_bf16 v[80:83], v[180:183], v[208:211], v[80:83]
	v_mfma_f32_16x16x32_bf16 v[68:71], v[172:175], v[216:219], v[68:71]
	v_mfma_f32_16x16x32_bf16 v[64:67], v[180:183], v[216:219], v[64:67]
	s_barrier
	s_add_i32 s54, s45, s38
	s_mov_b32 m0, s54
	s_nop 0
	global_load_lds_dwordx4 v130, s[26:27]
	s_add_i32 m0, s54, 0x2000
	s_add_u32 s54, s26, 0x40000
	s_mov_b64 s[98:99], s[26:27]
	s_addc_u32 s55, s27, 0
	s_add_i32 s56, s46, s38
	global_load_lds_dwordx4 v134, s[26:27]
	s_mov_b32 m0, s56
	s_mov_b64 s[100:101], s[28:29]
	global_load_lds_dwordx4 v130, s[54:55]
	s_add_i32 m0, s56, 0x2000
	s_nop 0
	global_load_lds_dwordx4 v134, s[54:55]
	ds_read_b128 v[184:187], v153 offset:16384
	ds_read_b128 v[188:191], v153 offset:17408
	ds_read_b128 v[192:195], v153 offset:18432
	ds_read_b128 v[196:199], v153 offset:19456
	ds_read_b128 v[200:203], v153 offset:20480
	ds_read_b128 v[208:211], v153 offset:21504
	ds_read_b128 v[212:215], v153 offset:22528
	ds_read_b128 v[216:219], v153 offset:23552
	s_waitcnt vmcnt(6)
	s_waitcnt lgkmcnt(0)
	s_barrier
	s_waitcnt lgkmcnt(0)
	v_mfma_f32_16x16x32_bf16 v[60:63], v[144:147], v[184:187], v[60:63]
	v_mfma_f32_16x16x32_bf16 v[56:59], v[160:163], v[184:187], v[56:59]
	v_mfma_f32_16x16x32_bf16 v[44:47], v[144:147], v[192:195], v[44:47]
	v_mfma_f32_16x16x32_bf16 v[40:43], v[160:163], v[192:195], v[40:43]
	v_mfma_f32_16x16x32_bf16 v[28:31], v[144:147], v[200:203], v[28:31]
	v_mfma_f32_16x16x32_bf16 v[24:27], v[160:163], v[200:203], v[24:27]
	v_mfma_f32_16x16x32_bf16 v[12:15], v[144:147], v[212:215], v[12:15]
	v_mfma_f32_16x16x32_bf16 v[8:11], v[160:163], v[212:215], v[8:11]
	v_mfma_f32_16x16x32_bf16 v[60:63], v[156:159], v[188:191], v[60:63]
	v_mfma_f32_16x16x32_bf16 v[56:59], v[164:167], v[188:191], v[56:59]
	v_mfma_f32_16x16x32_bf16 v[44:47], v[156:159], v[196:199], v[44:47]
	v_mfma_f32_16x16x32_bf16 v[40:43], v[164:167], v[196:199], v[40:43]
	v_mfma_f32_16x16x32_bf16 v[28:31], v[156:159], v[208:211], v[28:31]
	v_mfma_f32_16x16x32_bf16 v[24:27], v[164:167], v[208:211], v[24:27]
	v_mfma_f32_16x16x32_bf16 v[12:15], v[156:159], v[216:219], v[12:15]
	v_mfma_f32_16x16x32_bf16 v[8:11], v[164:167], v[216:219], v[8:11]
	v_mfma_f32_16x16x32_bf16 v[52:55], v[168:171], v[184:187], v[52:55]
	v_mfma_f32_16x16x32_bf16 v[48:51], v[176:179], v[184:187], v[48:51]
	v_mfma_f32_16x16x32_bf16 v[36:39], v[168:171], v[192:195], v[36:39]
	v_mfma_f32_16x16x32_bf16 v[32:35], v[176:179], v[192:195], v[32:35]
	v_mfma_f32_16x16x32_bf16 v[20:23], v[168:171], v[200:203], v[20:23]
	v_mfma_f32_16x16x32_bf16 v[16:19], v[176:179], v[200:203], v[16:19]
	v_mfma_f32_16x16x32_bf16 v[4:7], v[168:171], v[212:215], v[4:7]
	v_mfma_f32_16x16x32_bf16 v[0:3], v[176:179], v[212:215], v[0:3]
	s_mov_b32 m0, s25
	s_nop 0
	global_load_lds_dwordx4 v128, s[28:29]
	s_mov_b32 m0, s39
	s_nop 0
	global_load_lds_dwordx4 v132, s[28:29]
	v_mfma_f32_16x16x32_bf16 v[52:55], v[172:175], v[188:191], v[52:55]
	v_mfma_f32_16x16x32_bf16 v[48:51], v[180:183], v[188:191], v[48:51]
	v_mfma_f32_16x16x32_bf16 v[36:39], v[172:175], v[196:199], v[36:39]
	v_mfma_f32_16x16x32_bf16 v[32:35], v[180:183], v[196:199], v[32:35]
	v_mfma_f32_16x16x32_bf16 v[20:23], v[172:175], v[208:211], v[20:23]
	v_mfma_f32_16x16x32_bf16 v[16:19], v[180:183], v[208:211], v[16:19]
	v_mfma_f32_16x16x32_bf16 v[4:7], v[172:175], v[216:219], v[4:7]
	v_mfma_f32_16x16x32_bf16 v[0:3], v[180:183], v[216:219], v[0:3]
	s_barrier
	s_add_i32 s54, 0, 0x18000
	s_add_i32 s55, 0, 0x1c000
	s_add_u32 s28, s28, 0x40000
	s_addc_u32 s29, s29, 0
	s_mov_b32 m0, s40
	s_nop 0
	global_load_lds_dwordx4 v128, s[28:29]
	s_mov_b32 m0, s41
	s_nop 0
	global_load_lds_dwordx4 v132, s[28:29]
	v_add_u32_e32 v155, s54, v149
	ds_read_b128 v[144:147], v155
	ds_read_b128 v[156:159], v155 offset:1024
	ds_read_b128 v[160:163], v155 offset:2048
	ds_read_b128 v[164:167], v155 offset:3072
	v_add_u32_e32 v155, s55, v149
	ds_read_b128 v[168:171], v155
	ds_read_b128 v[172:175], v155 offset:1024
	ds_read_b128 v[176:179], v155 offset:2048
	ds_read_b128 v[180:183], v155 offset:3072
	ds_read_b128 v[184:187], v153 offset:32768
	ds_read_b128 v[188:191], v153 offset:33792
	ds_read_b128 v[192:195], v153 offset:34816
	ds_read_b128 v[196:199], v153 offset:35840
	ds_read_b128 v[200:203], v153 offset:36864
	ds_read_b128 v[208:211], v153 offset:37888
	ds_read_b128 v[212:215], v153 offset:38912
	ds_read_b128 v[216:219], v153 offset:39936
	s_waitcnt vmcnt(8)
	s_waitcnt lgkmcnt(0)
	s_barrier
	s_waitcnt lgkmcnt(0)
	v_mfma_f32_16x16x32_bf16 v[124:127], v[144:147], v[184:187], v[124:127]
	v_mfma_f32_16x16x32_bf16 v[120:123], v[160:163], v[184:187], v[120:123]
	v_mfma_f32_16x16x32_bf16 v[108:111], v[144:147], v[192:195], v[108:111]
	v_mfma_f32_16x16x32_bf16 v[104:107], v[160:163], v[192:195], v[104:107]
	v_mfma_f32_16x16x32_bf16 v[92:95], v[144:147], v[200:203], v[92:95]
	v_mfma_f32_16x16x32_bf16 v[88:91], v[160:163], v[200:203], v[88:91]
	v_mfma_f32_16x16x32_bf16 v[76:79], v[144:147], v[212:215], v[76:79]
	v_mfma_f32_16x16x32_bf16 v[72:75], v[160:163], v[212:215], v[72:75]
	v_mfma_f32_16x16x32_bf16 v[124:127], v[156:159], v[188:191], v[124:127]
	v_mfma_f32_16x16x32_bf16 v[120:123], v[164:167], v[188:191], v[120:123]
	v_mfma_f32_16x16x32_bf16 v[108:111], v[156:159], v[196:199], v[108:111]
	v_mfma_f32_16x16x32_bf16 v[104:107], v[164:167], v[196:199], v[104:107]
	v_mfma_f32_16x16x32_bf16 v[92:95], v[156:159], v[208:211], v[92:95]
	v_mfma_f32_16x16x32_bf16 v[88:91], v[164:167], v[208:211], v[88:91]
	v_mfma_f32_16x16x32_bf16 v[76:79], v[156:159], v[216:219], v[76:79]
	v_mfma_f32_16x16x32_bf16 v[72:75], v[164:167], v[216:219], v[72:75]
	v_mfma_f32_16x16x32_bf16 v[116:119], v[168:171], v[184:187], v[116:119]
	v_mfma_f32_16x16x32_bf16 v[112:115], v[176:179], v[184:187], v[112:115]
	v_mfma_f32_16x16x32_bf16 v[100:103], v[168:171], v[192:195], v[100:103]
	v_mfma_f32_16x16x32_bf16 v[96:99], v[176:179], v[192:195], v[96:99]
	v_mfma_f32_16x16x32_bf16 v[84:87], v[168:171], v[200:203], v[84:87]
	v_mfma_f32_16x16x32_bf16 v[80:83], v[176:179], v[200:203], v[80:83]
	v_mfma_f32_16x16x32_bf16 v[68:71], v[168:171], v[212:215], v[68:71]
	v_mfma_f32_16x16x32_bf16 v[64:67], v[176:179], v[212:215], v[64:67]
	v_mfma_f32_16x16x32_bf16 v[116:119], v[172:175], v[188:191], v[116:119]
	v_mfma_f32_16x16x32_bf16 v[112:115], v[180:183], v[188:191], v[112:115]
	v_mfma_f32_16x16x32_bf16 v[100:103], v[172:175], v[196:199], v[100:103]
	v_mfma_f32_16x16x32_bf16 v[96:99], v[180:183], v[196:199], v[96:99]
	v_mfma_f32_16x16x32_bf16 v[84:87], v[172:175], v[208:211], v[84:87]
	v_mfma_f32_16x16x32_bf16 v[80:83], v[180:183], v[208:211], v[80:83]
	v_mfma_f32_16x16x32_bf16 v[68:71], v[172:175], v[216:219], v[68:71]
	v_mfma_f32_16x16x32_bf16 v[64:67], v[180:183], v[216:219], v[64:67]
	s_barrier
	s_add_i32 s28, s54, s38
	s_mov_b32 m0, s28
	s_nop 0
	global_load_lds_dwordx4 v205, s[26:27]
	s_add_i32 m0, s28, 0x2000
	s_add_u32 s26, s26, 0x40080
	s_addc_u32 s27, s27, 0
	s_add_i32 s28, s55, s38
	global_load_lds_dwordx4 v221, s[98:99]
	s_mov_b32 m0, s28
	s_nop 0
	global_load_lds_dwordx4 v130, s[26:27]
	s_add_i32 m0, s28, 0x2000
	s_nop 0
	global_load_lds_dwordx4 v134, s[26:27]
	ds_read_b128 v[184:187], v153 offset:49152
	ds_read_b128 v[188:191], v153 offset:50176
	ds_read_b128 v[192:195], v153 offset:51200
	ds_read_b128 v[196:199], v153 offset:52224
	ds_read_b128 v[200:203], v153 offset:53248
	ds_read_b128 v[208:211], v153 offset:54272
	ds_read_b128 v[212:215], v153 offset:55296
	ds_read_b128 v[216:219], v153 offset:56320
	s_waitcnt vmcnt(6)
	s_waitcnt lgkmcnt(0)
	s_barrier
	s_waitcnt lgkmcnt(0)
	v_mfma_f32_16x16x32_bf16 v[60:63], v[144:147], v[184:187], v[60:63]
	v_mfma_f32_16x16x32_bf16 v[56:59], v[160:163], v[184:187], v[56:59]
	v_mfma_f32_16x16x32_bf16 v[44:47], v[144:147], v[192:195], v[44:47]
	v_mfma_f32_16x16x32_bf16 v[40:43], v[160:163], v[192:195], v[40:43]
	v_mfma_f32_16x16x32_bf16 v[28:31], v[144:147], v[200:203], v[28:31]
	v_mfma_f32_16x16x32_bf16 v[24:27], v[160:163], v[200:203], v[24:27]
	v_mfma_f32_16x16x32_bf16 v[12:15], v[144:147], v[212:215], v[12:15]
	v_mfma_f32_16x16x32_bf16 v[8:11], v[160:163], v[212:215], v[8:11]
	v_mfma_f32_16x16x32_bf16 v[60:63], v[156:159], v[188:191], v[60:63]
	v_mfma_f32_16x16x32_bf16 v[56:59], v[164:167], v[188:191], v[56:59]
	v_mfma_f32_16x16x32_bf16 v[44:47], v[156:159], v[196:199], v[44:47]
	v_mfma_f32_16x16x32_bf16 v[40:43], v[164:167], v[196:199], v[40:43]
	v_mfma_f32_16x16x32_bf16 v[28:31], v[156:159], v[208:211], v[28:31]
	v_mfma_f32_16x16x32_bf16 v[24:27], v[164:167], v[208:211], v[24:27]
	v_mfma_f32_16x16x32_bf16 v[12:15], v[156:159], v[216:219], v[12:15]
	v_mfma_f32_16x16x32_bf16 v[8:11], v[164:167], v[216:219], v[8:11]
	v_mfma_f32_16x16x32_bf16 v[52:55], v[168:171], v[184:187], v[52:55]
	v_mfma_f32_16x16x32_bf16 v[48:51], v[176:179], v[184:187], v[48:51]
	v_mfma_f32_16x16x32_bf16 v[36:39], v[168:171], v[192:195], v[36:39]
	v_mfma_f32_16x16x32_bf16 v[32:35], v[176:179], v[192:195], v[32:35]
	v_mfma_f32_16x16x32_bf16 v[20:23], v[168:171], v[200:203], v[20:23]
	v_mfma_f32_16x16x32_bf16 v[16:19], v[176:179], v[200:203], v[16:19]
	v_mfma_f32_16x16x32_bf16 v[4:7], v[168:171], v[212:215], v[4:7]
	v_mfma_f32_16x16x32_bf16 v[0:3], v[176:179], v[212:215], v[0:3]
	s_mov_b32 m0, s43
	s_nop 0
	global_load_lds_dwordx4 v204, s[100:101]
	s_mov_b32 m0, s44
	s_nop 0
	global_load_lds_dwordx4 v220, s[100:101]
	v_mfma_f32_16x16x32_bf16 v[52:55], v[172:175], v[188:191], v[52:55]
	v_mfma_f32_16x16x32_bf16 v[48:51], v[180:183], v[188:191], v[48:51]
	v_mfma_f32_16x16x32_bf16 v[36:39], v[172:175], v[196:199], v[36:39]
	v_mfma_f32_16x16x32_bf16 v[32:35], v[180:183], v[196:199], v[32:35]
	v_mfma_f32_16x16x32_bf16 v[20:23], v[172:175], v[208:211], v[20:23]
	v_mfma_f32_16x16x32_bf16 v[16:19], v[180:183], v[208:211], v[16:19]
	v_mfma_f32_16x16x32_bf16 v[4:7], v[172:175], v[216:219], v[4:7]
	v_mfma_f32_16x16x32_bf16 v[0:3], v[180:183], v[216:219], v[0:3]
	s_barrier
	s_add_i32 s53, s53, 2
	s_add_u32 s51, s51, 0x100
	s_addc_u32 s52, s52, 0
	s_add_u32 s6, s6, 0x100
	s_addc_u32 s7, s7, 0
	s_cmp_gt_u32 s53, 13
	s_cbranch_scc0 .LBB0_988
	s_setprio 0
	s_and_b64 vcc, exec, s[14:15]
	s_cbranch_vccz .LBB0_991
	s_barrier

.LBB0_1193:
	s_add_u32 s26, s24, 0xfffe0080
	s_addc_u32 s27, s25, -1
	s_cmp_eq_u32 s50, 4
	s_cselect_b32 s29, s17, s27
	s_cselect_b32 s28, s46, s26
	s_cselect_b32 s27, s15, s49
	s_cselect_b32 s26, s47, s48
	s_add_i32 m0, s23, 0xc000
	s_nop 0
	global_load_lds_dwordx4 v138, s[24:25]
	s_add_i32 m0, s23, 0xe000
	s_nop 0
	global_load_lds_dwordx4 v136, s[24:25]
	ds_read_b128 v[144:147], v151
	ds_read_b128 v[154:157], v151 offset:1024
	ds_read_b128 v[158:161], v151 offset:2048
	ds_read_b128 v[162:165], v151 offset:3072
	ds_read_b128 v[166:169], v152
	ds_read_b128 v[170:173], v152 offset:1024
	ds_read_b128 v[174:177], v152 offset:2048
	ds_read_b128 v[178:181], v152 offset:3072
	ds_read_b128 v[182:185], v153
	ds_read_b128 v[186:189], v153 offset:1024
	ds_read_b128 v[190:193], v153 offset:2048
	ds_read_b128 v[194:197], v153 offset:3072
	ds_read_b128 v[198:201], v153 offset:4096
	ds_read_b128 v[202:205], v153 offset:5120
	ds_read_b128 v[208:211], v153 offset:6144
	ds_read_b128 v[212:215], v153 offset:7168
	s_waitcnt vmcnt(8)
	s_waitcnt lgkmcnt(0)
	s_barrier
	s_waitcnt lgkmcnt(0)
	v_mfma_f32_16x16x32_bf16 v[124:127], v[144:147], v[182:185], v[124:127]
	v_mfma_f32_16x16x32_bf16 v[120:123], v[158:161], v[182:185], v[120:123]
	v_mfma_f32_16x16x32_bf16 v[108:111], v[144:147], v[190:193], v[108:111]
	v_mfma_f32_16x16x32_bf16 v[104:107], v[158:161], v[190:193], v[104:107]
	v_mfma_f32_16x16x32_bf16 v[92:95], v[144:147], v[198:201], v[92:95]
	v_mfma_f32_16x16x32_bf16 v[88:91], v[158:161], v[198:201], v[88:91]
	v_mfma_f32_16x16x32_bf16 v[76:79], v[144:147], v[208:211], v[76:79]
	v_mfma_f32_16x16x32_bf16 v[72:75], v[158:161], v[208:211], v[72:75]
	v_mfma_f32_16x16x32_bf16 v[124:127], v[154:157], v[186:189], v[124:127]
	v_mfma_f32_16x16x32_bf16 v[120:123], v[162:165], v[186:189], v[120:123]
	v_mfma_f32_16x16x32_bf16 v[108:111], v[154:157], v[194:197], v[108:111]
	v_mfma_f32_16x16x32_bf16 v[104:107], v[162:165], v[194:197], v[104:107]
	v_mfma_f32_16x16x32_bf16 v[92:95], v[154:157], v[202:205], v[92:95]
	v_mfma_f32_16x16x32_bf16 v[88:91], v[162:165], v[202:205], v[88:91]
	v_mfma_f32_16x16x32_bf16 v[76:79], v[154:157], v[212:215], v[76:79]
	v_mfma_f32_16x16x32_bf16 v[72:75], v[162:165], v[212:215], v[72:75]
	v_mfma_f32_16x16x32_bf16 v[116:119], v[166:169], v[182:185], v[116:119]
	v_mfma_f32_16x16x32_bf16 v[112:115], v[174:177], v[182:185], v[112:115]
	v_mfma_f32_16x16x32_bf16 v[100:103], v[166:169], v[190:193], v[100:103]
	v_mfma_f32_16x16x32_bf16 v[96:99], v[174:177], v[190:193], v[96:99]
	v_mfma_f32_16x16x32_bf16 v[84:87], v[166:169], v[198:201], v[84:87]
	v_mfma_f32_16x16x32_bf16 v[80:83], v[174:177], v[198:201], v[80:83]
	v_mfma_f32_16x16x32_bf16 v[68:71], v[166:169], v[208:211], v[68:71]
	v_mfma_f32_16x16x32_bf16 v[64:67], v[174:177], v[208:211], v[64:67]
	v_mfma_f32_16x16x32_bf16 v[116:119], v[170:173], v[186:189], v[116:119]
	v_mfma_f32_16x16x32_bf16 v[112:115], v[178:181], v[186:189], v[112:115]
	v_mfma_f32_16x16x32_bf16 v[100:103], v[170:173], v[194:197], v[100:103]
	v_mfma_f32_16x16x32_bf16 v[96:99], v[178:181], v[194:197], v[96:99]
	v_mfma_f32_16x16x32_bf16 v[84:87], v[170:173], v[202:205], v[84:87]
	v_mfma_f32_16x16x32_bf16 v[80:83], v[178:181], v[202:205], v[80:83]
	v_mfma_f32_16x16x32_bf16 v[68:71], v[170:173], v[212:215], v[68:71]
	v_mfma_f32_16x16x32_bf16 v[64:67], v[178:181], v[212:215], v[64:67]
	s_barrier
	s_add_i32 s51, s43, s36
	s_mov_b32 m0, s51
	s_nop 0
	global_load_lds_dwordx4 v130, s[26:27]
	s_add_i32 m0, s51, 0x2000
	s_add_u32 s52, s26, 0x20000
	s_mov_b64 s[98:99], s[26:27]
	s_addc_u32 s53, s27, 0
	s_add_i32 s51, s44, s36
	global_load_lds_dwordx4 v134, s[26:27]
	s_mov_b32 m0, s51
	s_mov_b64 s[100:101], s[28:29]
	global_load_lds_dwordx4 v130, s[52:53]
	s_add_i32 m0, s51, 0x2000
	s_nop 0
	global_load_lds_dwordx4 v134, s[52:53]
	ds_read_b128 v[182:185], v153 offset:16384
	ds_read_b128 v[186:189], v153 offset:17408
	ds_read_b128 v[190:193], v153 offset:18432
	ds_read_b128 v[194:197], v153 offset:19456
	ds_read_b128 v[198:201], v153 offset:20480
	ds_read_b128 v[202:205], v153 offset:21504
	ds_read_b128 v[208:211], v153 offset:22528
	ds_read_b128 v[212:215], v153 offset:23552
	s_waitcnt vmcnt(6)
	s_waitcnt lgkmcnt(0)
	s_barrier
	s_waitcnt lgkmcnt(0)
	v_mfma_f32_16x16x32_bf16 v[60:63], v[144:147], v[182:185], v[60:63]
	v_mfma_f32_16x16x32_bf16 v[56:59], v[158:161], v[182:185], v[56:59]
	v_mfma_f32_16x16x32_bf16 v[44:47], v[144:147], v[190:193], v[44:47]
	v_mfma_f32_16x16x32_bf16 v[40:43], v[158:161], v[190:193], v[40:43]
	v_mfma_f32_16x16x32_bf16 v[28:31], v[144:147], v[198:201], v[28:31]
	v_mfma_f32_16x16x32_bf16 v[24:27], v[158:161], v[198:201], v[24:27]
	v_mfma_f32_16x16x32_bf16 v[12:15], v[144:147], v[208:211], v[12:15]
	v_mfma_f32_16x16x32_bf16 v[8:11], v[158:161], v[208:211], v[8:11]
	v_mfma_f32_16x16x32_bf16 v[60:63], v[154:157], v[186:189], v[60:63]
	v_mfma_f32_16x16x32_bf16 v[56:59], v[162:165], v[186:189], v[56:59]
	v_mfma_f32_16x16x32_bf16 v[44:47], v[154:157], v[194:197], v[44:47]
	v_mfma_f32_16x16x32_bf16 v[40:43], v[162:165], v[194:197], v[40:43]
	v_mfma_f32_16x16x32_bf16 v[28:31], v[154:157], v[202:205], v[28:31]
	v_mfma_f32_16x16x32_bf16 v[24:27], v[162:165], v[202:205], v[24:27]
	v_mfma_f32_16x16x32_bf16 v[12:15], v[154:157], v[212:215], v[12:15]
	v_mfma_f32_16x16x32_bf16 v[8:11], v[162:165], v[212:215], v[8:11]
	v_mfma_f32_16x16x32_bf16 v[52:55], v[166:169], v[182:185], v[52:55]
	v_mfma_f32_16x16x32_bf16 v[48:51], v[174:177], v[182:185], v[48:51]
	v_mfma_f32_16x16x32_bf16 v[36:39], v[166:169], v[190:193], v[36:39]
	v_mfma_f32_16x16x32_bf16 v[32:35], v[174:177], v[190:193], v[32:35]
	v_mfma_f32_16x16x32_bf16 v[20:23], v[166:169], v[198:201], v[20:23]
	v_mfma_f32_16x16x32_bf16 v[16:19], v[174:177], v[198:201], v[16:19]
	v_mfma_f32_16x16x32_bf16 v[4:7], v[166:169], v[208:211], v[4:7]
	v_mfma_f32_16x16x32_bf16 v[0:3], v[174:177], v[208:211], v[0:3]
	s_mov_b32 m0, s23
	s_nop 0
	global_load_lds_dwordx4 v128, s[28:29]
	s_mov_b32 m0, s37
	s_nop 0
	global_load_lds_dwordx4 v132, s[28:29]
	v_mfma_f32_16x16x32_bf16 v[52:55], v[170:173], v[186:189], v[52:55]
	v_mfma_f32_16x16x32_bf16 v[48:51], v[178:181], v[186:189], v[48:51]
	v_mfma_f32_16x16x32_bf16 v[36:39], v[170:173], v[194:197], v[36:39]
	v_mfma_f32_16x16x32_bf16 v[32:35], v[178:181], v[194:197], v[32:35]
	v_mfma_f32_16x16x32_bf16 v[20:23], v[170:173], v[202:205], v[20:23]
	v_mfma_f32_16x16x32_bf16 v[16:19], v[178:181], v[202:205], v[16:19]
	v_mfma_f32_16x16x32_bf16 v[4:7], v[170:173], v[212:215], v[4:7]
	v_mfma_f32_16x16x32_bf16 v[0:3], v[178:181], v[212:215], v[0:3]
	s_barrier
	s_add_i32 s51, 0, 0x18000
	s_add_i32 s52, 0, 0x1c000
	s_add_u32 s28, s28, 0x20000
	s_addc_u32 s29, s29, 0
	s_mov_b32 m0, s38
	s_nop 0
	global_load_lds_dwordx4 v128, s[28:29]
	s_mov_b32 m0, s39
	s_nop 0
	global_load_lds_dwordx4 v132, s[28:29]
	v_add_u32_e32 v162, s51, v149
	v_add_u32_e32 v178, s52, v149
	ds_read_b128 v[144:147], v162
	ds_read_b128 v[154:157], v162 offset:1024
	ds_read_b128 v[158:161], v162 offset:2048
	ds_read_b128 v[162:165], v162 offset:3072
	ds_read_b128 v[166:169], v178
	ds_read_b128 v[170:173], v178 offset:1024
	ds_read_b128 v[174:177], v178 offset:2048
	ds_read_b128 v[178:181], v178 offset:3072
	ds_read_b128 v[182:185], v153 offset:32768
	ds_read_b128 v[186:189], v153 offset:33792
	ds_read_b128 v[190:193], v153 offset:34816
	ds_read_b128 v[194:197], v153 offset:35840
	ds_read_b128 v[198:201], v153 offset:36864
	ds_read_b128 v[202:205], v153 offset:37888
	ds_read_b128 v[208:211], v153 offset:38912
	ds_read_b128 v[212:215], v153 offset:39936
	s_waitcnt vmcnt(8)
	s_waitcnt lgkmcnt(0)
	s_barrier
	s_waitcnt lgkmcnt(0)
	v_mfma_f32_16x16x32_bf16 v[124:127], v[144:147], v[182:185], v[124:127]
	v_mfma_f32_16x16x32_bf16 v[120:123], v[158:161], v[182:185], v[120:123]
	v_mfma_f32_16x16x32_bf16 v[108:111], v[144:147], v[190:193], v[108:111]
	v_mfma_f32_16x16x32_bf16 v[104:107], v[158:161], v[190:193], v[104:107]
	v_mfma_f32_16x16x32_bf16 v[92:95], v[144:147], v[198:201], v[92:95]
	v_mfma_f32_16x16x32_bf16 v[88:91], v[158:161], v[198:201], v[88:91]
	v_mfma_f32_16x16x32_bf16 v[76:79], v[144:147], v[208:211], v[76:79]
	v_mfma_f32_16x16x32_bf16 v[72:75], v[158:161], v[208:211], v[72:75]
	v_mfma_f32_16x16x32_bf16 v[124:127], v[154:157], v[186:189], v[124:127]
	v_mfma_f32_16x16x32_bf16 v[120:123], v[162:165], v[186:189], v[120:123]
	v_mfma_f32_16x16x32_bf16 v[108:111], v[154:157], v[194:197], v[108:111]
	v_mfma_f32_16x16x32_bf16 v[104:107], v[162:165], v[194:197], v[104:107]
	v_mfma_f32_16x16x32_bf16 v[92:95], v[154:157], v[202:205], v[92:95]
	v_mfma_f32_16x16x32_bf16 v[88:91], v[162:165], v[202:205], v[88:91]
	v_mfma_f32_16x16x32_bf16 v[76:79], v[154:157], v[212:215], v[76:79]
	v_mfma_f32_16x16x32_bf16 v[72:75], v[162:165], v[212:215], v[72:75]
	v_mfma_f32_16x16x32_bf16 v[116:119], v[166:169], v[182:185], v[116:119]
	v_mfma_f32_16x16x32_bf16 v[112:115], v[174:177], v[182:185], v[112:115]
	v_mfma_f32_16x16x32_bf16 v[100:103], v[166:169], v[190:193], v[100:103]
	v_mfma_f32_16x16x32_bf16 v[96:99], v[174:177], v[190:193], v[96:99]
	v_mfma_f32_16x16x32_bf16 v[84:87], v[166:169], v[198:201], v[84:87]
	v_mfma_f32_16x16x32_bf16 v[80:83], v[174:177], v[198:201], v[80:83]
	v_mfma_f32_16x16x32_bf16 v[68:71], v[166:169], v[208:211], v[68:71]
	v_mfma_f32_16x16x32_bf16 v[64:67], v[174:177], v[208:211], v[64:67]
	v_mfma_f32_16x16x32_bf16 v[116:119], v[170:173], v[186:189], v[116:119]
	v_mfma_f32_16x16x32_bf16 v[112:115], v[178:181], v[186:189], v[112:115]
	v_mfma_f32_16x16x32_bf16 v[100:103], v[170:173], v[194:197], v[100:103]
	v_mfma_f32_16x16x32_bf16 v[96:99], v[178:181], v[194:197], v[96:99]
	v_mfma_f32_16x16x32_bf16 v[84:87], v[170:173], v[202:205], v[84:87]
	v_mfma_f32_16x16x32_bf16 v[80:83], v[178:181], v[202:205], v[80:83]
	v_mfma_f32_16x16x32_bf16 v[68:71], v[170:173], v[212:215], v[68:71]
	v_mfma_f32_16x16x32_bf16 v[64:67], v[178:181], v[212:215], v[64:67]
	s_barrier
	s_add_i32 s28, s51, s36
	s_mov_b32 m0, s28
	s_nop 0
	global_load_lds_dwordx4 v217, s[26:27]
	s_add_i32 m0, s28, 0x2000
	s_add_u32 s26, s26, 0x20080
	s_addc_u32 s27, s27, 0
	s_add_i32 s28, s52, s36
	global_load_lds_dwordx4 v219, s[98:99]
	s_mov_b32 m0, s28
	s_nop 0
	global_load_lds_dwordx4 v130, s[26:27]
	s_add_i32 m0, s28, 0x2000
	s_nop 0
	global_load_lds_dwordx4 v134, s[26:27]
	ds_read_b128 v[182:185], v153 offset:49152
	ds_read_b128 v[186:189], v153 offset:50176
	ds_read_b128 v[190:193], v153 offset:51200
	ds_read_b128 v[194:197], v153 offset:52224
	ds_read_b128 v[198:201], v153 offset:53248
	ds_read_b128 v[202:205], v153 offset:54272
	ds_read_b128 v[208:211], v153 offset:55296
	ds_read_b128 v[212:215], v153 offset:56320
	s_waitcnt vmcnt(6)
	s_waitcnt lgkmcnt(0)
	s_barrier
	s_waitcnt lgkmcnt(0)
	v_mfma_f32_16x16x32_bf16 v[60:63], v[144:147], v[182:185], v[60:63]
	v_mfma_f32_16x16x32_bf16 v[56:59], v[158:161], v[182:185], v[56:59]
	v_mfma_f32_16x16x32_bf16 v[44:47], v[144:147], v[190:193], v[44:47]
	v_mfma_f32_16x16x32_bf16 v[40:43], v[158:161], v[190:193], v[40:43]
	v_mfma_f32_16x16x32_bf16 v[28:31], v[144:147], v[198:201], v[28:31]
	v_mfma_f32_16x16x32_bf16 v[24:27], v[158:161], v[198:201], v[24:27]
	v_mfma_f32_16x16x32_bf16 v[12:15], v[144:147], v[208:211], v[12:15]
	v_mfma_f32_16x16x32_bf16 v[8:11], v[158:161], v[208:211], v[8:11]
	v_mfma_f32_16x16x32_bf16 v[60:63], v[154:157], v[186:189], v[60:63]
	v_mfma_f32_16x16x32_bf16 v[56:59], v[162:165], v[186:189], v[56:59]
	v_mfma_f32_16x16x32_bf16 v[44:47], v[154:157], v[194:197], v[44:47]
	v_mfma_f32_16x16x32_bf16 v[40:43], v[162:165], v[194:197], v[40:43]
	v_mfma_f32_16x16x32_bf16 v[28:31], v[154:157], v[202:205], v[28:31]
	v_mfma_f32_16x16x32_bf16 v[24:27], v[162:165], v[202:205], v[24:27]
	v_mfma_f32_16x16x32_bf16 v[12:15], v[154:157], v[212:215], v[12:15]
	v_mfma_f32_16x16x32_bf16 v[8:11], v[162:165], v[212:215], v[8:11]
	v_mfma_f32_16x16x32_bf16 v[52:55], v[166:169], v[182:185], v[52:55]
	v_mfma_f32_16x16x32_bf16 v[48:51], v[174:177], v[182:185], v[48:51]
	v_mfma_f32_16x16x32_bf16 v[36:39], v[166:169], v[190:193], v[36:39]
	v_mfma_f32_16x16x32_bf16 v[32:35], v[174:177], v[190:193], v[32:35]
	v_mfma_f32_16x16x32_bf16 v[20:23], v[166:169], v[198:201], v[20:23]
	v_mfma_f32_16x16x32_bf16 v[16:19], v[174:177], v[198:201], v[16:19]
	v_mfma_f32_16x16x32_bf16 v[4:7], v[166:169], v[208:211], v[4:7]
	v_mfma_f32_16x16x32_bf16 v[0:3], v[174:177], v[208:211], v[0:3]
	s_mov_b32 m0, s41
	s_nop 0
	global_load_lds_dwordx4 v216, s[100:101]
	s_mov_b32 m0, s42
	s_nop 0
	global_load_lds_dwordx4 v218, s[100:101]
	v_mfma_f32_16x16x32_bf16 v[52:55], v[170:173], v[186:189], v[52:55]
	v_mfma_f32_16x16x32_bf16 v[48:51], v[178:181], v[186:189], v[48:51]
	v_mfma_f32_16x16x32_bf16 v[36:39], v[170:173], v[194:197], v[36:39]
	v_mfma_f32_16x16x32_bf16 v[32:35], v[178:181], v[194:197], v[32:35]
	v_mfma_f32_16x16x32_bf16 v[20:23], v[170:173], v[202:205], v[20:23]
	v_mfma_f32_16x16x32_bf16 v[16:19], v[178:181], v[202:205], v[16:19]
	v_mfma_f32_16x16x32_bf16 v[4:7], v[170:173], v[212:215], v[4:7]
	v_mfma_f32_16x16x32_bf16 v[0:3], v[178:181], v[212:215], v[0:3]
	s_barrier
	s_add_i32 s50, s50, 2
	s_add_u32 s48, s48, 0x100
	s_addc_u32 s49, s49, 0
	s_add_u32 s24, s24, 0x100
	s_addc_u32 s25, s25, 0
	s_cmp_gt_u32 s50, 5
	s_cbranch_scc0 .LBB0_1193
	s_setprio 0
	s_and_b64 vcc, exec, s[12:13]
	s_cbranch_vccz .LBB0_1196
	s_barrier

.LBB0_1365:
	s_add_u32 s26, s24, 0xfffc0080
	s_addc_u32 s27, s25, -1
	s_cmp_eq_u32 s53, 12
	s_cselect_b32 s29, s19, s27
	s_cselect_b32 s28, s49, s26
	s_cselect_b32 s27, s17, s52
	s_cselect_b32 s26, s50, s51
	s_add_i32 m0, s39, 0xc000
	s_nop 0
	global_load_lds_dwordx4 v138, s[24:25]
	s_add_i32 m0, s39, 0xe000
	s_nop 0
	global_load_lds_dwordx4 v136, s[24:25]
	ds_read_b128 v[144:147], v151
	ds_read_b128 v[156:159], v151 offset:1024
	ds_read_b128 v[160:163], v151 offset:2048
	ds_read_b128 v[164:167], v151 offset:3072
	ds_read_b128 v[168:171], v152
	ds_read_b128 v[172:175], v152 offset:1024
	ds_read_b128 v[176:179], v152 offset:2048
	ds_read_b128 v[180:183], v152 offset:3072
	ds_read_b128 v[184:187], v153
	ds_read_b128 v[188:191], v153 offset:1024
	ds_read_b128 v[192:195], v153 offset:2048
	ds_read_b128 v[196:199], v153 offset:3072
	ds_read_b128 v[200:203], v153 offset:4096
	ds_read_b128 v[208:211], v153 offset:5120
	ds_read_b128 v[212:215], v153 offset:6144
	ds_read_b128 v[216:219], v153 offset:7168
	s_waitcnt vmcnt(8)
	s_waitcnt lgkmcnt(0)
	s_barrier
	s_waitcnt lgkmcnt(0)
	v_mfma_f32_16x16x32_bf16 v[124:127], v[144:147], v[184:187], v[124:127]
	v_mfma_f32_16x16x32_bf16 v[120:123], v[160:163], v[184:187], v[120:123]
	v_mfma_f32_16x16x32_bf16 v[108:111], v[144:147], v[192:195], v[108:111]
	v_mfma_f32_16x16x32_bf16 v[104:107], v[160:163], v[192:195], v[104:107]
	v_mfma_f32_16x16x32_bf16 v[92:95], v[144:147], v[200:203], v[92:95]
	v_mfma_f32_16x16x32_bf16 v[88:91], v[160:163], v[200:203], v[88:91]
	v_mfma_f32_16x16x32_bf16 v[76:79], v[144:147], v[212:215], v[76:79]
	v_mfma_f32_16x16x32_bf16 v[72:75], v[160:163], v[212:215], v[72:75]
	v_mfma_f32_16x16x32_bf16 v[124:127], v[156:159], v[188:191], v[124:127]
	v_mfma_f32_16x16x32_bf16 v[120:123], v[164:167], v[188:191], v[120:123]
	v_mfma_f32_16x16x32_bf16 v[108:111], v[156:159], v[196:199], v[108:111]
	v_mfma_f32_16x16x32_bf16 v[104:107], v[164:167], v[196:199], v[104:107]
	v_mfma_f32_16x16x32_bf16 v[92:95], v[156:159], v[208:211], v[92:95]
	v_mfma_f32_16x16x32_bf16 v[88:91], v[164:167], v[208:211], v[88:91]
	v_mfma_f32_16x16x32_bf16 v[76:79], v[156:159], v[216:219], v[76:79]
	v_mfma_f32_16x16x32_bf16 v[72:75], v[164:167], v[216:219], v[72:75]
	v_mfma_f32_16x16x32_bf16 v[116:119], v[168:171], v[184:187], v[116:119]
	v_mfma_f32_16x16x32_bf16 v[112:115], v[176:179], v[184:187], v[112:115]
	v_mfma_f32_16x16x32_bf16 v[100:103], v[168:171], v[192:195], v[100:103]
	v_mfma_f32_16x16x32_bf16 v[96:99], v[176:179], v[192:195], v[96:99]
	v_mfma_f32_16x16x32_bf16 v[84:87], v[168:171], v[200:203], v[84:87]
	v_mfma_f32_16x16x32_bf16 v[80:83], v[176:179], v[200:203], v[80:83]
	v_mfma_f32_16x16x32_bf16 v[68:71], v[168:171], v[212:215], v[68:71]
	v_mfma_f32_16x16x32_bf16 v[64:67], v[176:179], v[212:215], v[64:67]
	v_mfma_f32_16x16x32_bf16 v[116:119], v[172:175], v[188:191], v[116:119]
	v_mfma_f32_16x16x32_bf16 v[112:115], v[180:183], v[188:191], v[112:115]
	v_mfma_f32_16x16x32_bf16 v[100:103], v[172:175], v[196:199], v[100:103]
	v_mfma_f32_16x16x32_bf16 v[96:99], v[180:183], v[196:199], v[96:99]
	v_mfma_f32_16x16x32_bf16 v[84:87], v[172:175], v[208:211], v[84:87]
	v_mfma_f32_16x16x32_bf16 v[80:83], v[180:183], v[208:211], v[80:83]
	v_mfma_f32_16x16x32_bf16 v[68:71], v[172:175], v[216:219], v[68:71]
	v_mfma_f32_16x16x32_bf16 v[64:67], v[180:183], v[216:219], v[64:67]
	s_barrier
	s_add_i32 s54, s46, s38
	s_mov_b32 m0, s54
	s_nop 0
	global_load_lds_dwordx4 v130, s[26:27]
	s_add_i32 m0, s54, 0x2000
	s_add_u32 s54, s26, 0x40000
	s_mov_b64 s[98:99], s[26:27]
	s_addc_u32 s55, s27, 0
	s_add_i32 s56, s47, s38
	global_load_lds_dwordx4 v134, s[26:27]
	s_mov_b32 m0, s56
	s_mov_b64 s[100:101], s[28:29]
	global_load_lds_dwordx4 v130, s[54:55]
	s_add_i32 m0, s56, 0x2000
	s_nop 0
	global_load_lds_dwordx4 v134, s[54:55]
	ds_read_b128 v[184:187], v153 offset:16384
	ds_read_b128 v[188:191], v153 offset:17408
	ds_read_b128 v[192:195], v153 offset:18432
	ds_read_b128 v[196:199], v153 offset:19456
	ds_read_b128 v[200:203], v153 offset:20480
	ds_read_b128 v[208:211], v153 offset:21504
	ds_read_b128 v[212:215], v153 offset:22528
	ds_read_b128 v[216:219], v153 offset:23552
	s_waitcnt vmcnt(6)
	s_waitcnt lgkmcnt(0)
	s_barrier
	s_waitcnt lgkmcnt(0)
	v_mfma_f32_16x16x32_bf16 v[60:63], v[144:147], v[184:187], v[60:63]
	v_mfma_f32_16x16x32_bf16 v[56:59], v[160:163], v[184:187], v[56:59]
	v_mfma_f32_16x16x32_bf16 v[44:47], v[144:147], v[192:195], v[44:47]
	v_mfma_f32_16x16x32_bf16 v[40:43], v[160:163], v[192:195], v[40:43]
	v_mfma_f32_16x16x32_bf16 v[28:31], v[144:147], v[200:203], v[28:31]
	v_mfma_f32_16x16x32_bf16 v[24:27], v[160:163], v[200:203], v[24:27]
	v_mfma_f32_16x16x32_bf16 v[12:15], v[144:147], v[212:215], v[12:15]
	v_mfma_f32_16x16x32_bf16 v[8:11], v[160:163], v[212:215], v[8:11]
	v_mfma_f32_16x16x32_bf16 v[60:63], v[156:159], v[188:191], v[60:63]
	v_mfma_f32_16x16x32_bf16 v[56:59], v[164:167], v[188:191], v[56:59]
	v_mfma_f32_16x16x32_bf16 v[44:47], v[156:159], v[196:199], v[44:47]
	v_mfma_f32_16x16x32_bf16 v[40:43], v[164:167], v[196:199], v[40:43]
	v_mfma_f32_16x16x32_bf16 v[28:31], v[156:159], v[208:211], v[28:31]
	v_mfma_f32_16x16x32_bf16 v[24:27], v[164:167], v[208:211], v[24:27]
	v_mfma_f32_16x16x32_bf16 v[12:15], v[156:159], v[216:219], v[12:15]
	v_mfma_f32_16x16x32_bf16 v[8:11], v[164:167], v[216:219], v[8:11]
	v_mfma_f32_16x16x32_bf16 v[52:55], v[168:171], v[184:187], v[52:55]
	v_mfma_f32_16x16x32_bf16 v[48:51], v[176:179], v[184:187], v[48:51]
	v_mfma_f32_16x16x32_bf16 v[36:39], v[168:171], v[192:195], v[36:39]
	v_mfma_f32_16x16x32_bf16 v[32:35], v[176:179], v[192:195], v[32:35]
	v_mfma_f32_16x16x32_bf16 v[20:23], v[168:171], v[200:203], v[20:23]
	v_mfma_f32_16x16x32_bf16 v[16:19], v[176:179], v[200:203], v[16:19]
	v_mfma_f32_16x16x32_bf16 v[4:7], v[168:171], v[212:215], v[4:7]
	v_mfma_f32_16x16x32_bf16 v[0:3], v[176:179], v[212:215], v[0:3]
	s_mov_b32 m0, s39
	s_nop 0
	global_load_lds_dwordx4 v128, s[28:29]
	s_mov_b32 m0, s40
	s_nop 0
	global_load_lds_dwordx4 v132, s[28:29]
	v_mfma_f32_16x16x32_bf16 v[52:55], v[172:175], v[188:191], v[52:55]
	v_mfma_f32_16x16x32_bf16 v[48:51], v[180:183], v[188:191], v[48:51]
	v_mfma_f32_16x16x32_bf16 v[36:39], v[172:175], v[196:199], v[36:39]
	v_mfma_f32_16x16x32_bf16 v[32:35], v[180:183], v[196:199], v[32:35]
	v_mfma_f32_16x16x32_bf16 v[20:23], v[172:175], v[208:211], v[20:23]
	v_mfma_f32_16x16x32_bf16 v[16:19], v[180:183], v[208:211], v[16:19]
	v_mfma_f32_16x16x32_bf16 v[4:7], v[172:175], v[216:219], v[4:7]
	v_mfma_f32_16x16x32_bf16 v[0:3], v[180:183], v[216:219], v[0:3]
	s_barrier
	s_add_i32 s54, 0, 0x18000
	s_add_i32 s55, 0, 0x1c000
	s_add_u32 s28, s28, 0x40000
	s_addc_u32 s29, s29, 0
	s_mov_b32 m0, s41
	s_nop 0
	global_load_lds_dwordx4 v128, s[28:29]
	s_mov_b32 m0, s42
	s_nop 0
	global_load_lds_dwordx4 v132, s[28:29]
	v_add_u32_e32 v155, s54, v149
	ds_read_b128 v[144:147], v155
	ds_read_b128 v[156:159], v155 offset:1024
	ds_read_b128 v[160:163], v155 offset:2048
	ds_read_b128 v[164:167], v155 offset:3072
	v_add_u32_e32 v155, s55, v149
	ds_read_b128 v[168:171], v155
	ds_read_b128 v[172:175], v155 offset:1024
	ds_read_b128 v[176:179], v155 offset:2048
	ds_read_b128 v[180:183], v155 offset:3072
	ds_read_b128 v[184:187], v153 offset:32768
	ds_read_b128 v[188:191], v153 offset:33792
	ds_read_b128 v[192:195], v153 offset:34816
	ds_read_b128 v[196:199], v153 offset:35840
	ds_read_b128 v[200:203], v153 offset:36864
	ds_read_b128 v[208:211], v153 offset:37888
	ds_read_b128 v[212:215], v153 offset:38912
	ds_read_b128 v[216:219], v153 offset:39936
	s_waitcnt vmcnt(8)
	s_waitcnt lgkmcnt(0)
	s_barrier
	s_waitcnt lgkmcnt(0)
	v_mfma_f32_16x16x32_bf16 v[124:127], v[144:147], v[184:187], v[124:127]
	v_mfma_f32_16x16x32_bf16 v[120:123], v[160:163], v[184:187], v[120:123]
	v_mfma_f32_16x16x32_bf16 v[108:111], v[144:147], v[192:195], v[108:111]
	v_mfma_f32_16x16x32_bf16 v[104:107], v[160:163], v[192:195], v[104:107]
	v_mfma_f32_16x16x32_bf16 v[92:95], v[144:147], v[200:203], v[92:95]
	v_mfma_f32_16x16x32_bf16 v[88:91], v[160:163], v[200:203], v[88:91]
	v_mfma_f32_16x16x32_bf16 v[76:79], v[144:147], v[212:215], v[76:79]
	v_mfma_f32_16x16x32_bf16 v[72:75], v[160:163], v[212:215], v[72:75]
	v_mfma_f32_16x16x32_bf16 v[124:127], v[156:159], v[188:191], v[124:127]
	v_mfma_f32_16x16x32_bf16 v[120:123], v[164:167], v[188:191], v[120:123]
	v_mfma_f32_16x16x32_bf16 v[108:111], v[156:159], v[196:199], v[108:111]
	v_mfma_f32_16x16x32_bf16 v[104:107], v[164:167], v[196:199], v[104:107]
	v_mfma_f32_16x16x32_bf16 v[92:95], v[156:159], v[208:211], v[92:95]
	v_mfma_f32_16x16x32_bf16 v[88:91], v[164:167], v[208:211], v[88:91]
	v_mfma_f32_16x16x32_bf16 v[76:79], v[156:159], v[216:219], v[76:79]
	v_mfma_f32_16x16x32_bf16 v[72:75], v[164:167], v[216:219], v[72:75]
	v_mfma_f32_16x16x32_bf16 v[116:119], v[168:171], v[184:187], v[116:119]
	v_mfma_f32_16x16x32_bf16 v[112:115], v[176:179], v[184:187], v[112:115]
	v_mfma_f32_16x16x32_bf16 v[100:103], v[168:171], v[192:195], v[100:103]
	v_mfma_f32_16x16x32_bf16 v[96:99], v[176:179], v[192:195], v[96:99]
	v_mfma_f32_16x16x32_bf16 v[84:87], v[168:171], v[200:203], v[84:87]
	v_mfma_f32_16x16x32_bf16 v[80:83], v[176:179], v[200:203], v[80:83]
	v_mfma_f32_16x16x32_bf16 v[68:71], v[168:171], v[212:215], v[68:71]
	v_mfma_f32_16x16x32_bf16 v[64:67], v[176:179], v[212:215], v[64:67]
	v_mfma_f32_16x16x32_bf16 v[116:119], v[172:175], v[188:191], v[116:119]
	v_mfma_f32_16x16x32_bf16 v[112:115], v[180:183], v[188:191], v[112:115]
	v_mfma_f32_16x16x32_bf16 v[100:103], v[172:175], v[196:199], v[100:103]
	v_mfma_f32_16x16x32_bf16 v[96:99], v[180:183], v[196:199], v[96:99]
	v_mfma_f32_16x16x32_bf16 v[84:87], v[172:175], v[208:211], v[84:87]
	v_mfma_f32_16x16x32_bf16 v[80:83], v[180:183], v[208:211], v[80:83]
	v_mfma_f32_16x16x32_bf16 v[68:71], v[172:175], v[216:219], v[68:71]
	v_mfma_f32_16x16x32_bf16 v[64:67], v[180:183], v[216:219], v[64:67]
	s_barrier
	s_add_i32 s28, s54, s38
	s_mov_b32 m0, s28
	s_nop 0
	global_load_lds_dwordx4 v205, s[26:27]
	s_add_i32 m0, s28, 0x2000
	s_add_u32 s26, s26, 0x40080
	s_addc_u32 s27, s27, 0
	s_add_i32 s28, s55, s38
	global_load_lds_dwordx4 v221, s[98:99]
	s_mov_b32 m0, s28
	s_nop 0
	global_load_lds_dwordx4 v130, s[26:27]
	s_add_i32 m0, s28, 0x2000
	s_nop 0
	global_load_lds_dwordx4 v134, s[26:27]
	ds_read_b128 v[184:187], v153 offset:49152
	ds_read_b128 v[188:191], v153 offset:50176
	ds_read_b128 v[192:195], v153 offset:51200
	ds_read_b128 v[196:199], v153 offset:52224
	ds_read_b128 v[200:203], v153 offset:53248
	ds_read_b128 v[208:211], v153 offset:54272
	ds_read_b128 v[212:215], v153 offset:55296
	ds_read_b128 v[216:219], v153 offset:56320
	s_waitcnt vmcnt(6)
	s_waitcnt lgkmcnt(0)
	s_barrier
	s_waitcnt lgkmcnt(0)
	v_mfma_f32_16x16x32_bf16 v[60:63], v[144:147], v[184:187], v[60:63]
	v_mfma_f32_16x16x32_bf16 v[56:59], v[160:163], v[184:187], v[56:59]
	v_mfma_f32_16x16x32_bf16 v[44:47], v[144:147], v[192:195], v[44:47]
	v_mfma_f32_16x16x32_bf16 v[40:43], v[160:163], v[192:195], v[40:43]
	v_mfma_f32_16x16x32_bf16 v[28:31], v[144:147], v[200:203], v[28:31]
	v_mfma_f32_16x16x32_bf16 v[24:27], v[160:163], v[200:203], v[24:27]
	v_mfma_f32_16x16x32_bf16 v[12:15], v[144:147], v[212:215], v[12:15]
	v_mfma_f32_16x16x32_bf16 v[8:11], v[160:163], v[212:215], v[8:11]
	v_mfma_f32_16x16x32_bf16 v[60:63], v[156:159], v[188:191], v[60:63]
	v_mfma_f32_16x16x32_bf16 v[56:59], v[164:167], v[188:191], v[56:59]
	v_mfma_f32_16x16x32_bf16 v[44:47], v[156:159], v[196:199], v[44:47]
	v_mfma_f32_16x16x32_bf16 v[40:43], v[164:167], v[196:199], v[40:43]
	v_mfma_f32_16x16x32_bf16 v[28:31], v[156:159], v[208:211], v[28:31]
	v_mfma_f32_16x16x32_bf16 v[24:27], v[164:167], v[208:211], v[24:27]
	v_mfma_f32_16x16x32_bf16 v[12:15], v[156:159], v[216:219], v[12:15]
	v_mfma_f32_16x16x32_bf16 v[8:11], v[164:167], v[216:219], v[8:11]
	v_mfma_f32_16x16x32_bf16 v[52:55], v[168:171], v[184:187], v[52:55]
	v_mfma_f32_16x16x32_bf16 v[48:51], v[176:179], v[184:187], v[48:51]
	v_mfma_f32_16x16x32_bf16 v[36:39], v[168:171], v[192:195], v[36:39]
	v_mfma_f32_16x16x32_bf16 v[32:35], v[176:179], v[192:195], v[32:35]
	v_mfma_f32_16x16x32_bf16 v[20:23], v[168:171], v[200:203], v[20:23]
	v_mfma_f32_16x16x32_bf16 v[16:19], v[176:179], v[200:203], v[16:19]
	v_mfma_f32_16x16x32_bf16 v[4:7], v[168:171], v[212:215], v[4:7]
	v_mfma_f32_16x16x32_bf16 v[0:3], v[176:179], v[212:215], v[0:3]
	s_mov_b32 m0, s44
	s_nop 0
	global_load_lds_dwordx4 v204, s[100:101]
	s_mov_b32 m0, s45
	s_nop 0
	global_load_lds_dwordx4 v220, s[100:101]
	v_mfma_f32_16x16x32_bf16 v[52:55], v[172:175], v[188:191], v[52:55]
	v_mfma_f32_16x16x32_bf16 v[48:51], v[180:183], v[188:191], v[48:51]
	v_mfma_f32_16x16x32_bf16 v[36:39], v[172:175], v[196:199], v[36:39]
	v_mfma_f32_16x16x32_bf16 v[32:35], v[180:183], v[196:199], v[32:35]
	v_mfma_f32_16x16x32_bf16 v[20:23], v[172:175], v[208:211], v[20:23]
	v_mfma_f32_16x16x32_bf16 v[16:19], v[180:183], v[208:211], v[16:19]
	v_mfma_f32_16x16x32_bf16 v[4:7], v[172:175], v[216:219], v[4:7]
	v_mfma_f32_16x16x32_bf16 v[0:3], v[180:183], v[216:219], v[0:3]
	s_barrier
	s_add_i32 s53, s53, 2
	s_add_u32 s51, s51, 0x100
	s_addc_u32 s52, s52, 0
	s_add_u32 s24, s24, 0x100
	s_addc_u32 s25, s25, 0
	s_cmp_gt_u32 s53, 13
	s_cbranch_scc0 .LBB0_1365
	s_setprio 0
	s_and_b64 vcc, exec, s[14:15]
	s_cbranch_vccz .LBB0_1368
	s_barrier

.LBB0_1561:
	s_add_u32 s38, s36, 0xfffc0080
	s_addc_u32 s39, s37, -1
	s_cmp_eq_u32 s61, 12
	s_cselect_b32 s41, s3, s39
	s_cselect_b32 s40, s29, s38
	s_cselect_b32 s39, s27, s60
	s_cselect_b32 s38, s58, s59
	s_add_i32 m0, s46, 0xc000
	s_nop 0
	global_load_lds_dwordx4 v134, s[36:37]
	s_add_i32 m0, s46, 0xe000
	s_nop 0
	global_load_lds_dwordx4 v132, s[36:37]
	ds_read_b128 v[140:143], v151
	ds_read_b128 v[144:147], v151 offset:1024
	ds_read_b128 v[156:159], v151 offset:2048
	ds_read_b128 v[160:163], v151 offset:3072
	ds_read_b128 v[164:167], v152
	ds_read_b128 v[168:171], v152 offset:1024
	ds_read_b128 v[172:175], v152 offset:2048
	ds_read_b128 v[176:179], v152 offset:3072
	ds_read_b128 v[180:183], v153
	ds_read_b128 v[184:187], v153 offset:1024
	ds_read_b128 v[188:191], v153 offset:2048
	ds_read_b128 v[192:195], v153 offset:3072
	ds_read_b128 v[196:199], v153 offset:4096
	ds_read_b128 v[200:203], v153 offset:5120
	ds_read_b128 v[208:211], v153 offset:6144
	ds_read_b128 v[212:215], v153 offset:7168
	s_waitcnt vmcnt(8)
	s_waitcnt lgkmcnt(0)
	s_barrier
	s_waitcnt lgkmcnt(0)
	v_mfma_f32_16x16x32_bf16 v[124:127], v[140:143], v[180:183], v[124:127]
	v_mfma_f32_16x16x32_bf16 v[120:123], v[156:159], v[180:183], v[120:123]
	v_mfma_f32_16x16x32_bf16 v[108:111], v[140:143], v[188:191], v[108:111]
	v_mfma_f32_16x16x32_bf16 v[104:107], v[156:159], v[188:191], v[104:107]
	v_mfma_f32_16x16x32_bf16 v[92:95], v[140:143], v[196:199], v[92:95]
	v_mfma_f32_16x16x32_bf16 v[88:91], v[156:159], v[196:199], v[88:91]
	v_mfma_f32_16x16x32_bf16 v[76:79], v[140:143], v[208:211], v[76:79]
	v_mfma_f32_16x16x32_bf16 v[72:75], v[156:159], v[208:211], v[72:75]
	v_mfma_f32_16x16x32_bf16 v[124:127], v[144:147], v[184:187], v[124:127]
	v_mfma_f32_16x16x32_bf16 v[120:123], v[160:163], v[184:187], v[120:123]
	v_mfma_f32_16x16x32_bf16 v[108:111], v[144:147], v[192:195], v[108:111]
	v_mfma_f32_16x16x32_bf16 v[104:107], v[160:163], v[192:195], v[104:107]
	v_mfma_f32_16x16x32_bf16 v[92:95], v[144:147], v[200:203], v[92:95]
	v_mfma_f32_16x16x32_bf16 v[88:91], v[160:163], v[200:203], v[88:91]
	v_mfma_f32_16x16x32_bf16 v[76:79], v[144:147], v[212:215], v[76:79]
	v_mfma_f32_16x16x32_bf16 v[72:75], v[160:163], v[212:215], v[72:75]
	v_mfma_f32_16x16x32_bf16 v[116:119], v[164:167], v[180:183], v[116:119]
	v_mfma_f32_16x16x32_bf16 v[112:115], v[172:175], v[180:183], v[112:115]
	v_mfma_f32_16x16x32_bf16 v[100:103], v[164:167], v[188:191], v[100:103]
	v_mfma_f32_16x16x32_bf16 v[96:99], v[172:175], v[188:191], v[96:99]
	v_mfma_f32_16x16x32_bf16 v[84:87], v[164:167], v[196:199], v[84:87]
	v_mfma_f32_16x16x32_bf16 v[80:83], v[172:175], v[196:199], v[80:83]
	v_mfma_f32_16x16x32_bf16 v[68:71], v[164:167], v[208:211], v[68:71]
	v_mfma_f32_16x16x32_bf16 v[64:67], v[172:175], v[208:211], v[64:67]
	v_mfma_f32_16x16x32_bf16 v[116:119], v[168:171], v[184:187], v[116:119]
	v_mfma_f32_16x16x32_bf16 v[112:115], v[176:179], v[184:187], v[112:115]
	v_mfma_f32_16x16x32_bf16 v[100:103], v[168:171], v[192:195], v[100:103]
	v_mfma_f32_16x16x32_bf16 v[96:99], v[176:179], v[192:195], v[96:99]
	v_mfma_f32_16x16x32_bf16 v[84:87], v[168:171], v[200:203], v[84:87]
	v_mfma_f32_16x16x32_bf16 v[80:83], v[176:179], v[200:203], v[80:83]
	v_mfma_f32_16x16x32_bf16 v[68:71], v[168:171], v[212:215], v[68:71]
	v_mfma_f32_16x16x32_bf16 v[64:67], v[176:179], v[212:215], v[64:67]
	s_barrier
	s_add_i32 s62, s54, s45
	s_mov_b32 m0, s62
	s_nop 0
	global_load_lds_dwordx4 v128, s[38:39]
	s_add_i32 m0, s62, 0x2000
	s_add_u32 s62, s38, 0x40000
	s_mov_b64 s[98:99], s[38:39]
	s_addc_u32 s63, s39, 0
	s_add_i32 s64, s55, s45
	global_load_lds_dwordx4 v130, s[38:39]
	s_mov_b32 m0, s64
	s_mov_b64 s[100:101], s[40:41]
	global_load_lds_dwordx4 v128, s[62:63]
	s_add_i32 m0, s64, 0x2000
	s_nop 0
	global_load_lds_dwordx4 v130, s[62:63]
	ds_read_b128 v[180:183], v153 offset:16384
	ds_read_b128 v[184:187], v153 offset:17408
	ds_read_b128 v[188:191], v153 offset:18432
	ds_read_b128 v[192:195], v153 offset:19456
	ds_read_b128 v[196:199], v153 offset:20480
	ds_read_b128 v[200:203], v153 offset:21504
	ds_read_b128 v[208:211], v153 offset:22528
	ds_read_b128 v[212:215], v153 offset:23552
	s_waitcnt vmcnt(6)
	s_waitcnt lgkmcnt(0)
	s_barrier
	s_waitcnt lgkmcnt(0)
	v_mfma_f32_16x16x32_bf16 v[60:63], v[140:143], v[180:183], v[60:63]
	v_mfma_f32_16x16x32_bf16 v[56:59], v[156:159], v[180:183], v[56:59]
	v_mfma_f32_16x16x32_bf16 v[44:47], v[140:143], v[188:191], v[44:47]
	v_mfma_f32_16x16x32_bf16 v[40:43], v[156:159], v[188:191], v[40:43]
	v_mfma_f32_16x16x32_bf16 v[28:31], v[140:143], v[196:199], v[28:31]
	v_mfma_f32_16x16x32_bf16 v[24:27], v[156:159], v[196:199], v[24:27]
	v_mfma_f32_16x16x32_bf16 v[12:15], v[140:143], v[208:211], v[12:15]
	v_mfma_f32_16x16x32_bf16 v[8:11], v[156:159], v[208:211], v[8:11]
	v_mfma_f32_16x16x32_bf16 v[60:63], v[144:147], v[184:187], v[60:63]
	v_mfma_f32_16x16x32_bf16 v[56:59], v[160:163], v[184:187], v[56:59]
	v_mfma_f32_16x16x32_bf16 v[44:47], v[144:147], v[192:195], v[44:47]
	v_mfma_f32_16x16x32_bf16 v[40:43], v[160:163], v[192:195], v[40:43]
	v_mfma_f32_16x16x32_bf16 v[28:31], v[144:147], v[200:203], v[28:31]
	v_mfma_f32_16x16x32_bf16 v[24:27], v[160:163], v[200:203], v[24:27]
	v_mfma_f32_16x16x32_bf16 v[12:15], v[144:147], v[212:215], v[12:15]
	v_mfma_f32_16x16x32_bf16 v[8:11], v[160:163], v[212:215], v[8:11]
	v_mfma_f32_16x16x32_bf16 v[52:55], v[164:167], v[180:183], v[52:55]
	v_mfma_f32_16x16x32_bf16 v[48:51], v[172:175], v[180:183], v[48:51]
	v_mfma_f32_16x16x32_bf16 v[36:39], v[164:167], v[188:191], v[36:39]
	v_mfma_f32_16x16x32_bf16 v[32:35], v[172:175], v[188:191], v[32:35]
	v_mfma_f32_16x16x32_bf16 v[20:23], v[164:167], v[196:199], v[20:23]
	v_mfma_f32_16x16x32_bf16 v[16:19], v[172:175], v[196:199], v[16:19]
	v_mfma_f32_16x16x32_bf16 v[4:7], v[164:167], v[208:211], v[4:7]
	v_mfma_f32_16x16x32_bf16 v[0:3], v[172:175], v[208:211], v[0:3]
	s_mov_b32 m0, s46
	s_nop 0
	global_load_lds_dwordx4 v128, s[40:41]
	s_mov_b32 m0, s47
	s_nop 0
	global_load_lds_dwordx4 v130, s[40:41]
	v_mfma_f32_16x16x32_bf16 v[52:55], v[168:171], v[184:187], v[52:55]
	v_mfma_f32_16x16x32_bf16 v[48:51], v[176:179], v[184:187], v[48:51]
	v_mfma_f32_16x16x32_bf16 v[36:39], v[168:171], v[192:195], v[36:39]
	v_mfma_f32_16x16x32_bf16 v[32:35], v[176:179], v[192:195], v[32:35]
	v_mfma_f32_16x16x32_bf16 v[20:23], v[168:171], v[200:203], v[20:23]
	v_mfma_f32_16x16x32_bf16 v[16:19], v[176:179], v[200:203], v[16:19]
	v_mfma_f32_16x16x32_bf16 v[4:7], v[168:171], v[212:215], v[4:7]
	v_mfma_f32_16x16x32_bf16 v[0:3], v[176:179], v[212:215], v[0:3]
	s_barrier
	s_add_i32 s62, 0, 0x18000
	s_add_i32 s63, 0, 0x1c000
	s_add_u32 s40, s40, 0x40000
	s_addc_u32 s41, s41, 0
	s_mov_b32 m0, s48
	s_nop 0
	global_load_lds_dwordx4 v128, s[40:41]
	s_mov_b32 m0, s49
	s_nop 0
	global_load_lds_dwordx4 v130, s[40:41]
	v_add_u32_e32 v155, s62, v149
	ds_read_b128 v[140:143], v155
	ds_read_b128 v[144:147], v155 offset:1024
	ds_read_b128 v[156:159], v155 offset:2048
	ds_read_b128 v[160:163], v155 offset:3072
	v_add_u32_e32 v155, s63, v149
	ds_read_b128 v[164:167], v155
	ds_read_b128 v[168:171], v155 offset:1024
	ds_read_b128 v[172:175], v155 offset:2048
	ds_read_b128 v[176:179], v155 offset:3072
	ds_read_b128 v[180:183], v153 offset:32768
	ds_read_b128 v[184:187], v153 offset:33792
	ds_read_b128 v[188:191], v153 offset:34816
	ds_read_b128 v[192:195], v153 offset:35840
	ds_read_b128 v[196:199], v153 offset:36864
	ds_read_b128 v[200:203], v153 offset:37888
	ds_read_b128 v[208:211], v153 offset:38912
	ds_read_b128 v[212:215], v153 offset:39936
	s_waitcnt vmcnt(8)
	s_waitcnt lgkmcnt(0)
	s_barrier
	s_waitcnt lgkmcnt(0)
	v_mfma_f32_16x16x32_bf16 v[124:127], v[140:143], v[180:183], v[124:127]
	v_mfma_f32_16x16x32_bf16 v[120:123], v[156:159], v[180:183], v[120:123]
	v_mfma_f32_16x16x32_bf16 v[108:111], v[140:143], v[188:191], v[108:111]
	v_mfma_f32_16x16x32_bf16 v[104:107], v[156:159], v[188:191], v[104:107]
	v_mfma_f32_16x16x32_bf16 v[92:95], v[140:143], v[196:199], v[92:95]
	v_mfma_f32_16x16x32_bf16 v[88:91], v[156:159], v[196:199], v[88:91]
	v_mfma_f32_16x16x32_bf16 v[76:79], v[140:143], v[208:211], v[76:79]
	v_mfma_f32_16x16x32_bf16 v[72:75], v[156:159], v[208:211], v[72:75]
	v_mfma_f32_16x16x32_bf16 v[124:127], v[144:147], v[184:187], v[124:127]
	v_mfma_f32_16x16x32_bf16 v[120:123], v[160:163], v[184:187], v[120:123]
	v_mfma_f32_16x16x32_bf16 v[108:111], v[144:147], v[192:195], v[108:111]
	v_mfma_f32_16x16x32_bf16 v[104:107], v[160:163], v[192:195], v[104:107]
	v_mfma_f32_16x16x32_bf16 v[92:95], v[144:147], v[200:203], v[92:95]
	v_mfma_f32_16x16x32_bf16 v[88:91], v[160:163], v[200:203], v[88:91]
	v_mfma_f32_16x16x32_bf16 v[76:79], v[144:147], v[212:215], v[76:79]
	v_mfma_f32_16x16x32_bf16 v[72:75], v[160:163], v[212:215], v[72:75]
	v_mfma_f32_16x16x32_bf16 v[116:119], v[164:167], v[180:183], v[116:119]
	v_mfma_f32_16x16x32_bf16 v[112:115], v[172:175], v[180:183], v[112:115]
	v_mfma_f32_16x16x32_bf16 v[100:103], v[164:167], v[188:191], v[100:103]
	v_mfma_f32_16x16x32_bf16 v[96:99], v[172:175], v[188:191], v[96:99]
	v_mfma_f32_16x16x32_bf16 v[84:87], v[164:167], v[196:199], v[84:87]
	v_mfma_f32_16x16x32_bf16 v[80:83], v[172:175], v[196:199], v[80:83]
	v_mfma_f32_16x16x32_bf16 v[68:71], v[164:167], v[208:211], v[68:71]
	v_mfma_f32_16x16x32_bf16 v[64:67], v[172:175], v[208:211], v[64:67]
	v_mfma_f32_16x16x32_bf16 v[116:119], v[168:171], v[184:187], v[116:119]
	v_mfma_f32_16x16x32_bf16 v[112:115], v[176:179], v[184:187], v[112:115]
	v_mfma_f32_16x16x32_bf16 v[100:103], v[168:171], v[192:195], v[100:103]
	v_mfma_f32_16x16x32_bf16 v[96:99], v[176:179], v[192:195], v[96:99]
	v_mfma_f32_16x16x32_bf16 v[84:87], v[168:171], v[200:203], v[84:87]
	v_mfma_f32_16x16x32_bf16 v[80:83], v[176:179], v[200:203], v[80:83]
	v_mfma_f32_16x16x32_bf16 v[68:71], v[168:171], v[212:215], v[68:71]
	v_mfma_f32_16x16x32_bf16 v[64:67], v[176:179], v[212:215], v[64:67]
	s_barrier
	s_add_i32 s40, s62, s45
	s_mov_b32 m0, s40
	s_nop 0
	global_load_lds_dwordx4 v204, s[38:39]
	s_add_i32 m0, s40, 0x2000
	s_add_u32 s38, s38, 0x40080
	s_addc_u32 s39, s39, 0
	s_add_i32 s40, s63, s45
	global_load_lds_dwordx4 v205, s[98:99]
	s_mov_b32 m0, s40
	s_nop 0
	global_load_lds_dwordx4 v128, s[38:39]
	s_add_i32 m0, s40, 0x2000
	s_nop 0
	global_load_lds_dwordx4 v130, s[38:39]
	ds_read_b128 v[180:183], v153 offset:49152
	ds_read_b128 v[184:187], v153 offset:50176
	ds_read_b128 v[188:191], v153 offset:51200
	ds_read_b128 v[192:195], v153 offset:52224
	ds_read_b128 v[196:199], v153 offset:53248
	ds_read_b128 v[200:203], v153 offset:54272
	ds_read_b128 v[208:211], v153 offset:55296
	ds_read_b128 v[212:215], v153 offset:56320
	s_waitcnt vmcnt(6)
	s_waitcnt lgkmcnt(0)
	s_barrier
	s_waitcnt lgkmcnt(0)
	v_mfma_f32_16x16x32_bf16 v[60:63], v[140:143], v[180:183], v[60:63]
	v_mfma_f32_16x16x32_bf16 v[56:59], v[156:159], v[180:183], v[56:59]
	v_mfma_f32_16x16x32_bf16 v[44:47], v[140:143], v[188:191], v[44:47]
	v_mfma_f32_16x16x32_bf16 v[40:43], v[156:159], v[188:191], v[40:43]
	v_mfma_f32_16x16x32_bf16 v[28:31], v[140:143], v[196:199], v[28:31]
	v_mfma_f32_16x16x32_bf16 v[24:27], v[156:159], v[196:199], v[24:27]
	v_mfma_f32_16x16x32_bf16 v[12:15], v[140:143], v[208:211], v[12:15]
	v_mfma_f32_16x16x32_bf16 v[8:11], v[156:159], v[208:211], v[8:11]
	v_mfma_f32_16x16x32_bf16 v[60:63], v[144:147], v[184:187], v[60:63]
	v_mfma_f32_16x16x32_bf16 v[56:59], v[160:163], v[184:187], v[56:59]
	v_mfma_f32_16x16x32_bf16 v[44:47], v[144:147], v[192:195], v[44:47]
	v_mfma_f32_16x16x32_bf16 v[40:43], v[160:163], v[192:195], v[40:43]
	v_mfma_f32_16x16x32_bf16 v[28:31], v[144:147], v[200:203], v[28:31]
	v_mfma_f32_16x16x32_bf16 v[24:27], v[160:163], v[200:203], v[24:27]
	v_mfma_f32_16x16x32_bf16 v[12:15], v[144:147], v[212:215], v[12:15]
	v_mfma_f32_16x16x32_bf16 v[8:11], v[160:163], v[212:215], v[8:11]
	v_mfma_f32_16x16x32_bf16 v[52:55], v[164:167], v[180:183], v[52:55]
	v_mfma_f32_16x16x32_bf16 v[48:51], v[172:175], v[180:183], v[48:51]
	v_mfma_f32_16x16x32_bf16 v[36:39], v[164:167], v[188:191], v[36:39]
	v_mfma_f32_16x16x32_bf16 v[32:35], v[172:175], v[188:191], v[32:35]
	v_mfma_f32_16x16x32_bf16 v[20:23], v[164:167], v[196:199], v[20:23]
	v_mfma_f32_16x16x32_bf16 v[16:19], v[172:175], v[196:199], v[16:19]
	v_mfma_f32_16x16x32_bf16 v[4:7], v[164:167], v[208:211], v[4:7]
	v_mfma_f32_16x16x32_bf16 v[0:3], v[172:175], v[208:211], v[0:3]
	s_mov_b32 m0, s51
	s_nop 0
	global_load_lds_dwordx4 v204, s[100:101]
	s_mov_b32 m0, s52
	s_nop 0
	global_load_lds_dwordx4 v205, s[100:101]
	v_mfma_f32_16x16x32_bf16 v[52:55], v[168:171], v[184:187], v[52:55]
	v_mfma_f32_16x16x32_bf16 v[48:51], v[176:179], v[184:187], v[48:51]
	v_mfma_f32_16x16x32_bf16 v[36:39], v[168:171], v[192:195], v[36:39]
	v_mfma_f32_16x16x32_bf16 v[32:35], v[176:179], v[192:195], v[32:35]
	v_mfma_f32_16x16x32_bf16 v[20:23], v[168:171], v[200:203], v[20:23]
	v_mfma_f32_16x16x32_bf16 v[16:19], v[176:179], v[200:203], v[16:19]
	v_mfma_f32_16x16x32_bf16 v[4:7], v[168:171], v[212:215], v[4:7]
	v_mfma_f32_16x16x32_bf16 v[0:3], v[176:179], v[212:215], v[0:3]
	s_barrier
	s_add_i32 s61, s61, 2
	s_add_u32 s59, s59, 0x100
	s_addc_u32 s60, s60, 0
	s_add_u32 s36, s36, 0x100
	s_addc_u32 s37, s37, 0
	s_cmp_gt_u32 s61, 13
	s_cbranch_scc0 .LBB0_1561
	s_setprio 0
	s_and_b64 vcc, exec, s[24:25]
	s_cbranch_vccz .LBB0_1564
	s_barrier

.LBB0_1646:
	s_add_u32 s26, s24, 0xfffc0080
	s_addc_u32 s27, s25, -1
	s_cmp_eq_u32 s54, 12
	s_cselect_b32 s29, s19, s27
	s_cselect_b32 s28, s50, s26
	s_cselect_b32 s27, s17, s53
	s_cselect_b32 s26, s51, s52
	s_add_i32 m0, s38, 0xc000
	s_nop 0
	global_load_lds_dwordx4 v138, s[24:25]
	s_add_i32 m0, s38, 0xe000
	s_nop 0
	global_load_lds_dwordx4 v136, s[24:25]
	ds_read_b128 v[144:147], v151
	ds_read_b128 v[156:159], v151 offset:1024
	ds_read_b128 v[160:163], v151 offset:2048
	ds_read_b128 v[164:167], v151 offset:3072
	ds_read_b128 v[168:171], v152
	ds_read_b128 v[172:175], v152 offset:1024
	ds_read_b128 v[176:179], v152 offset:2048
	ds_read_b128 v[180:183], v152 offset:3072
	ds_read_b128 v[184:187], v153
	ds_read_b128 v[188:191], v153 offset:1024
	ds_read_b128 v[192:195], v153 offset:2048
	ds_read_b128 v[196:199], v153 offset:3072
	ds_read_b128 v[200:203], v153 offset:4096
	ds_read_b128 v[208:211], v153 offset:5120
	ds_read_b128 v[212:215], v153 offset:6144
	ds_read_b128 v[216:219], v153 offset:7168
	s_waitcnt vmcnt(8)
	s_waitcnt lgkmcnt(0)
	s_barrier
	s_waitcnt lgkmcnt(0)
	v_mfma_f32_16x16x32_bf16 v[124:127], v[144:147], v[184:187], v[124:127]
	v_mfma_f32_16x16x32_bf16 v[120:123], v[160:163], v[184:187], v[120:123]
	v_mfma_f32_16x16x32_bf16 v[108:111], v[144:147], v[192:195], v[108:111]
	v_mfma_f32_16x16x32_bf16 v[104:107], v[160:163], v[192:195], v[104:107]
	v_mfma_f32_16x16x32_bf16 v[92:95], v[144:147], v[200:203], v[92:95]
	v_mfma_f32_16x16x32_bf16 v[88:91], v[160:163], v[200:203], v[88:91]
	v_mfma_f32_16x16x32_bf16 v[76:79], v[144:147], v[212:215], v[76:79]
	v_mfma_f32_16x16x32_bf16 v[72:75], v[160:163], v[212:215], v[72:75]
	v_mfma_f32_16x16x32_bf16 v[124:127], v[156:159], v[188:191], v[124:127]
	v_mfma_f32_16x16x32_bf16 v[120:123], v[164:167], v[188:191], v[120:123]
	v_mfma_f32_16x16x32_bf16 v[108:111], v[156:159], v[196:199], v[108:111]
	v_mfma_f32_16x16x32_bf16 v[104:107], v[164:167], v[196:199], v[104:107]
	v_mfma_f32_16x16x32_bf16 v[92:95], v[156:159], v[208:211], v[92:95]
	v_mfma_f32_16x16x32_bf16 v[88:91], v[164:167], v[208:211], v[88:91]
	v_mfma_f32_16x16x32_bf16 v[76:79], v[156:159], v[216:219], v[76:79]
	v_mfma_f32_16x16x32_bf16 v[72:75], v[164:167], v[216:219], v[72:75]
	v_mfma_f32_16x16x32_bf16 v[116:119], v[168:171], v[184:187], v[116:119]
	v_mfma_f32_16x16x32_bf16 v[112:115], v[176:179], v[184:187], v[112:115]
	v_mfma_f32_16x16x32_bf16 v[100:103], v[168:171], v[192:195], v[100:103]
	v_mfma_f32_16x16x32_bf16 v[96:99], v[176:179], v[192:195], v[96:99]
	v_mfma_f32_16x16x32_bf16 v[84:87], v[168:171], v[200:203], v[84:87]
	v_mfma_f32_16x16x32_bf16 v[80:83], v[176:179], v[200:203], v[80:83]
	v_mfma_f32_16x16x32_bf16 v[68:71], v[168:171], v[212:215], v[68:71]
	v_mfma_f32_16x16x32_bf16 v[64:67], v[176:179], v[212:215], v[64:67]
	v_mfma_f32_16x16x32_bf16 v[116:119], v[172:175], v[188:191], v[116:119]
	v_mfma_f32_16x16x32_bf16 v[112:115], v[180:183], v[188:191], v[112:115]
	v_mfma_f32_16x16x32_bf16 v[100:103], v[172:175], v[196:199], v[100:103]
	v_mfma_f32_16x16x32_bf16 v[96:99], v[180:183], v[196:199], v[96:99]
	v_mfma_f32_16x16x32_bf16 v[84:87], v[172:175], v[208:211], v[84:87]
	v_mfma_f32_16x16x32_bf16 v[80:83], v[180:183], v[208:211], v[80:83]
	v_mfma_f32_16x16x32_bf16 v[68:71], v[172:175], v[216:219], v[68:71]
	v_mfma_f32_16x16x32_bf16 v[64:67], v[180:183], v[216:219], v[64:67]
	s_barrier
	s_add_i32 s55, s47, s35
	s_mov_b32 m0, s55
	s_nop 0
	global_load_lds_dwordx4 v132, s[26:27]
	s_add_i32 m0, s55, 0x2000
	s_add_u32 s56, s26, 0x40000
	s_mov_b64 s[98:99], s[26:27]
	s_addc_u32 s57, s27, 0
	s_add_i32 s55, s48, s35
	global_load_lds_dwordx4 v128, s[26:27]
	s_mov_b32 m0, s55
	s_mov_b64 s[100:101], s[28:29]
	global_load_lds_dwordx4 v132, s[56:57]
	s_add_i32 m0, s55, 0x2000
	s_nop 0
	global_load_lds_dwordx4 v128, s[56:57]
	ds_read_b128 v[184:187], v153 offset:16384
	ds_read_b128 v[188:191], v153 offset:17408
	ds_read_b128 v[192:195], v153 offset:18432
	ds_read_b128 v[196:199], v153 offset:19456
	ds_read_b128 v[200:203], v153 offset:20480
	ds_read_b128 v[208:211], v153 offset:21504
	ds_read_b128 v[212:215], v153 offset:22528
	ds_read_b128 v[216:219], v153 offset:23552
	s_waitcnt vmcnt(6)
	s_waitcnt lgkmcnt(0)
	s_barrier
	s_waitcnt lgkmcnt(0)
	v_mfma_f32_16x16x32_bf16 v[60:63], v[144:147], v[184:187], v[60:63]
	v_mfma_f32_16x16x32_bf16 v[56:59], v[160:163], v[184:187], v[56:59]
	v_mfma_f32_16x16x32_bf16 v[44:47], v[144:147], v[192:195], v[44:47]
	v_mfma_f32_16x16x32_bf16 v[40:43], v[160:163], v[192:195], v[40:43]
	v_mfma_f32_16x16x32_bf16 v[28:31], v[144:147], v[200:203], v[28:31]
	v_mfma_f32_16x16x32_bf16 v[24:27], v[160:163], v[200:203], v[24:27]
	v_mfma_f32_16x16x32_bf16 v[12:15], v[144:147], v[212:215], v[12:15]
	v_mfma_f32_16x16x32_bf16 v[8:11], v[160:163], v[212:215], v[8:11]
	v_mfma_f32_16x16x32_bf16 v[60:63], v[156:159], v[188:191], v[60:63]
	v_mfma_f32_16x16x32_bf16 v[56:59], v[164:167], v[188:191], v[56:59]
	v_mfma_f32_16x16x32_bf16 v[44:47], v[156:159], v[196:199], v[44:47]
	v_mfma_f32_16x16x32_bf16 v[40:43], v[164:167], v[196:199], v[40:43]
	v_mfma_f32_16x16x32_bf16 v[28:31], v[156:159], v[208:211], v[28:31]
	v_mfma_f32_16x16x32_bf16 v[24:27], v[164:167], v[208:211], v[24:27]
	v_mfma_f32_16x16x32_bf16 v[12:15], v[156:159], v[216:219], v[12:15]
	v_mfma_f32_16x16x32_bf16 v[8:11], v[164:167], v[216:219], v[8:11]
	v_mfma_f32_16x16x32_bf16 v[52:55], v[168:171], v[184:187], v[52:55]
	v_mfma_f32_16x16x32_bf16 v[48:51], v[176:179], v[184:187], v[48:51]
	v_mfma_f32_16x16x32_bf16 v[36:39], v[168:171], v[192:195], v[36:39]
	v_mfma_f32_16x16x32_bf16 v[32:35], v[176:179], v[192:195], v[32:35]
	v_mfma_f32_16x16x32_bf16 v[20:23], v[168:171], v[200:203], v[20:23]
	v_mfma_f32_16x16x32_bf16 v[16:19], v[176:179], v[200:203], v[16:19]
	v_mfma_f32_16x16x32_bf16 v[4:7], v[168:171], v[212:215], v[4:7]
	v_mfma_f32_16x16x32_bf16 v[0:3], v[176:179], v[212:215], v[0:3]
	s_mov_b32 m0, s38
	s_nop 0
	global_load_lds_dwordx4 v134, s[28:29]
	s_mov_b32 m0, s39
	s_nop 0
	global_load_lds_dwordx4 v130, s[28:29]
	v_mfma_f32_16x16x32_bf16 v[52:55], v[172:175], v[188:191], v[52:55]
	v_mfma_f32_16x16x32_bf16 v[48:51], v[180:183], v[188:191], v[48:51]
	v_mfma_f32_16x16x32_bf16 v[36:39], v[172:175], v[196:199], v[36:39]
	v_mfma_f32_16x16x32_bf16 v[32:35], v[180:183], v[196:199], v[32:35]
	v_mfma_f32_16x16x32_bf16 v[20:23], v[172:175], v[208:211], v[20:23]
	v_mfma_f32_16x16x32_bf16 v[16:19], v[180:183], v[208:211], v[16:19]
	v_mfma_f32_16x16x32_bf16 v[4:7], v[172:175], v[216:219], v[4:7]
	v_mfma_f32_16x16x32_bf16 v[0:3], v[180:183], v[216:219], v[0:3]
	s_barrier
	s_add_i32 s55, 0, 0x18000
	s_add_i32 s56, 0, 0x1c000
	s_add_u32 s28, s28, 0x40000
	s_addc_u32 s29, s29, 0
	s_mov_b32 m0, s40
	s_nop 0
	global_load_lds_dwordx4 v134, s[28:29]
	s_mov_b32 m0, s41
	s_nop 0
	global_load_lds_dwordx4 v130, s[28:29]
	v_add_u32_e32 v164, s55, v149
	v_add_u32_e32 v180, s56, v149
	ds_read_b128 v[144:147], v164
	ds_read_b128 v[156:159], v164 offset:1024
	ds_read_b128 v[160:163], v164 offset:2048
	ds_read_b128 v[164:167], v164 offset:3072
	ds_read_b128 v[168:171], v180
	ds_read_b128 v[172:175], v180 offset:1024
	ds_read_b128 v[176:179], v180 offset:2048
	ds_read_b128 v[180:183], v180 offset:3072
	ds_read_b128 v[184:187], v153 offset:32768
	ds_read_b128 v[188:191], v153 offset:33792
	ds_read_b128 v[192:195], v153 offset:34816
	ds_read_b128 v[196:199], v153 offset:35840
	ds_read_b128 v[200:203], v153 offset:36864
	ds_read_b128 v[208:211], v153 offset:37888
	ds_read_b128 v[212:215], v153 offset:38912
	ds_read_b128 v[216:219], v153 offset:39936
	s_waitcnt vmcnt(8)
	s_waitcnt lgkmcnt(0)
	s_barrier
	s_waitcnt lgkmcnt(0)
	v_mfma_f32_16x16x32_bf16 v[124:127], v[144:147], v[184:187], v[124:127]
	v_mfma_f32_16x16x32_bf16 v[120:123], v[160:163], v[184:187], v[120:123]
	v_mfma_f32_16x16x32_bf16 v[108:111], v[144:147], v[192:195], v[108:111]
	v_mfma_f32_16x16x32_bf16 v[104:107], v[160:163], v[192:195], v[104:107]
	v_mfma_f32_16x16x32_bf16 v[92:95], v[144:147], v[200:203], v[92:95]
	v_mfma_f32_16x16x32_bf16 v[88:91], v[160:163], v[200:203], v[88:91]
	v_mfma_f32_16x16x32_bf16 v[76:79], v[144:147], v[212:215], v[76:79]
	v_mfma_f32_16x16x32_bf16 v[72:75], v[160:163], v[212:215], v[72:75]
	v_mfma_f32_16x16x32_bf16 v[124:127], v[156:159], v[188:191], v[124:127]
	v_mfma_f32_16x16x32_bf16 v[120:123], v[164:167], v[188:191], v[120:123]
	v_mfma_f32_16x16x32_bf16 v[108:111], v[156:159], v[196:199], v[108:111]
	v_mfma_f32_16x16x32_bf16 v[104:107], v[164:167], v[196:199], v[104:107]
	v_mfma_f32_16x16x32_bf16 v[92:95], v[156:159], v[208:211], v[92:95]
	v_mfma_f32_16x16x32_bf16 v[88:91], v[164:167], v[208:211], v[88:91]
	v_mfma_f32_16x16x32_bf16 v[76:79], v[156:159], v[216:219], v[76:79]
	v_mfma_f32_16x16x32_bf16 v[72:75], v[164:167], v[216:219], v[72:75]
	v_mfma_f32_16x16x32_bf16 v[116:119], v[168:171], v[184:187], v[116:119]
	v_mfma_f32_16x16x32_bf16 v[112:115], v[176:179], v[184:187], v[112:115]
	v_mfma_f32_16x16x32_bf16 v[100:103], v[168:171], v[192:195], v[100:103]
	v_mfma_f32_16x16x32_bf16 v[96:99], v[176:179], v[192:195], v[96:99]
	v_mfma_f32_16x16x32_bf16 v[84:87], v[168:171], v[200:203], v[84:87]
	v_mfma_f32_16x16x32_bf16 v[80:83], v[176:179], v[200:203], v[80:83]
	v_mfma_f32_16x16x32_bf16 v[68:71], v[168:171], v[212:215], v[68:71]
	v_mfma_f32_16x16x32_bf16 v[64:67], v[176:179], v[212:215], v[64:67]
	v_mfma_f32_16x16x32_bf16 v[116:119], v[172:175], v[188:191], v[116:119]
	v_mfma_f32_16x16x32_bf16 v[112:115], v[180:183], v[188:191], v[112:115]
	v_mfma_f32_16x16x32_bf16 v[100:103], v[172:175], v[196:199], v[100:103]
	v_mfma_f32_16x16x32_bf16 v[96:99], v[180:183], v[196:199], v[96:99]
	v_mfma_f32_16x16x32_bf16 v[84:87], v[172:175], v[208:211], v[84:87]
	v_mfma_f32_16x16x32_bf16 v[80:83], v[180:183], v[208:211], v[80:83]
	v_mfma_f32_16x16x32_bf16 v[68:71], v[172:175], v[216:219], v[68:71]
	v_mfma_f32_16x16x32_bf16 v[64:67], v[180:183], v[216:219], v[64:67]
	s_barrier
	s_add_i32 s28, s55, s35
	s_mov_b32 m0, s28
	s_nop 0
	global_load_lds_dwordx4 v220, s[26:27]
	s_add_i32 m0, s28, 0x2000
	s_add_u32 s26, s26, 0x40080
	s_addc_u32 s27, s27, 0
	s_add_i32 s28, s56, s35
	global_load_lds_dwordx4 v204, s[98:99]
	s_mov_b32 m0, s28
	s_nop 0
	global_load_lds_dwordx4 v132, s[26:27]
	s_add_i32 m0, s28, 0x2000
	s_nop 0
	global_load_lds_dwordx4 v128, s[26:27]
	ds_read_b128 v[184:187], v153 offset:49152
	ds_read_b128 v[188:191], v153 offset:50176
	ds_read_b128 v[192:195], v153 offset:51200
	ds_read_b128 v[196:199], v153 offset:52224
	ds_read_b128 v[200:203], v153 offset:53248
	ds_read_b128 v[208:211], v153 offset:54272
	ds_read_b128 v[212:215], v153 offset:55296
	ds_read_b128 v[216:219], v153 offset:56320
	s_waitcnt vmcnt(6)
	s_waitcnt lgkmcnt(0)
	s_barrier
	s_waitcnt lgkmcnt(0)
	v_mfma_f32_16x16x32_bf16 v[60:63], v[144:147], v[184:187], v[60:63]
	v_mfma_f32_16x16x32_bf16 v[56:59], v[160:163], v[184:187], v[56:59]
	v_mfma_f32_16x16x32_bf16 v[44:47], v[144:147], v[192:195], v[44:47]
	v_mfma_f32_16x16x32_bf16 v[40:43], v[160:163], v[192:195], v[40:43]
	v_mfma_f32_16x16x32_bf16 v[28:31], v[144:147], v[200:203], v[28:31]
	v_mfma_f32_16x16x32_bf16 v[24:27], v[160:163], v[200:203], v[24:27]
	v_mfma_f32_16x16x32_bf16 v[12:15], v[144:147], v[212:215], v[12:15]
	v_mfma_f32_16x16x32_bf16 v[8:11], v[160:163], v[212:215], v[8:11]
	v_mfma_f32_16x16x32_bf16 v[60:63], v[156:159], v[188:191], v[60:63]
	v_mfma_f32_16x16x32_bf16 v[56:59], v[164:167], v[188:191], v[56:59]
	v_mfma_f32_16x16x32_bf16 v[44:47], v[156:159], v[196:199], v[44:47]
	v_mfma_f32_16x16x32_bf16 v[40:43], v[164:167], v[196:199], v[40:43]
	v_mfma_f32_16x16x32_bf16 v[28:31], v[156:159], v[208:211], v[28:31]
	v_mfma_f32_16x16x32_bf16 v[24:27], v[164:167], v[208:211], v[24:27]
	v_mfma_f32_16x16x32_bf16 v[12:15], v[156:159], v[216:219], v[12:15]
	v_mfma_f32_16x16x32_bf16 v[8:11], v[164:167], v[216:219], v[8:11]
	v_mfma_f32_16x16x32_bf16 v[52:55], v[168:171], v[184:187], v[52:55]
	v_mfma_f32_16x16x32_bf16 v[48:51], v[176:179], v[184:187], v[48:51]
	v_mfma_f32_16x16x32_bf16 v[36:39], v[168:171], v[192:195], v[36:39]
	v_mfma_f32_16x16x32_bf16 v[32:35], v[176:179], v[192:195], v[32:35]
	v_mfma_f32_16x16x32_bf16 v[20:23], v[168:171], v[200:203], v[20:23]
	v_mfma_f32_16x16x32_bf16 v[16:19], v[176:179], v[200:203], v[16:19]
	v_mfma_f32_16x16x32_bf16 v[4:7], v[168:171], v[212:215], v[4:7]
	v_mfma_f32_16x16x32_bf16 v[0:3], v[176:179], v[212:215], v[0:3]
	s_mov_b32 m0, s45
	s_nop 0
	global_load_lds_dwordx4 v221, s[100:101]
	s_mov_b32 m0, s46
	s_nop 0
	global_load_lds_dwordx4 v205, s[100:101]
	v_mfma_f32_16x16x32_bf16 v[52:55], v[172:175], v[188:191], v[52:55]
	v_mfma_f32_16x16x32_bf16 v[48:51], v[180:183], v[188:191], v[48:51]
	v_mfma_f32_16x16x32_bf16 v[36:39], v[172:175], v[196:199], v[36:39]
	v_mfma_f32_16x16x32_bf16 v[32:35], v[180:183], v[196:199], v[32:35]
	v_mfma_f32_16x16x32_bf16 v[20:23], v[172:175], v[208:211], v[20:23]
	v_mfma_f32_16x16x32_bf16 v[16:19], v[180:183], v[208:211], v[16:19]
	v_mfma_f32_16x16x32_bf16 v[4:7], v[172:175], v[216:219], v[4:7]
	v_mfma_f32_16x16x32_bf16 v[0:3], v[180:183], v[216:219], v[0:3]
	s_barrier
	s_add_i32 s54, s54, 2
	s_add_u32 s52, s52, 0x100
	s_addc_u32 s53, s53, 0
	s_add_u32 s24, s24, 0x100
	s_addc_u32 s25, s25, 0
	s_cmp_gt_u32 s54, 13
	s_cbranch_scc0 .LBB0_1646
	s_setprio 0
	s_and_b64 vcc, exec, s[14:15]
	s_cbranch_vccz .LBB0_1649
	s_barrier
